# first grid sync replaced by the XCD-hierarchical barrier; accumulator zeroing moved into the first K-iteration load segments (overlaps LDS read latency)
# speedup vs baseline: 1.0058x; 1.0058x over previous
.LBB0_137:
	global_load_dwordx4 v[10:13], v[38:39], off offset:3072
	v_mov_b32_e32 v15, v8
	v_mov_b32_e32 v8, v7
	v_mov_b32_e32 v14, v6
	v_pk_mul_f32 v[8:9], v[44:45], v[8:9]
	v_pk_mul_f32 v[14:15], v[44:45], v[14:15]
	s_and_b64 vcc, exec, s[4:5]
	s_waitcnt vmcnt(0)
	v_mov_b32_e32 v7, v12
	v_mov_b32_e32 v12, v11
	v_mov_b32_e32 v6, v10
	v_pk_mul_f32 v[8:9], v[8:9], v[12:13]
	v_pk_mul_f32 v[10:11], v[14:15], v[6:7]
	v_and_b32_sdwa v16, v9, v54 dst_sel:DWORD dst_unused:UNUSED_PAD src0_sel:WORD_1 src1_sel:DWORD
	v_and_b32_sdwa v17, v8, v54 dst_sel:DWORD dst_unused:UNUSED_PAD src0_sel:WORD_1 src1_sel:DWORD
	v_and_b32_sdwa v14, v11, v54 dst_sel:DWORD dst_unused:UNUSED_PAD src0_sel:WORD_1 src1_sel:DWORD
	v_and_b32_sdwa v15, v10, v54 dst_sel:DWORD dst_unused:UNUSED_PAD src0_sel:WORD_1 src1_sel:DWORD
	v_add3_u32 v9, v9, v16, s3
	v_add3_u32 v8, v8, v17, s3
	v_add3_u32 v10, v10, v15, s3
	v_add3_u32 v11, v11, v14, s3
	v_and_b32_e32 v9, 0xffff0000, v9
	v_and_b32_e32 v8, 0xffff0000, v8
	v_or_b32_sdwa v9, v9, v11 dst_sel:DWORD dst_unused:UNUSED_PAD src0_sel:DWORD src1_sel:WORD_1
	v_or_b32_sdwa v8, v8, v10 dst_sel:DWORD dst_unused:UNUSED_PAD src0_sel:DWORD src1_sel:WORD_1
	global_store_dwordx2 v[42:43], v[8:9], off offset:1536
	s_cbranch_vccnz .LBB0_130
	v_mov_b32_e32 v8, v2
	v_mov_b32_e32 v9, v4
	v_pk_mul_f32 v[8:9], v[30:31], v[8:9] op_sel_hi:[0,1]
	v_mov_b32_e32 v4, v3
	v_pk_mul_f32 v[2:3], v[30:31], v[4:5] op_sel_hi:[0,1]
	v_pk_mul_f32 v[4:5], v[6:7], v[8:9]
	v_pk_mul_f32 v[2:3], v[12:13], v[2:3]
	v_and_b32_sdwa v6, v5, v54 dst_sel:DWORD dst_unused:UNUSED_PAD src0_sel:WORD_1 src1_sel:DWORD
	v_and_b32_sdwa v7, v4, v54 dst_sel:DWORD dst_unused:UNUSED_PAD src0_sel:WORD_1 src1_sel:DWORD
	v_add3_u32 v4, v4, v7, s3
	v_add3_u32 v5, v5, v6, s3
	v_and_b32_sdwa v6, v3, v54 dst_sel:DWORD dst_unused:UNUSED_PAD src0_sel:WORD_1 src1_sel:DWORD
	v_and_b32_sdwa v7, v2, v54 dst_sel:DWORD dst_unused:UNUSED_PAD src0_sel:WORD_1 src1_sel:DWORD
	v_add3_u32 v3, v3, v6, s3
	v_add3_u32 v2, v2, v7, s3
	v_and_b32_e32 v3, 0xffff0000, v3
	v_and_b32_e32 v2, 0xffff0000, v2
	v_or_b32_sdwa v3, v3, v5 dst_sel:DWORD dst_unused:UNUSED_PAD src0_sel:DWORD src1_sel:WORD_1
	v_or_b32_sdwa v2, v2, v4 dst_sel:DWORD dst_unused:UNUSED_PAD src0_sel:DWORD src1_sel:WORD_1
	global_store_dwordx2 v[40:41], v[2:3], off offset:1536
	s_branch .LBB0_130
.LBB0_139:
	s_getreg_b32 s6, hwreg(HW_REG_XCC_ID, 0, 4)
	s_waitcnt vmcnt(0)
	s_add_u32 s87, s44, 0x2e00000
	s_addc_u32 s88, s45, 0
	s_waitcnt vmcnt(0)
	s_barrier
	s_and_saveexec_b64 s[4:5], s[40:41]
	s_xor_b64 s[4:5], exec, s[4:5]
	s_cbranch_execz .Lgsync_222
	s_add_i32 s7, 0, 0x26000
	v_mov_b32_e32 v0, s7
	s_waitcnt vmcnt(0) expcnt(0) lgkmcnt(0)
	ds_read_b32 v2, v0
	s_add_i32 s7, 0, 0x26004
	v_mov_b32_e32 v0, s7
	ds_read_b32 v0, v0
	s_and_b32 s21, s6, 15
	s_waitcnt lgkmcnt(1)
	v_cmp_ne_u32_e32 vcc, 0, v2
	s_cbranch_vccnz .Lgsync_185
	s_load_dword s6, s[0:1], 0xa0
	s_mov_b32 s61, 1
	v_mov_b32_e32 v16, 0
	s_waitcnt lgkmcnt(0)
	s_mul_i32 s60, s43, s6
	s_add_u32 s6, s44, 0x2e00200
	s_addc_u32 s7, s45, 0
	s_add_u32 s8, s44, 0x2e00400
	s_addc_u32 s9, s45, 0
	s_add_u32 s10, s44, 0x2e00500
	s_addc_u32 s11, s45, 0
	s_add_u32 s12, s44, 0x2e00600
	s_addc_u32 s13, s45, 0
	s_add_u32 s14, s44, 0x2e00700
	s_addc_u32 s15, s45, 0
	s_add_u32 s16, s44, 0x2e00800
	s_addc_u32 s17, s45, 0
	s_add_u32 s18, s44, 0x2e00900
	s_addc_u32 s19, s45, 0
	s_add_u32 s24, s44, 0x2e00a00
	s_addc_u32 s25, s45, 0
	s_add_u32 s26, s44, 0x2e00b00
	s_addc_u32 s27, s45, 0
	s_add_u32 s28, s44, 0x2e00c00
	s_addc_u32 s29, s45, 0
	s_add_u32 s30, s44, 0x2e00d00
	s_addc_u32 s31, s45, 0
	s_add_u32 s34, s44, 0x2e00e00
	s_addc_u32 s35, s45, 0
	s_add_u32 s36, s44, 0x2e00f00
	s_addc_u32 s37, s45, 0
	s_add_u32 s38, s44, 0x2e01000
	s_addc_u32 s39, s45, 0
	s_add_u32 s48, s44, 0x2e01100
	s_addc_u32 s49, s45, 0
	s_add_u32 s50, s44, 0x2e01200
	s_addc_u32 s51, s45, 0
	s_add_u32 s52, s44, 0x2e01300
	s_mul_i32 s60, s60, s42
	s_addc_u32 s53, s45, 0
	s_branch .Lgsync_173

.Lgsync_221:
	s_or_b64 exec, exec, s[8:9]
.Lgsync_222:
	s_or_b64 exec, exec, s[4:5]
	s_cmpk_lt_i32 s2, 0xc00
	s_cselect_b64 s[22:23], -1, 0
	s_ashr_i32 s3, s2, 31
	s_lshr_b32 s4, s3, 29
	s_add_i32 s4, s2, s4
	s_ashr_i32 s7, s4, 3
	s_and_b32 s4, s4, -8
	s_sub_i32 s90, s2, s4
	s_cmp_lt_i32 s90, 0
	s_cselect_b64 s[4:5], -1, 0
	v_writelane_b32 v255, s4, 1
	s_movk_i32 s6, 0x181
	v_mov_b32_e32 v0, v216
	v_writelane_b32 v255, s5, 2
	s_and_b64 s[4:5], s[4:5], exec
	s_cselect_b32 s4, s6, 0x180
	s_mul_i32 s4, s4, s90
	s_add_i32 s4, s4, s7
	s_mul_hi_i32 s5, s4, 0x2aaaaaab
	s_lshr_b32 s6, s5, 31
	s_ashr_i32 s5, s5, 3
	s_add_i32 s5, s5, s6
	s_lshl_b32 s6, s5, 2
	s_mul_i32 s5, s5, 48
	s_sub_i32 s4, s4, s5
	s_bfe_i32 s5, s4, 0x80000
	s_bfe_u32 s5, s5, 0x2000d
	s_add_i32 s5, s4, s5
	v_writelane_b32 v255, s7, 3
	s_bfe_i32 s7, s5, 0x80000
	s_and_b32 s5, s5, 0xfc
	s_sub_i32 s4, s4, s5
	s_sext_i32_i8 s4, s4
	s_sext_i32_i16 s7, s7
	s_add_i32 s20, s6, s4
	s_mov_b64 s[4:5], s[0:1]
	v_mov_b32_e32 v8, v216
	s_barrier
	s_lshr_b32 s71, s7, 2
	s_ashr_i32 s70, s7, 2
	s_ashr_i32 s86, s42, 31
	s_and_b64 vcc, exec, s[22:23]
	v_readfirstlane_b32 s18, v8
	s_cbranch_vccz .LBB0_169
	v_mov_b32_e32 v0, s71
	s_load_dwordx2 s[4:5], s[4:5], 0x90
	v_readfirstlane_b32 s6, v0
	v_lshlrev_b32_e32 v0, 4, v8
	v_add_u32_e32 v1, 0x2000, v0
	v_ashrrev_i32_e32 v2, 31, v1
	v_lshrrev_b32_e32 v2, 22, v2
	v_add_u32_e32 v2, v1, v2
	v_ashrrev_i32_e32 v9, 10, v2
	v_mul_i32_i24_e32 v2, 0x400, v9
	v_sub_u32_e32 v1, v1, v2
	v_lshrrev_b32_e32 v2, 4, v1
	v_bitop3_b32 v1, v2, v1, 32 bitop3:0x6c
	v_ashrrev_i32_e32 v2, 31, v1
	v_lshrrev_b32_e32 v2, 26, v2
	s_waitcnt lgkmcnt(0)
	s_add_u32 s54, s4, 0x3000000
	v_add_u32_e32 v2, v1, v2
	v_lshlrev_b32_e32 v3, 3, v9
	s_addc_u32 s55, s5, 0
	v_ashrrev_i32_e32 v10, 6, v2
	v_and_b32_e32 v3, -16, v3
	s_add_u32 s56, s4, 0x8000000
	s_mov_b32 s7, 0
	v_add_u32_e32 v3, v10, v3
	s_addc_u32 s57, s5, 0
	s_bfe_i64 s[8:9], s[6:7], 0x80000
	v_and_b32_e32 v4, 3, v10
	s_mov_b32 s6, 0x1fffe0
	v_lshrrev_b32_e32 v5, 2, v3
	v_lshlrev_b32_e32 v6, 1, v3
	v_and_b32_e32 v2, 0xc0, v2
	v_and_or_b32 v4, v3, s6, v4
	v_and_b32_e32 v5, 4, v5
	v_and_b32_e32 v6, 24, v6
	v_sub_u32_e32 v1, v1, v2
	v_mov_b32_e32 v2, 1
	v_or3_b32 v4, v4, v5, v6
	v_lshlrev_b32_e32 v5, 5, v9
	v_ashrrev_i16_sdwa v1, v2, sext(v1) dst_sel:DWORD dst_unused:UNUSED_PAD src0_sel:DWORD src1_sel:BYTE_0
	v_and_b32_e32 v5, 32, v5
	v_bfe_i32 v11, v1, 0, 16
	v_add_lshl_u32 v1, v5, v11, 1
	v_lshl_add_u32 v128, v4, 11, v1
	v_lshl_add_u32 v130, v3, 11, v1
	v_bfe_i32 v1, v8, 27, 1
	v_lshrrev_b32_e32 v1, 22, v1
	v_add_u32_e32 v1, v0, v1
	v_and_b32_e32 v1, 0xfffffc00, v1
	v_sub_u32_e32 v0, v0, v1
	v_lshrrev_b32_e32 v1, 4, v0
	v_ashrrev_i32_e32 v3, 31, v8
	v_bitop3_b32 v0, v1, v0, 32 bitop3:0x6c
	v_lshrrev_b32_e32 v3, 26, v3
	v_ashrrev_i32_e32 v1, 31, v0
	v_add_u32_e32 v3, v8, v3
	v_lshrrev_b32_e32 v1, 26, v1
	v_ashrrev_i32_e32 v13, 6, v3
	v_add_u32_e32 v1, v0, v1
	v_lshlrev_b32_e32 v3, 3, v13
	v_ashrrev_i32_e32 v12, 6, v1
	v_and_b32_e32 v3, -16, v3
	v_add_u32_e32 v3, v12, v3
	v_and_b32_e32 v4, 3, v12
	v_lshrrev_b32_e32 v5, 2, v3
	v_lshlrev_b32_e32 v6, 1, v3
	v_and_b32_e32 v1, 0xc0, v1
	s_ashr_i32 s16, s18, 6
	s_ashr_i32 s21, s20, 31
	v_and_or_b32 v4, v3, s6, v4
	v_and_b32_e32 v5, 4, v5
	v_and_b32_e32 v6, 24, v6
	v_sub_u32_e32 v0, v0, v1
	s_ashr_i32 s19, s18, 8
	s_lshl_b32 s58, s16, 10
	s_lshl_b64 s[10:11], s[8:9], 19
	s_lshl_b64 s[8:9], s[20:21], 19
	v_or3_b32 v4, v4, v5, v6
	v_lshlrev_b32_e32 v5, 5, v13
	v_ashrrev_i16_sdwa v0, v2, sext(v0) dst_sel:DWORD dst_unused:UNUSED_PAD src0_sel:DWORD src1_sel:BYTE_0
	v_and_b32_e32 v5, 32, v5
	v_bfe_i32 v14, v0, 0, 16
	s_add_u32 s50, s54, s10
	v_add_lshl_u32 v0, v5, v14, 1
	s_addc_u32 s51, s55, s11
	s_add_i32 s6, s58, 0
	v_lshl_add_u32 v132, v4, 11, v0
	s_add_i32 m0, s6, 0x10000
	v_lshl_add_u32 v134, v3, 11, v0
	global_load_lds_dwordx4 v132, s[50:51]
	s_add_i32 m0, s6, 0x12000
	s_add_u32 s10, s50, 0x40000
	global_load_lds_dwordx4 v128, s[50:51]
	s_addc_u32 s11, s51, 0
	s_add_i32 m0, s6, 0x14000
	v_mov_b32_e32 v137, 0
	global_load_lds_dwordx4 v132, s[10:11]
	s_add_i32 m0, s6, 0x16000
	s_add_u32 s48, s56, s8
	s_addc_u32 s49, s57, s9
	s_add_i32 s21, s6, 0x2000
	global_load_lds_dwordx4 v128, s[10:11]
	s_mov_b32 m0, s6
	s_add_u32 s8, s48, 0x40000
	global_load_lds_dwordx4 v134, s[48:49]
	s_mov_b32 m0, s21
	s_addc_u32 s9, s49, 0
	s_add_i32 s59, s6, 0x4000
	global_load_lds_dwordx4 v130, s[48:49]
	s_mov_b32 m0, s59
	s_add_i32 s60, s6, 0x6000
	global_load_lds_dwordx4 v134, s[8:9]
	s_mov_b32 m0, s60
	v_mov_b32_e32 v133, v137
	global_load_lds_dwordx4 v130, s[8:9]
	v_mov_b32_e32 v129, v137
	v_mov_b32_e32 v135, v137
	v_mov_b32_e32 v131, v137
	s_cmp_eq_u32 s19, 1
	v_lshl_add_u64 v[6:7], s[50:51], 0, v[132:133]
	v_lshl_add_u64 v[2:3], s[50:51], 0, v[128:129]
	s_mov_b64 s[8:9], 0x40000
	v_lshl_add_u64 v[0:1], s[48:49], 0, v[134:135]
	s_cselect_b64 s[10:11], -1, 0
	s_cmp_lg_u32 s19, 1
	v_lshl_add_u64 v[4:5], s[48:49], 0, v[130:131]
	s_cbranch_scc1 .LBB0_152
	s_barrier

.LBB0_157:
	s_ashr_i32 s35, s34, 31
	s_lshl_b64 s[36:37], s[34:35], 19
	s_add_u32 s36, s56, s36
	s_addc_u32 s37, s57, s37
	s_and_b64 s[38:39], s[4:5], exec
	s_cselect_b32 s35, s37, s49
	s_cselect_b32 s74, s36, s48
	s_ashr_i32 s31, s30, 31
	s_lshl_b64 s[38:39], s[30:31], 19
	s_add_u32 s38, s54, s38
	s_addc_u32 s39, s55, s39
	s_and_b64 s[52:53], s[4:5], exec
	s_cselect_b32 s31, s39, s51
	s_cselect_b32 s75, s38, s50
	s_add_u32 s48, s48, 0x40080
	s_addc_u32 s49, s49, 0
	s_add_u32 s76, s50, 0x100
	s_addc_u32 s77, s51, 0
	s_mov_b32 s78, -2
.LBB0_158:
	ds_read_b128 v[146:149], v160
	ds_read_b128 v[150:153], v160 offset:1024
	ds_read_b128 v[164:167], v160 offset:2048
	ds_read_b128 v[168:171], v160 offset:3072
	ds_read_b128 v[172:175], v161
	ds_read_b128 v[176:179], v161 offset:1024
	ds_read_b128 v[180:183], v161 offset:2048
	ds_read_b128 v[184:187], v161 offset:3072
	s_add_u32 s50, s48, 0xfffc0080
	s_addc_u32 s51, s49, -1
	s_cmp_eq_u32 s78, 12
	s_cselect_b32 s53, s35, s51
	s_cselect_b32 s52, s74, s50
	s_cselect_b32 s51, s31, s77
	s_cselect_b32 s50, s75, s76
	v_lshl_add_u64 v[154:155], s[48:49], 0, v[138:139]
	s_add_i32 m0, s6, 0xc000
	ds_read_b128 v[188:191], v162
	ds_read_b128 v[192:195], v162 offset:1024
	ds_read_b128 v[196:199], v162 offset:2048
	ds_read_b128 v[200:203], v162 offset:3072
	ds_read_b128 v[204:207], v162 offset:4096
	ds_read_b128 v[208:211], v162 offset:5120
	ds_read_b128 v[212:215], v162 offset:6144
	ds_read_b128 v[218:221], v162 offset:7168
	global_load_lds_dwordx4 v[154:155], off
	v_lshl_add_u64 v[154:155], s[48:49], 0, v[140:141]
	s_add_i32 m0, s6, 0xe000
	s_nop 0
	global_load_lds_dwordx4 v[154:155], off
	s_cmp_lg_u32 s78, -2
	s_cbranch_scc1 .Lzacc0a
	v_mov_b32_e32 v64, 0
	v_mov_b32_e32 v65, 0
	v_mov_b32_e32 v66, 0
	v_mov_b32_e32 v67, 0
	v_mov_b32_e32 v68, 0
	v_mov_b32_e32 v69, 0
	v_mov_b32_e32 v70, 0
	v_mov_b32_e32 v71, 0
	v_mov_b32_e32 v72, 0
	v_mov_b32_e32 v73, 0
	v_mov_b32_e32 v74, 0
	v_mov_b32_e32 v75, 0
	v_mov_b32_e32 v76, 0
	v_mov_b32_e32 v77, 0
	v_mov_b32_e32 v78, 0
	v_mov_b32_e32 v79, 0
	v_mov_b32_e32 v80, 0
	v_mov_b32_e32 v81, 0
	v_mov_b32_e32 v82, 0
	v_mov_b32_e32 v83, 0
	v_mov_b32_e32 v84, 0
	v_mov_b32_e32 v85, 0
	v_mov_b32_e32 v86, 0
	v_mov_b32_e32 v87, 0
	v_mov_b32_e32 v88, 0
	v_mov_b32_e32 v89, 0
	v_mov_b32_e32 v90, 0
	v_mov_b32_e32 v91, 0
	v_mov_b32_e32 v92, 0
	v_mov_b32_e32 v93, 0
	v_mov_b32_e32 v94, 0
	v_mov_b32_e32 v95, 0
	v_mov_b32_e32 v96, 0
	v_mov_b32_e32 v97, 0
	v_mov_b32_e32 v98, 0
	v_mov_b32_e32 v99, 0
	v_mov_b32_e32 v100, 0
	v_mov_b32_e32 v101, 0
	v_mov_b32_e32 v102, 0
	v_mov_b32_e32 v103, 0
	v_mov_b32_e32 v104, 0
	v_mov_b32_e32 v105, 0
	v_mov_b32_e32 v106, 0
	v_mov_b32_e32 v107, 0
	v_mov_b32_e32 v108, 0
	v_mov_b32_e32 v109, 0
	v_mov_b32_e32 v110, 0
	v_mov_b32_e32 v111, 0
	v_mov_b32_e32 v112, 0
	v_mov_b32_e32 v113, 0
	v_mov_b32_e32 v114, 0
	v_mov_b32_e32 v115, 0
	v_mov_b32_e32 v116, 0
	v_mov_b32_e32 v117, 0
	v_mov_b32_e32 v118, 0
	v_mov_b32_e32 v119, 0
	v_mov_b32_e32 v120, 0
	v_mov_b32_e32 v121, 0
	v_mov_b32_e32 v122, 0
	v_mov_b32_e32 v123, 0
	v_mov_b32_e32 v124, 0
	v_mov_b32_e32 v125, 0
	v_mov_b32_e32 v126, 0
	v_mov_b32_e32 v127, 0
.Lzacc0a:
	s_waitcnt vmcnt(8)
	s_waitcnt lgkmcnt(0)
	s_barrier
	s_setprio 1
	s_waitcnt lgkmcnt(0)
	v_mfma_f32_16x16x32_bf16 v[124:127], v[146:149], v[188:191], v[124:127]
	v_mfma_f32_16x16x32_bf16 v[120:123], v[164:167], v[188:191], v[120:123]
	v_mfma_f32_16x16x32_bf16 v[116:119], v[146:149], v[196:199], v[116:119]
	v_mfma_f32_16x16x32_bf16 v[112:115], v[164:167], v[196:199], v[112:115]
	v_mfma_f32_16x16x32_bf16 v[100:103], v[146:149], v[204:207], v[100:103]
	v_mfma_f32_16x16x32_bf16 v[96:99], v[164:167], v[204:207], v[96:99]
	v_mfma_f32_16x16x32_bf16 v[84:87], v[146:149], v[212:215], v[84:87]
	v_mfma_f32_16x16x32_bf16 v[80:83], v[164:167], v[212:215], v[80:83]
	v_mfma_f32_16x16x32_bf16 v[124:127], v[150:153], v[192:195], v[124:127]
	v_mfma_f32_16x16x32_bf16 v[120:123], v[168:171], v[192:195], v[120:123]
	v_mfma_f32_16x16x32_bf16 v[116:119], v[150:153], v[200:203], v[116:119]
	v_mfma_f32_16x16x32_bf16 v[112:115], v[168:171], v[200:203], v[112:115]
	v_mfma_f32_16x16x32_bf16 v[100:103], v[150:153], v[208:211], v[100:103]
	v_mfma_f32_16x16x32_bf16 v[96:99], v[168:171], v[208:211], v[96:99]
	v_mfma_f32_16x16x32_bf16 v[84:87], v[150:153], v[218:221], v[84:87]
	v_mfma_f32_16x16x32_bf16 v[80:83], v[168:171], v[218:221], v[80:83]
	s_setprio 0
	s_setprio 1
	v_mfma_f32_16x16x32_bf16 v[108:111], v[172:175], v[188:191], v[108:111]
	v_mfma_f32_16x16x32_bf16 v[104:107], v[180:183], v[188:191], v[104:107]
	v_mfma_f32_16x16x32_bf16 v[92:95], v[172:175], v[196:199], v[92:95]
	v_mfma_f32_16x16x32_bf16 v[88:91], v[180:183], v[196:199], v[88:91]
	v_mfma_f32_16x16x32_bf16 v[76:79], v[172:175], v[204:207], v[76:79]
	v_mfma_f32_16x16x32_bf16 v[72:75], v[180:183], v[204:207], v[72:75]
	v_mfma_f32_16x16x32_bf16 v[68:71], v[172:175], v[212:215], v[68:71]
	v_mfma_f32_16x16x32_bf16 v[64:67], v[180:183], v[212:215], v[64:67]
	v_mfma_f32_16x16x32_bf16 v[108:111], v[176:179], v[192:195], v[108:111]
	v_mfma_f32_16x16x32_bf16 v[104:107], v[184:187], v[192:195], v[104:107]
	v_mfma_f32_16x16x32_bf16 v[92:95], v[176:179], v[200:203], v[92:95]
	v_mfma_f32_16x16x32_bf16 v[88:91], v[184:187], v[200:203], v[88:91]
	v_mfma_f32_16x16x32_bf16 v[76:79], v[176:179], v[208:211], v[76:79]
	v_mfma_f32_16x16x32_bf16 v[72:75], v[184:187], v[208:211], v[72:75]
	v_mfma_f32_16x16x32_bf16 v[68:71], v[176:179], v[218:221], v[68:71]
	v_mfma_f32_16x16x32_bf16 v[64:67], v[184:187], v[218:221], v[64:67]
	s_setprio 0
	s_barrier
	s_add_i32 s79, s64, s58
	v_lshl_add_u64 v[154:155], s[50:51], 0, v[132:133]
	s_mov_b32 m0, s79
	ds_read_b128 v[188:191], v162 offset:16384
	ds_read_b128 v[192:195], v162 offset:17408
	ds_read_b128 v[196:199], v162 offset:18432
	ds_read_b128 v[200:203], v162 offset:19456
	ds_read_b128 v[204:207], v162 offset:20480
	ds_read_b128 v[208:211], v162 offset:21504
	ds_read_b128 v[212:215], v162 offset:22528
	ds_read_b128 v[218:221], v162 offset:23552
	global_load_lds_dwordx4 v[154:155], off
	s_add_i32 m0, s79, 0x2000
	s_add_u32 s80, s50, 0x40000
	v_lshl_add_u64 v[222:223], s[50:51], 0, v[128:129]
	s_addc_u32 s81, s51, 0
	s_add_i32 s79, s65, s58
	global_load_lds_dwordx4 v[222:223], off
	v_lshl_add_u64 v[224:225], s[80:81], 0, v[132:133]
	s_mov_b32 m0, s79
	v_lshl_add_u64 v[226:227], s[52:53], 0, v[130:131]
	global_load_lds_dwordx4 v[224:225], off
	v_lshl_add_u64 v[224:225], s[80:81], 0, v[128:129]
	s_add_i32 m0, s79, 0x2000
	s_nop 0
	global_load_lds_dwordx4 v[224:225], off
	v_lshl_add_u64 v[224:225], s[52:53], 0, v[134:135]
	s_mov_b32 m0, s6
	s_nop 0
	global_load_lds_dwordx4 v[224:225], off
	s_mov_b32 m0, s21
	s_nop 0
	global_load_lds_dwordx4 v[226:227], off
	s_cmp_lg_u32 s78, -2
	s_cbranch_scc1 .Lzacc0b
	v_mov_b32_e32 v0, 0
	v_mov_b32_e32 v1, 0
	v_mov_b32_e32 v2, 0
	v_mov_b32_e32 v3, 0
	v_mov_b32_e32 v4, 0
	v_mov_b32_e32 v5, 0
	v_mov_b32_e32 v6, 0
	v_mov_b32_e32 v7, 0
	v_mov_b32_e32 v8, 0
	v_mov_b32_e32 v9, 0
	v_mov_b32_e32 v10, 0
	v_mov_b32_e32 v11, 0
	v_mov_b32_e32 v12, 0
	v_mov_b32_e32 v13, 0
	v_mov_b32_e32 v14, 0
	v_mov_b32_e32 v15, 0
	v_mov_b32_e32 v16, 0
	v_mov_b32_e32 v17, 0
	v_mov_b32_e32 v18, 0
	v_mov_b32_e32 v19, 0
	v_mov_b32_e32 v20, 0
	v_mov_b32_e32 v21, 0
	v_mov_b32_e32 v22, 0
	v_mov_b32_e32 v23, 0
	v_mov_b32_e32 v24, 0
	v_mov_b32_e32 v25, 0
	v_mov_b32_e32 v26, 0
	v_mov_b32_e32 v27, 0
	v_mov_b32_e32 v28, 0
	v_mov_b32_e32 v29, 0
	v_mov_b32_e32 v30, 0
	v_mov_b32_e32 v31, 0
	v_mov_b32_e32 v32, 0
	v_mov_b32_e32 v33, 0
	v_mov_b32_e32 v34, 0
	v_mov_b32_e32 v35, 0
	v_mov_b32_e32 v36, 0
	v_mov_b32_e32 v37, 0
	v_mov_b32_e32 v38, 0
	v_mov_b32_e32 v39, 0
	v_mov_b32_e32 v40, 0
	v_mov_b32_e32 v41, 0
	v_mov_b32_e32 v42, 0
	v_mov_b32_e32 v43, 0
	v_mov_b32_e32 v44, 0
	v_mov_b32_e32 v45, 0
	v_mov_b32_e32 v46, 0
	v_mov_b32_e32 v47, 0
	v_mov_b32_e32 v48, 0
	v_mov_b32_e32 v49, 0
	v_mov_b32_e32 v50, 0
	v_mov_b32_e32 v51, 0
	v_mov_b32_e32 v52, 0
	v_mov_b32_e32 v53, 0
	v_mov_b32_e32 v54, 0
	v_mov_b32_e32 v55, 0
	v_mov_b32_e32 v56, 0
	v_mov_b32_e32 v57, 0
	v_mov_b32_e32 v58, 0
	v_mov_b32_e32 v59, 0
	v_mov_b32_e32 v60, 0
	v_mov_b32_e32 v61, 0
	v_mov_b32_e32 v62, 0
	v_mov_b32_e32 v63, 0
.Lzacc0b:
	s_waitcnt vmcnt(8)
	s_waitcnt lgkmcnt(0)
	s_barrier
	s_setprio 1
	s_waitcnt lgkmcnt(0)
	v_mfma_f32_16x16x32_bf16 v[60:63], v[146:149], v[188:191], v[60:63]
	v_mfma_f32_16x16x32_bf16 v[56:59], v[164:167], v[188:191], v[56:59]
	v_mfma_f32_16x16x32_bf16 v[52:55], v[146:149], v[196:199], v[52:55]
	v_mfma_f32_16x16x32_bf16 v[48:51], v[164:167], v[196:199], v[48:51]
	v_mfma_f32_16x16x32_bf16 v[36:39], v[146:149], v[204:207], v[36:39]
	v_mfma_f32_16x16x32_bf16 v[32:35], v[164:167], v[204:207], v[32:35]
	v_mfma_f32_16x16x32_bf16 v[20:23], v[146:149], v[212:215], v[20:23]
	v_mfma_f32_16x16x32_bf16 v[16:19], v[164:167], v[212:215], v[16:19]
	v_mfma_f32_16x16x32_bf16 v[60:63], v[150:153], v[192:195], v[60:63]
	v_mfma_f32_16x16x32_bf16 v[56:59], v[168:171], v[192:195], v[56:59]
	v_mfma_f32_16x16x32_bf16 v[52:55], v[150:153], v[200:203], v[52:55]
	v_mfma_f32_16x16x32_bf16 v[48:51], v[168:171], v[200:203], v[48:51]
	v_mfma_f32_16x16x32_bf16 v[36:39], v[150:153], v[208:211], v[36:39]
	v_mfma_f32_16x16x32_bf16 v[32:35], v[168:171], v[208:211], v[32:35]
	v_mfma_f32_16x16x32_bf16 v[20:23], v[150:153], v[218:221], v[20:23]
	v_mfma_f32_16x16x32_bf16 v[16:19], v[168:171], v[218:221], v[16:19]
	s_setprio 0
	s_setprio 1
	v_mfma_f32_16x16x32_bf16 v[44:47], v[172:175], v[188:191], v[44:47]
	v_mfma_f32_16x16x32_bf16 v[40:43], v[180:183], v[188:191], v[40:43]
	v_mfma_f32_16x16x32_bf16 v[28:31], v[172:175], v[196:199], v[28:31]
	v_mfma_f32_16x16x32_bf16 v[24:27], v[180:183], v[196:199], v[24:27]
	v_mfma_f32_16x16x32_bf16 v[12:15], v[172:175], v[204:207], v[12:15]
	v_mfma_f32_16x16x32_bf16 v[8:11], v[180:183], v[204:207], v[8:11]
	v_mfma_f32_16x16x32_bf16 v[4:7], v[172:175], v[212:215], v[4:7]
	v_mfma_f32_16x16x32_bf16 v[0:3], v[180:183], v[212:215], v[0:3]
	v_mfma_f32_16x16x32_bf16 v[44:47], v[176:179], v[192:195], v[44:47]
	v_mfma_f32_16x16x32_bf16 v[40:43], v[184:187], v[192:195], v[40:43]
	v_mfma_f32_16x16x32_bf16 v[28:31], v[176:179], v[200:203], v[28:31]
	v_mfma_f32_16x16x32_bf16 v[24:27], v[184:187], v[200:203], v[24:27]
	v_mfma_f32_16x16x32_bf16 v[12:15], v[176:179], v[208:211], v[12:15]
	v_mfma_f32_16x16x32_bf16 v[8:11], v[184:187], v[208:211], v[8:11]
	v_mfma_f32_16x16x32_bf16 v[4:7], v[176:179], v[218:221], v[4:7]
	v_mfma_f32_16x16x32_bf16 v[0:3], v[184:187], v[218:221], v[0:3]
	s_setprio 0
	s_barrier
	s_add_i32 s79, 0, 0x18000
	v_add_u32_e32 v136, s79, v157
	s_add_i32 s80, 0, 0x1c000
	ds_read_b128 v[146:149], v136
	ds_read_b128 v[150:153], v136 offset:1024
	ds_read_b128 v[164:167], v136 offset:2048
	ds_read_b128 v[168:171], v136 offset:3072
	v_add_u32_e32 v136, s80, v157
	ds_read_b128 v[172:175], v136
	ds_read_b128 v[176:179], v136 offset:1024
	ds_read_b128 v[180:183], v136 offset:2048
	ds_read_b128 v[184:187], v136 offset:3072
	s_add_u32 s52, s52, 0x40000
	s_addc_u32 s53, s53, 0
	s_mov_b32 m0, s59
	v_lshl_add_u64 v[228:229], s[52:53], 0, v[134:135]
	ds_read_b128 v[188:191], v162 offset:32768
	ds_read_b128 v[192:195], v162 offset:33792
	ds_read_b128 v[196:199], v162 offset:34816
	ds_read_b128 v[200:203], v162 offset:35840
	ds_read_b128 v[204:207], v162 offset:36864
	ds_read_b128 v[208:211], v162 offset:37888
	ds_read_b128 v[212:215], v162 offset:38912
	ds_read_b128 v[218:221], v162 offset:39936
	global_load_lds_dwordx4 v[228:229], off
	v_lshl_add_u64 v[228:229], s[52:53], 0, v[130:131]
	s_mov_b32 m0, s60
	s_nop 0
	global_load_lds_dwordx4 v[228:229], off
	s_waitcnt vmcnt(8)
	s_waitcnt lgkmcnt(0)
	s_barrier
	s_setprio 1
	s_waitcnt lgkmcnt(0)
	v_mfma_f32_16x16x32_bf16 v[124:127], v[146:149], v[188:191], v[124:127]
	v_mfma_f32_16x16x32_bf16 v[120:123], v[164:167], v[188:191], v[120:123]
	v_mfma_f32_16x16x32_bf16 v[116:119], v[146:149], v[196:199], v[116:119]
	v_mfma_f32_16x16x32_bf16 v[112:115], v[164:167], v[196:199], v[112:115]
	v_mfma_f32_16x16x32_bf16 v[100:103], v[146:149], v[204:207], v[100:103]
	v_mfma_f32_16x16x32_bf16 v[96:99], v[164:167], v[204:207], v[96:99]
	v_mfma_f32_16x16x32_bf16 v[84:87], v[146:149], v[212:215], v[84:87]
	v_mfma_f32_16x16x32_bf16 v[80:83], v[164:167], v[212:215], v[80:83]
	v_mfma_f32_16x16x32_bf16 v[124:127], v[150:153], v[192:195], v[124:127]
	v_mfma_f32_16x16x32_bf16 v[120:123], v[168:171], v[192:195], v[120:123]
	v_mfma_f32_16x16x32_bf16 v[116:119], v[150:153], v[200:203], v[116:119]
	v_mfma_f32_16x16x32_bf16 v[112:115], v[168:171], v[200:203], v[112:115]
	v_mfma_f32_16x16x32_bf16 v[100:103], v[150:153], v[208:211], v[100:103]
	v_mfma_f32_16x16x32_bf16 v[96:99], v[168:171], v[208:211], v[96:99]
	v_mfma_f32_16x16x32_bf16 v[84:87], v[150:153], v[218:221], v[84:87]
	v_mfma_f32_16x16x32_bf16 v[80:83], v[168:171], v[218:221], v[80:83]
	s_setprio 0
	s_setprio 1
	v_mfma_f32_16x16x32_bf16 v[108:111], v[172:175], v[188:191], v[108:111]
	v_mfma_f32_16x16x32_bf16 v[104:107], v[180:183], v[188:191], v[104:107]
	v_mfma_f32_16x16x32_bf16 v[92:95], v[172:175], v[196:199], v[92:95]
	v_mfma_f32_16x16x32_bf16 v[88:91], v[180:183], v[196:199], v[88:91]
	v_mfma_f32_16x16x32_bf16 v[76:79], v[172:175], v[204:207], v[76:79]
	v_mfma_f32_16x16x32_bf16 v[72:75], v[180:183], v[204:207], v[72:75]
	v_mfma_f32_16x16x32_bf16 v[68:71], v[172:175], v[212:215], v[68:71]
	v_mfma_f32_16x16x32_bf16 v[64:67], v[180:183], v[212:215], v[64:67]
	v_mfma_f32_16x16x32_bf16 v[108:111], v[176:179], v[192:195], v[108:111]
	v_mfma_f32_16x16x32_bf16 v[104:107], v[184:187], v[192:195], v[104:107]
	v_mfma_f32_16x16x32_bf16 v[92:95], v[176:179], v[200:203], v[92:95]
	v_mfma_f32_16x16x32_bf16 v[88:91], v[184:187], v[200:203], v[88:91]
	v_mfma_f32_16x16x32_bf16 v[76:79], v[176:179], v[208:211], v[76:79]
	v_mfma_f32_16x16x32_bf16 v[72:75], v[184:187], v[208:211], v[72:75]
	v_mfma_f32_16x16x32_bf16 v[68:71], v[176:179], v[218:221], v[68:71]
	v_mfma_f32_16x16x32_bf16 v[64:67], v[184:187], v[218:221], v[64:67]
	s_setprio 0
	s_barrier
	s_add_i32 s52, s79, s58
	v_lshl_add_u64 v[154:155], v[154:155], 0, s[16:17]
	s_mov_b32 m0, s52
	ds_read_b128 v[188:191], v162 offset:49152
	ds_read_b128 v[192:195], v162 offset:50176
	ds_read_b128 v[196:199], v162 offset:51200
	ds_read_b128 v[200:203], v162 offset:52224
	ds_read_b128 v[204:207], v162 offset:53248
	ds_read_b128 v[208:211], v162 offset:54272
	ds_read_b128 v[212:215], v162 offset:55296
	ds_read_b128 v[218:221], v162 offset:56320
	global_load_lds_dwordx4 v[154:155], off
	s_add_i32 m0, s52, 0x2000
	s_add_u32 s50, s50, 0x40080
	v_lshl_add_u64 v[154:155], v[222:223], 0, s[16:17]
	s_addc_u32 s51, s51, 0
	s_add_i32 s52, s80, s58
	global_load_lds_dwordx4 v[154:155], off
	v_lshl_add_u64 v[154:155], s[50:51], 0, v[132:133]
	s_mov_b32 m0, s52
	s_nop 0
	global_load_lds_dwordx4 v[154:155], off
	v_lshl_add_u64 v[154:155], s[50:51], 0, v[128:129]
	s_add_i32 m0, s52, 0x2000
	s_nop 0
	global_load_lds_dwordx4 v[154:155], off
	v_lshl_add_u64 v[154:155], v[224:225], 0, s[16:17]
	s_mov_b32 m0, s61
	s_nop 0
	global_load_lds_dwordx4 v[154:155], off
	v_lshl_add_u64 v[154:155], v[226:227], 0, s[16:17]
	s_mov_b32 m0, s62
	s_nop 0
	global_load_lds_dwordx4 v[154:155], off
	s_waitcnt vmcnt(8)
	s_waitcnt lgkmcnt(0)
	s_barrier
	s_setprio 1
	s_waitcnt lgkmcnt(0)
	v_mfma_f32_16x16x32_bf16 v[60:63], v[146:149], v[188:191], v[60:63]
	v_mfma_f32_16x16x32_bf16 v[56:59], v[164:167], v[188:191], v[56:59]
	v_mfma_f32_16x16x32_bf16 v[52:55], v[146:149], v[196:199], v[52:55]
	v_mfma_f32_16x16x32_bf16 v[48:51], v[164:167], v[196:199], v[48:51]
	v_mfma_f32_16x16x32_bf16 v[36:39], v[146:149], v[204:207], v[36:39]
	v_mfma_f32_16x16x32_bf16 v[32:35], v[164:167], v[204:207], v[32:35]
	v_mfma_f32_16x16x32_bf16 v[20:23], v[146:149], v[212:215], v[20:23]
	v_mfma_f32_16x16x32_bf16 v[16:19], v[164:167], v[212:215], v[16:19]
	v_mfma_f32_16x16x32_bf16 v[60:63], v[150:153], v[192:195], v[60:63]
	v_mfma_f32_16x16x32_bf16 v[56:59], v[168:171], v[192:195], v[56:59]
	v_mfma_f32_16x16x32_bf16 v[52:55], v[150:153], v[200:203], v[52:55]
	v_mfma_f32_16x16x32_bf16 v[48:51], v[168:171], v[200:203], v[48:51]
	v_mfma_f32_16x16x32_bf16 v[36:39], v[150:153], v[208:211], v[36:39]
	v_mfma_f32_16x16x32_bf16 v[32:35], v[168:171], v[208:211], v[32:35]
	v_mfma_f32_16x16x32_bf16 v[20:23], v[150:153], v[218:221], v[20:23]
	v_mfma_f32_16x16x32_bf16 v[16:19], v[168:171], v[218:221], v[16:19]
	s_setprio 0
	s_setprio 1
	v_mfma_f32_16x16x32_bf16 v[44:47], v[172:175], v[188:191], v[44:47]
	v_mfma_f32_16x16x32_bf16 v[40:43], v[180:183], v[188:191], v[40:43]
	v_mfma_f32_16x16x32_bf16 v[28:31], v[172:175], v[196:199], v[28:31]
	v_mfma_f32_16x16x32_bf16 v[24:27], v[180:183], v[196:199], v[24:27]
	v_mfma_f32_16x16x32_bf16 v[12:15], v[172:175], v[204:207], v[12:15]
	v_mfma_f32_16x16x32_bf16 v[8:11], v[180:183], v[204:207], v[8:11]
	v_mfma_f32_16x16x32_bf16 v[4:7], v[172:175], v[212:215], v[4:7]
	v_mfma_f32_16x16x32_bf16 v[0:3], v[180:183], v[212:215], v[0:3]
	v_mfma_f32_16x16x32_bf16 v[44:47], v[176:179], v[192:195], v[44:47]
	v_mfma_f32_16x16x32_bf16 v[40:43], v[184:187], v[192:195], v[40:43]
	v_mfma_f32_16x16x32_bf16 v[28:31], v[176:179], v[200:203], v[28:31]
	v_mfma_f32_16x16x32_bf16 v[24:27], v[184:187], v[200:203], v[24:27]
	v_mfma_f32_16x16x32_bf16 v[12:15], v[176:179], v[208:211], v[12:15]
	v_mfma_f32_16x16x32_bf16 v[8:11], v[184:187], v[208:211], v[8:11]
	v_mfma_f32_16x16x32_bf16 v[4:7], v[176:179], v[218:221], v[4:7]
	v_mfma_f32_16x16x32_bf16 v[0:3], v[184:187], v[218:221], v[0:3]
	s_setprio 0
	s_barrier
	s_add_i32 s78, s78, 2
	s_add_u32 s48, s48, 0x100
	s_addc_u32 s49, s49, 0
	s_add_u32 s76, s76, 0x100
	s_addc_u32 s77, s77, 0
	s_cmp_gt_u32 s78, 13
	s_cbranch_scc0 .LBB0_158
	s_and_b64 vcc, exec, s[18:19]
	s_cbranch_vccz .LBB0_161
	s_barrier

.LBB0_293:
	s_ashr_i32 s35, s34, 31
	s_lshl_b64 s[36:37], s[34:35], 19
	s_add_u32 s36, s59, s36
	s_addc_u32 s37, s60, s37
	s_and_b64 s[38:39], s[10:11], exec
	s_cselect_b32 s5, s37, s53
	s_cselect_b32 s17, s36, s52
	s_ashr_i32 s31, s30, 31
	s_lshl_b64 s[38:39], s[30:31], 19
	s_add_u32 s38, s21, s38
	s_addc_u32 s39, s58, s39
	s_and_b64 s[56:57], s[10:11], exec
	s_cselect_b32 s31, s39, s55
	s_cselect_b32 s35, s38, s54
	s_add_u32 s52, s52, 0x40080
	s_addc_u32 s53, s53, 0
	s_add_u32 s51, s54, 0x100
	s_addc_u32 s75, s55, 0
	s_mov_b32 s76, -2
	s_waitcnt lgkmcnt(0)
.LBB0_294:
	ds_read_b128 v[128:131], v209
	ds_read_b128 v[132:135], v209 offset:1024
	ds_read_b128 v[136:139], v209 offset:2048
	ds_read_b128 v[140:143], v209 offset:3072
	ds_read_b128 v[144:147], v210
	ds_read_b128 v[148:151], v210 offset:1024
	ds_read_b128 v[152:155], v210 offset:2048
	ds_read_b128 v[156:159], v210 offset:3072
	s_add_u32 s54, s52, 0xfffc0080
	s_addc_u32 s55, s53, -1
	s_cmp_eq_u32 s76, 12
	s_cselect_b32 s57, s5, s55
	s_cselect_b32 s56, s17, s54
	s_cselect_b32 s55, s31, s75
	s_cselect_b32 s54, s35, s51
	v_lshl_add_u64 v[214:215], s[52:53], 0, v[184:185]
	s_add_i32 m0, s62, 0xc000
	ds_read_b128 v[160:163], v211
	ds_read_b128 v[164:167], v211 offset:1024
	ds_read_b128 v[168:171], v211 offset:2048
	ds_read_b128 v[172:175], v211 offset:3072
	ds_read_b128 v[192:195], v211 offset:4096
	ds_read_b128 v[196:199], v211 offset:5120
	ds_read_b128 v[200:203], v211 offset:6144
	ds_read_b128 v[218:221], v211 offset:7168
	global_load_lds_dwordx4 v[214:215], off
	v_lshl_add_u64 v[214:215], s[52:53], 0, v[186:187]
	s_add_i32 m0, s62, 0xe000
	s_nop 0
	global_load_lds_dwordx4 v[214:215], off
	s_cmp_lg_u32 s76, -2
	s_cbranch_scc1 .Lzacc1a
	v_mov_b32_e32 v64, 0
	v_mov_b32_e32 v65, 0
	v_mov_b32_e32 v66, 0
	v_mov_b32_e32 v67, 0
	v_mov_b32_e32 v68, 0
	v_mov_b32_e32 v69, 0
	v_mov_b32_e32 v70, 0
	v_mov_b32_e32 v71, 0
	v_mov_b32_e32 v72, 0
	v_mov_b32_e32 v73, 0
	v_mov_b32_e32 v74, 0
	v_mov_b32_e32 v75, 0
	v_mov_b32_e32 v76, 0
	v_mov_b32_e32 v77, 0
	v_mov_b32_e32 v78, 0
	v_mov_b32_e32 v79, 0
	v_mov_b32_e32 v80, 0
	v_mov_b32_e32 v81, 0
	v_mov_b32_e32 v82, 0
	v_mov_b32_e32 v83, 0
	v_mov_b32_e32 v84, 0
	v_mov_b32_e32 v85, 0
	v_mov_b32_e32 v86, 0
	v_mov_b32_e32 v87, 0
	v_mov_b32_e32 v88, 0
	v_mov_b32_e32 v89, 0
	v_mov_b32_e32 v90, 0
	v_mov_b32_e32 v91, 0
	v_mov_b32_e32 v92, 0
	v_mov_b32_e32 v93, 0
	v_mov_b32_e32 v94, 0
	v_mov_b32_e32 v95, 0
	v_mov_b32_e32 v96, 0
	v_mov_b32_e32 v97, 0
	v_mov_b32_e32 v98, 0
	v_mov_b32_e32 v99, 0
	v_mov_b32_e32 v100, 0
	v_mov_b32_e32 v101, 0
	v_mov_b32_e32 v102, 0
	v_mov_b32_e32 v103, 0
	v_mov_b32_e32 v104, 0
	v_mov_b32_e32 v105, 0
	v_mov_b32_e32 v106, 0
	v_mov_b32_e32 v107, 0
	v_mov_b32_e32 v108, 0
	v_mov_b32_e32 v109, 0
	v_mov_b32_e32 v110, 0
	v_mov_b32_e32 v111, 0
	v_mov_b32_e32 v112, 0
	v_mov_b32_e32 v113, 0
	v_mov_b32_e32 v114, 0
	v_mov_b32_e32 v115, 0
	v_mov_b32_e32 v116, 0
	v_mov_b32_e32 v117, 0
	v_mov_b32_e32 v118, 0
	v_mov_b32_e32 v119, 0
	v_mov_b32_e32 v120, 0
	v_mov_b32_e32 v121, 0
	v_mov_b32_e32 v122, 0
	v_mov_b32_e32 v123, 0
	v_mov_b32_e32 v124, 0
	v_mov_b32_e32 v125, 0
	v_mov_b32_e32 v126, 0
	v_mov_b32_e32 v127, 0
.Lzacc1a:
	s_waitcnt vmcnt(8)
	s_waitcnt lgkmcnt(0)
	s_barrier
	s_setprio 1
	s_waitcnt lgkmcnt(0)
	v_mfma_f32_16x16x32_bf16 v[124:127], v[128:131], v[160:163], v[124:127]
	v_mfma_f32_16x16x32_bf16 v[120:123], v[136:139], v[160:163], v[120:123]
	v_mfma_f32_16x16x32_bf16 v[108:111], v[128:131], v[168:171], v[108:111]
	v_mfma_f32_16x16x32_bf16 v[104:107], v[136:139], v[168:171], v[104:107]
	v_mfma_f32_16x16x32_bf16 v[92:95], v[128:131], v[192:195], v[92:95]
	v_mfma_f32_16x16x32_bf16 v[88:91], v[136:139], v[192:195], v[88:91]
	v_mfma_f32_16x16x32_bf16 v[76:79], v[128:131], v[200:203], v[76:79]
	v_mfma_f32_16x16x32_bf16 v[72:75], v[136:139], v[200:203], v[72:75]
	v_mfma_f32_16x16x32_bf16 v[124:127], v[132:135], v[164:167], v[124:127]
	v_mfma_f32_16x16x32_bf16 v[120:123], v[140:143], v[164:167], v[120:123]
	v_mfma_f32_16x16x32_bf16 v[108:111], v[132:135], v[172:175], v[108:111]
	v_mfma_f32_16x16x32_bf16 v[104:107], v[140:143], v[172:175], v[104:107]
	v_mfma_f32_16x16x32_bf16 v[92:95], v[132:135], v[196:199], v[92:95]
	v_mfma_f32_16x16x32_bf16 v[88:91], v[140:143], v[196:199], v[88:91]
	v_mfma_f32_16x16x32_bf16 v[76:79], v[132:135], v[218:221], v[76:79]
	v_mfma_f32_16x16x32_bf16 v[72:75], v[140:143], v[218:221], v[72:75]
	s_setprio 0
	s_setprio 1
	v_mfma_f32_16x16x32_bf16 v[116:119], v[144:147], v[160:163], v[116:119]
	v_mfma_f32_16x16x32_bf16 v[112:115], v[152:155], v[160:163], v[112:115]
	v_mfma_f32_16x16x32_bf16 v[100:103], v[144:147], v[168:171], v[100:103]
	v_mfma_f32_16x16x32_bf16 v[96:99], v[152:155], v[168:171], v[96:99]
	v_mfma_f32_16x16x32_bf16 v[84:87], v[144:147], v[192:195], v[84:87]
	v_mfma_f32_16x16x32_bf16 v[80:83], v[152:155], v[192:195], v[80:83]
	v_mfma_f32_16x16x32_bf16 v[68:71], v[144:147], v[200:203], v[68:71]
	v_mfma_f32_16x16x32_bf16 v[64:67], v[152:155], v[200:203], v[64:67]
	v_mfma_f32_16x16x32_bf16 v[116:119], v[148:151], v[164:167], v[116:119]
	v_mfma_f32_16x16x32_bf16 v[112:115], v[156:159], v[164:167], v[112:115]
	v_mfma_f32_16x16x32_bf16 v[100:103], v[148:151], v[172:175], v[100:103]
	v_mfma_f32_16x16x32_bf16 v[96:99], v[156:159], v[172:175], v[96:99]
	v_mfma_f32_16x16x32_bf16 v[84:87], v[148:151], v[196:199], v[84:87]
	v_mfma_f32_16x16x32_bf16 v[80:83], v[156:159], v[196:199], v[80:83]
	v_mfma_f32_16x16x32_bf16 v[68:71], v[148:151], v[218:221], v[68:71]
	v_mfma_f32_16x16x32_bf16 v[64:67], v[156:159], v[218:221], v[64:67]
	s_setprio 0
	s_barrier
	s_add_i32 s77, s72, s61
	v_lshl_add_u64 v[214:215], s[54:55], 0, v[178:179]
	s_mov_b32 m0, s77
	ds_read_b128 v[160:163], v211 offset:16384
	ds_read_b128 v[164:167], v211 offset:17408
	ds_read_b128 v[168:171], v211 offset:18432
	ds_read_b128 v[172:175], v211 offset:19456
	ds_read_b128 v[192:195], v211 offset:20480
	ds_read_b128 v[196:199], v211 offset:21504
	ds_read_b128 v[200:203], v211 offset:22528
	ds_read_b128 v[218:221], v211 offset:23552
	global_load_lds_dwordx4 v[214:215], off
	s_add_i32 m0, s77, 0x2000
	s_add_u32 s78, s54, 0x40000
	v_lshl_add_u64 v[222:223], s[54:55], 0, v[182:183]
	s_addc_u32 s79, s55, 0
	s_add_i32 s77, s73, s61
	global_load_lds_dwordx4 v[222:223], off
	v_lshl_add_u64 v[224:225], s[78:79], 0, v[178:179]
	s_mov_b32 m0, s77
	v_lshl_add_u64 v[226:227], s[56:57], 0, v[180:181]
	global_load_lds_dwordx4 v[224:225], off
	v_lshl_add_u64 v[224:225], s[78:79], 0, v[182:183]
	s_add_i32 m0, s77, 0x2000
	s_nop 0
	global_load_lds_dwordx4 v[224:225], off
	v_lshl_add_u64 v[224:225], s[56:57], 0, v[176:177]
	s_mov_b32 m0, s62
	s_nop 0
	global_load_lds_dwordx4 v[224:225], off
	s_mov_b32 m0, s63
	s_nop 0
	global_load_lds_dwordx4 v[226:227], off
	s_cmp_lg_u32 s76, -2
	s_cbranch_scc1 .Lzacc1b
	v_mov_b32_e32 v0, 0
	v_mov_b32_e32 v1, 0
	v_mov_b32_e32 v2, 0
	v_mov_b32_e32 v3, 0
	v_mov_b32_e32 v4, 0
	v_mov_b32_e32 v5, 0
	v_mov_b32_e32 v6, 0
	v_mov_b32_e32 v7, 0
	v_mov_b32_e32 v8, 0
	v_mov_b32_e32 v9, 0
	v_mov_b32_e32 v10, 0
	v_mov_b32_e32 v11, 0
	v_mov_b32_e32 v12, 0
	v_mov_b32_e32 v13, 0
	v_mov_b32_e32 v14, 0
	v_mov_b32_e32 v15, 0
	v_mov_b32_e32 v16, 0
	v_mov_b32_e32 v17, 0
	v_mov_b32_e32 v18, 0
	v_mov_b32_e32 v19, 0
	v_mov_b32_e32 v20, 0
	v_mov_b32_e32 v21, 0
	v_mov_b32_e32 v22, 0
	v_mov_b32_e32 v23, 0
	v_mov_b32_e32 v24, 0
	v_mov_b32_e32 v25, 0
	v_mov_b32_e32 v26, 0
	v_mov_b32_e32 v27, 0
	v_mov_b32_e32 v28, 0
	v_mov_b32_e32 v29, 0
	v_mov_b32_e32 v30, 0
	v_mov_b32_e32 v31, 0
	v_mov_b32_e32 v32, 0
	v_mov_b32_e32 v33, 0
	v_mov_b32_e32 v34, 0
	v_mov_b32_e32 v35, 0
	v_mov_b32_e32 v36, 0
	v_mov_b32_e32 v37, 0
	v_mov_b32_e32 v38, 0
	v_mov_b32_e32 v39, 0
	v_mov_b32_e32 v40, 0
	v_mov_b32_e32 v41, 0
	v_mov_b32_e32 v42, 0
	v_mov_b32_e32 v43, 0
	v_mov_b32_e32 v44, 0
	v_mov_b32_e32 v45, 0
	v_mov_b32_e32 v46, 0
	v_mov_b32_e32 v47, 0
	v_mov_b32_e32 v48, 0
	v_mov_b32_e32 v49, 0
	v_mov_b32_e32 v50, 0
	v_mov_b32_e32 v51, 0
	v_mov_b32_e32 v52, 0
	v_mov_b32_e32 v53, 0
	v_mov_b32_e32 v54, 0
	v_mov_b32_e32 v55, 0
	v_mov_b32_e32 v56, 0
	v_mov_b32_e32 v57, 0
	v_mov_b32_e32 v58, 0
	v_mov_b32_e32 v59, 0
	v_mov_b32_e32 v60, 0
	v_mov_b32_e32 v61, 0
	v_mov_b32_e32 v62, 0
	v_mov_b32_e32 v63, 0
.Lzacc1b:
	s_waitcnt vmcnt(8)
	s_waitcnt lgkmcnt(0)
	s_barrier
	s_setprio 1
	s_waitcnt lgkmcnt(0)
	v_mfma_f32_16x16x32_bf16 v[60:63], v[128:131], v[160:163], v[60:63]
	v_mfma_f32_16x16x32_bf16 v[56:59], v[136:139], v[160:163], v[56:59]
	v_mfma_f32_16x16x32_bf16 v[44:47], v[128:131], v[168:171], v[44:47]
	v_mfma_f32_16x16x32_bf16 v[40:43], v[136:139], v[168:171], v[40:43]
	v_mfma_f32_16x16x32_bf16 v[28:31], v[128:131], v[192:195], v[28:31]
	v_mfma_f32_16x16x32_bf16 v[24:27], v[136:139], v[192:195], v[24:27]
	v_mfma_f32_16x16x32_bf16 v[12:15], v[128:131], v[200:203], v[12:15]
	v_mfma_f32_16x16x32_bf16 v[8:11], v[136:139], v[200:203], v[8:11]
	v_mfma_f32_16x16x32_bf16 v[60:63], v[132:135], v[164:167], v[60:63]
	v_mfma_f32_16x16x32_bf16 v[56:59], v[140:143], v[164:167], v[56:59]
	v_mfma_f32_16x16x32_bf16 v[44:47], v[132:135], v[172:175], v[44:47]
	v_mfma_f32_16x16x32_bf16 v[40:43], v[140:143], v[172:175], v[40:43]
	v_mfma_f32_16x16x32_bf16 v[28:31], v[132:135], v[196:199], v[28:31]
	v_mfma_f32_16x16x32_bf16 v[24:27], v[140:143], v[196:199], v[24:27]
	v_mfma_f32_16x16x32_bf16 v[12:15], v[132:135], v[218:221], v[12:15]
	v_mfma_f32_16x16x32_bf16 v[8:11], v[140:143], v[218:221], v[8:11]
	s_setprio 0
	s_setprio 1
	v_mfma_f32_16x16x32_bf16 v[52:55], v[144:147], v[160:163], v[52:55]
	v_mfma_f32_16x16x32_bf16 v[48:51], v[152:155], v[160:163], v[48:51]
	v_mfma_f32_16x16x32_bf16 v[36:39], v[144:147], v[168:171], v[36:39]
	v_mfma_f32_16x16x32_bf16 v[32:35], v[152:155], v[168:171], v[32:35]
	v_mfma_f32_16x16x32_bf16 v[20:23], v[144:147], v[192:195], v[20:23]
	v_mfma_f32_16x16x32_bf16 v[16:19], v[152:155], v[192:195], v[16:19]
	v_mfma_f32_16x16x32_bf16 v[4:7], v[144:147], v[200:203], v[4:7]
	v_mfma_f32_16x16x32_bf16 v[0:3], v[152:155], v[200:203], v[0:3]
	v_mfma_f32_16x16x32_bf16 v[52:55], v[148:151], v[164:167], v[52:55]
	v_mfma_f32_16x16x32_bf16 v[48:51], v[156:159], v[164:167], v[48:51]
	v_mfma_f32_16x16x32_bf16 v[36:39], v[148:151], v[172:175], v[36:39]
	v_mfma_f32_16x16x32_bf16 v[32:35], v[156:159], v[172:175], v[32:35]
	v_mfma_f32_16x16x32_bf16 v[20:23], v[148:151], v[196:199], v[20:23]
	v_mfma_f32_16x16x32_bf16 v[16:19], v[156:159], v[196:199], v[16:19]
	v_mfma_f32_16x16x32_bf16 v[4:7], v[148:151], v[218:221], v[4:7]
	v_mfma_f32_16x16x32_bf16 v[0:3], v[156:159], v[218:221], v[0:3]
	s_setprio 0
	s_barrier
	s_add_i32 s77, 0, 0x18000
	s_add_i32 s78, 0, 0x1c000
	v_add_u32_e32 v140, s77, v206
	v_add_u32_e32 v156, s78, v206
	ds_read_b128 v[128:131], v140
	ds_read_b128 v[132:135], v140 offset:1024
	ds_read_b128 v[136:139], v140 offset:2048
	ds_read_b128 v[140:143], v140 offset:3072
	ds_read_b128 v[144:147], v156
	ds_read_b128 v[148:151], v156 offset:1024
	ds_read_b128 v[152:155], v156 offset:2048
	ds_read_b128 v[156:159], v156 offset:3072
	s_add_u32 s56, s56, 0x40000
	s_addc_u32 s57, s57, 0
	s_mov_b32 m0, s64
	v_lshl_add_u64 v[228:229], s[56:57], 0, v[176:177]
	ds_read_b128 v[160:163], v211 offset:32768
	ds_read_b128 v[164:167], v211 offset:33792
	ds_read_b128 v[168:171], v211 offset:34816
	ds_read_b128 v[172:175], v211 offset:35840
	ds_read_b128 v[192:195], v211 offset:36864
	ds_read_b128 v[196:199], v211 offset:37888
	ds_read_b128 v[200:203], v211 offset:38912
	ds_read_b128 v[218:221], v211 offset:39936
	global_load_lds_dwordx4 v[228:229], off
	v_lshl_add_u64 v[228:229], s[56:57], 0, v[180:181]
	s_mov_b32 m0, s65
	s_nop 0
	global_load_lds_dwordx4 v[228:229], off
	s_waitcnt vmcnt(8)
	s_waitcnt lgkmcnt(0)
	s_barrier
	s_setprio 1
	s_waitcnt lgkmcnt(0)
	v_mfma_f32_16x16x32_bf16 v[124:127], v[128:131], v[160:163], v[124:127]
	v_mfma_f32_16x16x32_bf16 v[120:123], v[136:139], v[160:163], v[120:123]
	v_mfma_f32_16x16x32_bf16 v[108:111], v[128:131], v[168:171], v[108:111]
	v_mfma_f32_16x16x32_bf16 v[104:107], v[136:139], v[168:171], v[104:107]
	v_mfma_f32_16x16x32_bf16 v[92:95], v[128:131], v[192:195], v[92:95]
	v_mfma_f32_16x16x32_bf16 v[88:91], v[136:139], v[192:195], v[88:91]
	v_mfma_f32_16x16x32_bf16 v[76:79], v[128:131], v[200:203], v[76:79]
	v_mfma_f32_16x16x32_bf16 v[72:75], v[136:139], v[200:203], v[72:75]
	v_mfma_f32_16x16x32_bf16 v[124:127], v[132:135], v[164:167], v[124:127]
	v_mfma_f32_16x16x32_bf16 v[120:123], v[140:143], v[164:167], v[120:123]
	v_mfma_f32_16x16x32_bf16 v[108:111], v[132:135], v[172:175], v[108:111]
	v_mfma_f32_16x16x32_bf16 v[104:107], v[140:143], v[172:175], v[104:107]
	v_mfma_f32_16x16x32_bf16 v[92:95], v[132:135], v[196:199], v[92:95]
	v_mfma_f32_16x16x32_bf16 v[88:91], v[140:143], v[196:199], v[88:91]
	v_mfma_f32_16x16x32_bf16 v[76:79], v[132:135], v[218:221], v[76:79]
	v_mfma_f32_16x16x32_bf16 v[72:75], v[140:143], v[218:221], v[72:75]
	s_setprio 0
	s_setprio 1
	v_mfma_f32_16x16x32_bf16 v[116:119], v[144:147], v[160:163], v[116:119]
	v_mfma_f32_16x16x32_bf16 v[112:115], v[152:155], v[160:163], v[112:115]
	v_mfma_f32_16x16x32_bf16 v[100:103], v[144:147], v[168:171], v[100:103]
	v_mfma_f32_16x16x32_bf16 v[96:99], v[152:155], v[168:171], v[96:99]
	v_mfma_f32_16x16x32_bf16 v[84:87], v[144:147], v[192:195], v[84:87]
	v_mfma_f32_16x16x32_bf16 v[80:83], v[152:155], v[192:195], v[80:83]
	v_mfma_f32_16x16x32_bf16 v[68:71], v[144:147], v[200:203], v[68:71]
	v_mfma_f32_16x16x32_bf16 v[64:67], v[152:155], v[200:203], v[64:67]
	v_mfma_f32_16x16x32_bf16 v[116:119], v[148:151], v[164:167], v[116:119]
	v_mfma_f32_16x16x32_bf16 v[112:115], v[156:159], v[164:167], v[112:115]
	v_mfma_f32_16x16x32_bf16 v[100:103], v[148:151], v[172:175], v[100:103]
	v_mfma_f32_16x16x32_bf16 v[96:99], v[156:159], v[172:175], v[96:99]
	v_mfma_f32_16x16x32_bf16 v[84:87], v[148:151], v[196:199], v[84:87]
	v_mfma_f32_16x16x32_bf16 v[80:83], v[156:159], v[196:199], v[80:83]
	v_mfma_f32_16x16x32_bf16 v[68:71], v[148:151], v[218:221], v[68:71]
	v_mfma_f32_16x16x32_bf16 v[64:67], v[156:159], v[218:221], v[64:67]
	s_setprio 0
	s_barrier
	s_add_i32 s56, s77, s61
	v_lshl_add_u64 v[214:215], v[214:215], 0, s[26:27]
	s_mov_b32 m0, s56
	ds_read_b128 v[160:163], v211 offset:49152
	ds_read_b128 v[164:167], v211 offset:50176
	ds_read_b128 v[168:171], v211 offset:51200
	ds_read_b128 v[172:175], v211 offset:52224
	ds_read_b128 v[192:195], v211 offset:53248
	ds_read_b128 v[196:199], v211 offset:54272
	ds_read_b128 v[200:203], v211 offset:55296
	ds_read_b128 v[218:221], v211 offset:56320
	global_load_lds_dwordx4 v[214:215], off
	s_add_i32 m0, s56, 0x2000
	s_add_u32 s54, s54, 0x40080
	v_lshl_add_u64 v[214:215], v[222:223], 0, s[26:27]
	s_addc_u32 s55, s55, 0
	s_add_i32 s56, s78, s61
	global_load_lds_dwordx4 v[214:215], off
	v_lshl_add_u64 v[214:215], s[54:55], 0, v[178:179]
	s_mov_b32 m0, s56
	s_nop 0
	global_load_lds_dwordx4 v[214:215], off
	v_lshl_add_u64 v[214:215], s[54:55], 0, v[182:183]
	s_add_i32 m0, s56, 0x2000
	s_nop 0
	global_load_lds_dwordx4 v[214:215], off
	v_lshl_add_u64 v[214:215], v[224:225], 0, s[26:27]
	s_mov_b32 m0, s67
	s_nop 0
	global_load_lds_dwordx4 v[214:215], off
	v_lshl_add_u64 v[214:215], v[226:227], 0, s[26:27]
	s_mov_b32 m0, s68
	s_nop 0
	global_load_lds_dwordx4 v[214:215], off
	s_waitcnt vmcnt(8)
	s_waitcnt lgkmcnt(0)
	s_barrier
	s_setprio 1
	s_waitcnt lgkmcnt(0)
	v_mfma_f32_16x16x32_bf16 v[60:63], v[128:131], v[160:163], v[60:63]
	v_mfma_f32_16x16x32_bf16 v[56:59], v[136:139], v[160:163], v[56:59]
	v_mfma_f32_16x16x32_bf16 v[44:47], v[128:131], v[168:171], v[44:47]
	v_mfma_f32_16x16x32_bf16 v[40:43], v[136:139], v[168:171], v[40:43]
	v_mfma_f32_16x16x32_bf16 v[28:31], v[128:131], v[192:195], v[28:31]
	v_mfma_f32_16x16x32_bf16 v[24:27], v[136:139], v[192:195], v[24:27]
	v_mfma_f32_16x16x32_bf16 v[12:15], v[128:131], v[200:203], v[12:15]
	v_mfma_f32_16x16x32_bf16 v[8:11], v[136:139], v[200:203], v[8:11]
	v_mfma_f32_16x16x32_bf16 v[60:63], v[132:135], v[164:167], v[60:63]
	v_mfma_f32_16x16x32_bf16 v[56:59], v[140:143], v[164:167], v[56:59]
	v_mfma_f32_16x16x32_bf16 v[44:47], v[132:135], v[172:175], v[44:47]
	v_mfma_f32_16x16x32_bf16 v[40:43], v[140:143], v[172:175], v[40:43]
	v_mfma_f32_16x16x32_bf16 v[28:31], v[132:135], v[196:199], v[28:31]
	v_mfma_f32_16x16x32_bf16 v[24:27], v[140:143], v[196:199], v[24:27]
	v_mfma_f32_16x16x32_bf16 v[12:15], v[132:135], v[218:221], v[12:15]
	v_mfma_f32_16x16x32_bf16 v[8:11], v[140:143], v[218:221], v[8:11]
	s_setprio 0
	s_setprio 1
	v_mfma_f32_16x16x32_bf16 v[52:55], v[144:147], v[160:163], v[52:55]
	v_mfma_f32_16x16x32_bf16 v[48:51], v[152:155], v[160:163], v[48:51]
	v_mfma_f32_16x16x32_bf16 v[36:39], v[144:147], v[168:171], v[36:39]
	v_mfma_f32_16x16x32_bf16 v[32:35], v[152:155], v[168:171], v[32:35]
	v_mfma_f32_16x16x32_bf16 v[20:23], v[144:147], v[192:195], v[20:23]
	v_mfma_f32_16x16x32_bf16 v[16:19], v[152:155], v[192:195], v[16:19]
	v_mfma_f32_16x16x32_bf16 v[4:7], v[144:147], v[200:203], v[4:7]
	v_mfma_f32_16x16x32_bf16 v[0:3], v[152:155], v[200:203], v[0:3]
	v_mfma_f32_16x16x32_bf16 v[52:55], v[148:151], v[164:167], v[52:55]
	v_mfma_f32_16x16x32_bf16 v[48:51], v[156:159], v[164:167], v[48:51]
	v_mfma_f32_16x16x32_bf16 v[36:39], v[148:151], v[172:175], v[36:39]
	v_mfma_f32_16x16x32_bf16 v[32:35], v[156:159], v[172:175], v[32:35]
	v_mfma_f32_16x16x32_bf16 v[20:23], v[148:151], v[196:199], v[20:23]
	v_mfma_f32_16x16x32_bf16 v[16:19], v[156:159], v[196:199], v[16:19]
	v_mfma_f32_16x16x32_bf16 v[4:7], v[148:151], v[218:221], v[4:7]
	v_mfma_f32_16x16x32_bf16 v[0:3], v[156:159], v[218:221], v[0:3]
	s_setprio 0
	s_barrier
	s_add_i32 s76, s76, 2
	s_add_u32 s52, s52, 0x100
	s_addc_u32 s53, s53, 0
	s_add_u32 s51, s51, 0x100
	s_addc_u32 s75, s75, 0
	s_cmp_gt_u32 s76, 13
	s_cbranch_scc0 .LBB0_294
	s_and_b64 vcc, exec, s[28:29]
	s_cbranch_vccz .LBB0_297
	s_barrier

.LBB0_380:
	s_ashr_i32 s59, s58, 31
	s_lshl_b64 s[14:15], s[58:59], 19
	s_add_u32 s60, s65, s14
	s_addc_u32 s61, s66, s15
	s_and_b64 s[14:15], s[6:7], exec
	s_cselect_b32 s5, s61, s11
	s_cselect_b32 s51, s60, s10
	s_ashr_i32 s57, s56, 31
	s_lshl_b64 s[14:15], s[56:57], 19
	s_add_u32 s62, s21, s14
	s_addc_u32 s63, s64, s15
	s_and_b64 s[14:15], s[6:7], exec
	s_cselect_b32 s54, s63, s13
	s_cselect_b32 s55, s62, s12
	s_add_u32 s10, s10, 0x40080
	s_addc_u32 s11, s11, 0
	s_add_u32 s57, s12, 0x100
	s_addc_u32 s59, s13, 0
	s_mov_b32 s84, -2
.LBB0_381:
	ds_read_b128 v[128:131], v204
	ds_read_b128 v[132:135], v204 offset:1024
	ds_read_b128 v[136:139], v204 offset:2048
	ds_read_b128 v[140:143], v204 offset:3072
	ds_read_b128 v[144:147], v205
	ds_read_b128 v[148:151], v205 offset:1024
	ds_read_b128 v[152:155], v205 offset:2048
	ds_read_b128 v[156:159], v205 offset:3072
	s_add_u32 s12, s10, 0xfffc0080
	s_addc_u32 s13, s11, -1
	s_cmp_eq_u32 s84, 12
	s_cselect_b32 s15, s5, s13
	s_cselect_b32 s14, s51, s12
	s_cselect_b32 s13, s54, s59
	s_cselect_b32 s12, s55, s57
	v_lshl_add_u64 v[214:215], s[10:11], 0, v[178:179]
	s_add_i32 m0, s53, 0xc000
	ds_read_b128 v[160:163], v206
	ds_read_b128 v[164:167], v206 offset:1024
	ds_read_b128 v[186:189], v206 offset:2048
	ds_read_b128 v[190:193], v206 offset:3072
	ds_read_b128 v[194:197], v206 offset:4096
	ds_read_b128 v[198:201], v206 offset:5120
	ds_read_b128 v[210:213], v206 offset:6144
	ds_read_b128 v[218:221], v206 offset:7168
	global_load_lds_dwordx4 v[214:215], off
	v_lshl_add_u64 v[214:215], s[10:11], 0, v[180:181]
	s_add_i32 m0, s53, 0xe000
	s_nop 0
	global_load_lds_dwordx4 v[214:215], off
	s_cmp_lg_u32 s84, -2
	s_cbranch_scc1 .Lzacc2a
	v_mov_b32_e32 v24, 0
	v_mov_b32_e32 v25, 0
	v_mov_b32_e32 v26, 0
	v_mov_b32_e32 v27, 0
	v_mov_b32_e32 v36, 0
	v_mov_b32_e32 v37, 0
	v_mov_b32_e32 v38, 0
	v_mov_b32_e32 v39, 0
	v_mov_b32_e32 v52, 0
	v_mov_b32_e32 v53, 0
	v_mov_b32_e32 v54, 0
	v_mov_b32_e32 v55, 0
	v_mov_b32_e32 v64, 0
	v_mov_b32_e32 v65, 0
	v_mov_b32_e32 v66, 0
	v_mov_b32_e32 v67, 0
	v_mov_b32_e32 v80, 0
	v_mov_b32_e32 v81, 0
	v_mov_b32_e32 v82, 0
	v_mov_b32_e32 v83, 0
	v_mov_b32_e32 v84, 0
	v_mov_b32_e32 v85, 0
	v_mov_b32_e32 v86, 0
	v_mov_b32_e32 v87, 0
	v_mov_b32_e32 v88, 0
	v_mov_b32_e32 v89, 0
	v_mov_b32_e32 v90, 0
	v_mov_b32_e32 v91, 0
	v_mov_b32_e32 v92, 0
	v_mov_b32_e32 v93, 0
	v_mov_b32_e32 v94, 0
	v_mov_b32_e32 v95, 0
	v_mov_b32_e32 v96, 0
	v_mov_b32_e32 v97, 0
	v_mov_b32_e32 v98, 0
	v_mov_b32_e32 v99, 0
	v_mov_b32_e32 v100, 0
	v_mov_b32_e32 v101, 0
	v_mov_b32_e32 v102, 0
	v_mov_b32_e32 v103, 0
	v_mov_b32_e32 v104, 0
	v_mov_b32_e32 v105, 0
	v_mov_b32_e32 v106, 0
	v_mov_b32_e32 v107, 0
	v_mov_b32_e32 v108, 0
	v_mov_b32_e32 v109, 0
	v_mov_b32_e32 v110, 0
	v_mov_b32_e32 v111, 0
	v_mov_b32_e32 v112, 0
	v_mov_b32_e32 v113, 0
	v_mov_b32_e32 v114, 0
	v_mov_b32_e32 v115, 0
	v_mov_b32_e32 v116, 0
	v_mov_b32_e32 v117, 0
	v_mov_b32_e32 v118, 0
	v_mov_b32_e32 v119, 0
	v_mov_b32_e32 v120, 0
	v_mov_b32_e32 v121, 0
	v_mov_b32_e32 v122, 0
	v_mov_b32_e32 v123, 0
	v_mov_b32_e32 v124, 0
	v_mov_b32_e32 v125, 0
	v_mov_b32_e32 v126, 0
	v_mov_b32_e32 v127, 0
.Lzacc2a:
	s_waitcnt vmcnt(8)
	s_waitcnt lgkmcnt(0)
	s_barrier
	s_setprio 1
	s_waitcnt lgkmcnt(0)
	v_mfma_f32_16x16x32_bf16 v[124:127], v[128:131], v[160:163], v[124:127]
	v_mfma_f32_16x16x32_bf16 v[120:123], v[136:139], v[160:163], v[120:123]
	v_mfma_f32_16x16x32_bf16 v[116:119], v[128:131], v[186:189], v[116:119]
	v_mfma_f32_16x16x32_bf16 v[112:115], v[136:139], v[186:189], v[112:115]
	v_mfma_f32_16x16x32_bf16 v[108:111], v[128:131], v[194:197], v[108:111]
	v_mfma_f32_16x16x32_bf16 v[104:107], v[136:139], v[194:197], v[104:107]
	v_mfma_f32_16x16x32_bf16 v[92:95], v[128:131], v[210:213], v[92:95]
	v_mfma_f32_16x16x32_bf16 v[84:87], v[136:139], v[210:213], v[84:87]
	v_mfma_f32_16x16x32_bf16 v[124:127], v[132:135], v[164:167], v[124:127]
	v_mfma_f32_16x16x32_bf16 v[120:123], v[140:143], v[164:167], v[120:123]
	v_mfma_f32_16x16x32_bf16 v[116:119], v[132:135], v[190:193], v[116:119]
	v_mfma_f32_16x16x32_bf16 v[112:115], v[140:143], v[190:193], v[112:115]
	v_mfma_f32_16x16x32_bf16 v[108:111], v[132:135], v[198:201], v[108:111]
	v_mfma_f32_16x16x32_bf16 v[104:107], v[140:143], v[198:201], v[104:107]
	v_mfma_f32_16x16x32_bf16 v[92:95], v[132:135], v[218:221], v[92:95]
	v_mfma_f32_16x16x32_bf16 v[84:87], v[140:143], v[218:221], v[84:87]
	s_setprio 0
	s_setprio 1
	v_mfma_f32_16x16x32_bf16 v[88:91], v[144:147], v[160:163], v[88:91]
	v_mfma_f32_16x16x32_bf16 v[24:27], v[152:155], v[160:163], v[24:27]
	v_mfma_f32_16x16x32_bf16 v[100:103], v[144:147], v[186:189], v[100:103]
	v_mfma_f32_16x16x32_bf16 v[36:39], v[152:155], v[186:189], v[36:39]
	v_mfma_f32_16x16x32_bf16 v[96:99], v[144:147], v[194:197], v[96:99]
	v_mfma_f32_16x16x32_bf16 v[52:55], v[152:155], v[194:197], v[52:55]
	v_mfma_f32_16x16x32_bf16 v[80:83], v[144:147], v[210:213], v[80:83]
	v_mfma_f32_16x16x32_bf16 v[64:67], v[152:155], v[210:213], v[64:67]
	v_mfma_f32_16x16x32_bf16 v[88:91], v[148:151], v[164:167], v[88:91]
	v_mfma_f32_16x16x32_bf16 v[24:27], v[156:159], v[164:167], v[24:27]
	v_mfma_f32_16x16x32_bf16 v[100:103], v[148:151], v[190:193], v[100:103]
	v_mfma_f32_16x16x32_bf16 v[36:39], v[156:159], v[190:193], v[36:39]
	v_mfma_f32_16x16x32_bf16 v[96:99], v[148:151], v[198:201], v[96:99]
	v_mfma_f32_16x16x32_bf16 v[52:55], v[156:159], v[198:201], v[52:55]
	v_mfma_f32_16x16x32_bf16 v[80:83], v[148:151], v[218:221], v[80:83]
	v_mfma_f32_16x16x32_bf16 v[64:67], v[156:159], v[218:221], v[64:67]
	s_setprio 0
	s_barrier
	s_add_i32 s85, s83, s67
	v_lshl_add_u64 v[214:215], s[12:13], 0, v[172:173]
	s_mov_b32 m0, s85
	ds_read_b128 v[160:163], v206 offset:16384
	ds_read_b128 v[164:167], v206 offset:17408
	ds_read_b128 v[186:189], v206 offset:18432
	ds_read_b128 v[190:193], v206 offset:19456
	ds_read_b128 v[194:197], v206 offset:20480
	ds_read_b128 v[198:201], v206 offset:21504
	ds_read_b128 v[210:213], v206 offset:22528
	ds_read_b128 v[218:221], v206 offset:23552
	global_load_lds_dwordx4 v[214:215], off
	s_add_i32 m0, s85, 0x2000
	s_add_u32 s92, s12, 0x40000
	v_lshl_add_u64 v[222:223], s[12:13], 0, v[168:169]
	s_addc_u32 s93, s13, 0
	s_add_i32 s85, s94, s67
	global_load_lds_dwordx4 v[222:223], off
	v_lshl_add_u64 v[224:225], s[92:93], 0, v[172:173]
	s_mov_b32 m0, s85
	v_lshl_add_u64 v[226:227], s[14:15], 0, v[170:171]
	global_load_lds_dwordx4 v[224:225], off
	v_lshl_add_u64 v[224:225], s[92:93], 0, v[168:169]
	s_add_i32 m0, s85, 0x2000
	s_nop 0
	global_load_lds_dwordx4 v[224:225], off
	v_lshl_add_u64 v[224:225], s[14:15], 0, v[174:175]
	s_mov_b32 m0, s53
	s_nop 0
	global_load_lds_dwordx4 v[224:225], off
	s_mov_b32 m0, s68
	s_nop 0
	global_load_lds_dwordx4 v[226:227], off
	s_cmp_lg_u32 s84, -2
	s_cbranch_scc1 .Lzacc2b
	v_mov_b32_e32 v0, 0
	v_mov_b32_e32 v1, 0
	v_mov_b32_e32 v2, 0
	v_mov_b32_e32 v3, 0
	v_mov_b32_e32 v4, 0
	v_mov_b32_e32 v5, 0
	v_mov_b32_e32 v6, 0
	v_mov_b32_e32 v7, 0
	v_mov_b32_e32 v8, 0
	v_mov_b32_e32 v9, 0
	v_mov_b32_e32 v10, 0
	v_mov_b32_e32 v11, 0
	v_mov_b32_e32 v12, 0
	v_mov_b32_e32 v13, 0
	v_mov_b32_e32 v14, 0
	v_mov_b32_e32 v15, 0
	v_mov_b32_e32 v16, 0
	v_mov_b32_e32 v17, 0
	v_mov_b32_e32 v18, 0
	v_mov_b32_e32 v19, 0
	v_mov_b32_e32 v20, 0
	v_mov_b32_e32 v21, 0
	v_mov_b32_e32 v22, 0
	v_mov_b32_e32 v23, 0
	v_mov_b32_e32 v28, 0
	v_mov_b32_e32 v29, 0
	v_mov_b32_e32 v30, 0
	v_mov_b32_e32 v31, 0
	v_mov_b32_e32 v32, 0
	v_mov_b32_e32 v33, 0
	v_mov_b32_e32 v34, 0
	v_mov_b32_e32 v35, 0
	v_mov_b32_e32 v40, 0
	v_mov_b32_e32 v41, 0
	v_mov_b32_e32 v42, 0
	v_mov_b32_e32 v43, 0
	v_mov_b32_e32 v44, 0
	v_mov_b32_e32 v45, 0
	v_mov_b32_e32 v46, 0
	v_mov_b32_e32 v47, 0
	v_mov_b32_e32 v48, 0
	v_mov_b32_e32 v49, 0
	v_mov_b32_e32 v50, 0
	v_mov_b32_e32 v51, 0
	v_mov_b32_e32 v56, 0
	v_mov_b32_e32 v57, 0
	v_mov_b32_e32 v58, 0
	v_mov_b32_e32 v59, 0
	v_mov_b32_e32 v60, 0
	v_mov_b32_e32 v61, 0
	v_mov_b32_e32 v62, 0
	v_mov_b32_e32 v63, 0
	v_mov_b32_e32 v68, 0
	v_mov_b32_e32 v69, 0
	v_mov_b32_e32 v70, 0
	v_mov_b32_e32 v71, 0
	v_mov_b32_e32 v72, 0
	v_mov_b32_e32 v73, 0
	v_mov_b32_e32 v74, 0
	v_mov_b32_e32 v75, 0
	v_mov_b32_e32 v76, 0
	v_mov_b32_e32 v77, 0
	v_mov_b32_e32 v78, 0
	v_mov_b32_e32 v79, 0
.Lzacc2b:
	s_waitcnt vmcnt(8)
	s_waitcnt lgkmcnt(0)
	s_barrier
	s_setprio 1
	s_waitcnt lgkmcnt(0)
	v_mfma_f32_16x16x32_bf16 v[76:79], v[128:131], v[160:163], v[76:79]
	v_mfma_f32_16x16x32_bf16 v[72:75], v[136:139], v[160:163], v[72:75]
	v_mfma_f32_16x16x32_bf16 v[60:63], v[128:131], v[186:189], v[60:63]
	v_mfma_f32_16x16x32_bf16 v[56:59], v[136:139], v[186:189], v[56:59]
	v_mfma_f32_16x16x32_bf16 v[44:47], v[128:131], v[194:197], v[44:47]
	v_mfma_f32_16x16x32_bf16 v[40:43], v[136:139], v[194:197], v[40:43]
	v_mfma_f32_16x16x32_bf16 v[20:23], v[128:131], v[210:213], v[20:23]
	v_mfma_f32_16x16x32_bf16 v[8:11], v[136:139], v[210:213], v[8:11]
	v_mfma_f32_16x16x32_bf16 v[76:79], v[132:135], v[164:167], v[76:79]
	v_mfma_f32_16x16x32_bf16 v[72:75], v[140:143], v[164:167], v[72:75]
	v_mfma_f32_16x16x32_bf16 v[60:63], v[132:135], v[190:193], v[60:63]
	v_mfma_f32_16x16x32_bf16 v[56:59], v[140:143], v[190:193], v[56:59]
	v_mfma_f32_16x16x32_bf16 v[44:47], v[132:135], v[198:201], v[44:47]
	v_mfma_f32_16x16x32_bf16 v[40:43], v[140:143], v[198:201], v[40:43]
	v_mfma_f32_16x16x32_bf16 v[20:23], v[132:135], v[218:221], v[20:23]
	v_mfma_f32_16x16x32_bf16 v[8:11], v[140:143], v[218:221], v[8:11]
	s_setprio 0
	s_setprio 1
	v_mfma_f32_16x16x32_bf16 v[68:71], v[144:147], v[160:163], v[68:71]
	v_mfma_f32_16x16x32_bf16 v[12:15], v[152:155], v[160:163], v[12:15]
	v_mfma_f32_16x16x32_bf16 v[48:51], v[144:147], v[186:189], v[48:51]
	v_mfma_f32_16x16x32_bf16 v[28:31], v[152:155], v[186:189], v[28:31]
	v_mfma_f32_16x16x32_bf16 v[32:35], v[144:147], v[194:197], v[32:35]
	v_mfma_f32_16x16x32_bf16 v[16:19], v[152:155], v[194:197], v[16:19]
	v_mfma_f32_16x16x32_bf16 v[4:7], v[144:147], v[210:213], v[4:7]
	v_mfma_f32_16x16x32_bf16 v[0:3], v[152:155], v[210:213], v[0:3]
	v_mfma_f32_16x16x32_bf16 v[68:71], v[148:151], v[164:167], v[68:71]
	v_mfma_f32_16x16x32_bf16 v[12:15], v[156:159], v[164:167], v[12:15]
	v_mfma_f32_16x16x32_bf16 v[48:51], v[148:151], v[190:193], v[48:51]
	v_mfma_f32_16x16x32_bf16 v[28:31], v[156:159], v[190:193], v[28:31]
	v_mfma_f32_16x16x32_bf16 v[32:35], v[148:151], v[198:201], v[32:35]
	v_mfma_f32_16x16x32_bf16 v[16:19], v[156:159], v[198:201], v[16:19]
	v_mfma_f32_16x16x32_bf16 v[4:7], v[148:151], v[218:221], v[4:7]
	v_mfma_f32_16x16x32_bf16 v[0:3], v[156:159], v[218:221], v[0:3]
	s_setprio 0
	s_barrier
	s_add_i32 s85, 0, 0x18000
	s_add_i32 s89, 0, 0x1c000
	v_add_u32_e32 v140, s85, v203
	v_add_u32_e32 v156, s89, v203
	ds_read_b128 v[128:131], v140
	ds_read_b128 v[132:135], v140 offset:1024
	ds_read_b128 v[136:139], v140 offset:2048
	ds_read_b128 v[140:143], v140 offset:3072
	ds_read_b128 v[144:147], v156
	ds_read_b128 v[148:151], v156 offset:1024
	ds_read_b128 v[152:155], v156 offset:2048
	ds_read_b128 v[156:159], v156 offset:3072
	s_add_u32 s14, s14, 0x40000
	s_addc_u32 s15, s15, 0
	s_mov_b32 m0, s69
	v_lshl_add_u64 v[228:229], s[14:15], 0, v[174:175]
	ds_read_b128 v[160:163], v206 offset:32768
	ds_read_b128 v[164:167], v206 offset:33792
	ds_read_b128 v[186:189], v206 offset:34816
	ds_read_b128 v[190:193], v206 offset:35840
	ds_read_b128 v[194:197], v206 offset:36864
	ds_read_b128 v[198:201], v206 offset:37888
	ds_read_b128 v[210:213], v206 offset:38912
	ds_read_b128 v[218:221], v206 offset:39936
	global_load_lds_dwordx4 v[228:229], off
	v_lshl_add_u64 v[228:229], s[14:15], 0, v[170:171]
	s_mov_b32 m0, s72
	s_nop 0
	global_load_lds_dwordx4 v[228:229], off
	s_waitcnt vmcnt(8)
	s_waitcnt lgkmcnt(0)
	s_barrier
	s_setprio 1
	s_waitcnt lgkmcnt(0)
	v_mfma_f32_16x16x32_bf16 v[124:127], v[128:131], v[160:163], v[124:127]
	v_mfma_f32_16x16x32_bf16 v[120:123], v[136:139], v[160:163], v[120:123]
	v_mfma_f32_16x16x32_bf16 v[116:119], v[128:131], v[186:189], v[116:119]
	v_mfma_f32_16x16x32_bf16 v[112:115], v[136:139], v[186:189], v[112:115]
	v_mfma_f32_16x16x32_bf16 v[108:111], v[128:131], v[194:197], v[108:111]
	v_mfma_f32_16x16x32_bf16 v[104:107], v[136:139], v[194:197], v[104:107]
	v_mfma_f32_16x16x32_bf16 v[92:95], v[128:131], v[210:213], v[92:95]
	v_mfma_f32_16x16x32_bf16 v[84:87], v[136:139], v[210:213], v[84:87]
	v_mfma_f32_16x16x32_bf16 v[124:127], v[132:135], v[164:167], v[124:127]
	v_mfma_f32_16x16x32_bf16 v[120:123], v[140:143], v[164:167], v[120:123]
	v_mfma_f32_16x16x32_bf16 v[116:119], v[132:135], v[190:193], v[116:119]
	v_mfma_f32_16x16x32_bf16 v[112:115], v[140:143], v[190:193], v[112:115]
	v_mfma_f32_16x16x32_bf16 v[108:111], v[132:135], v[198:201], v[108:111]
	v_mfma_f32_16x16x32_bf16 v[104:107], v[140:143], v[198:201], v[104:107]
	v_mfma_f32_16x16x32_bf16 v[92:95], v[132:135], v[218:221], v[92:95]
	v_mfma_f32_16x16x32_bf16 v[84:87], v[140:143], v[218:221], v[84:87]
	s_setprio 0
	s_setprio 1
	v_mfma_f32_16x16x32_bf16 v[88:91], v[144:147], v[160:163], v[88:91]
	v_mfma_f32_16x16x32_bf16 v[24:27], v[152:155], v[160:163], v[24:27]
	v_mfma_f32_16x16x32_bf16 v[100:103], v[144:147], v[186:189], v[100:103]
	v_mfma_f32_16x16x32_bf16 v[36:39], v[152:155], v[186:189], v[36:39]
	v_mfma_f32_16x16x32_bf16 v[96:99], v[144:147], v[194:197], v[96:99]
	v_mfma_f32_16x16x32_bf16 v[52:55], v[152:155], v[194:197], v[52:55]
	v_mfma_f32_16x16x32_bf16 v[80:83], v[144:147], v[210:213], v[80:83]
	v_mfma_f32_16x16x32_bf16 v[64:67], v[152:155], v[210:213], v[64:67]
	v_mfma_f32_16x16x32_bf16 v[88:91], v[148:151], v[164:167], v[88:91]
	v_mfma_f32_16x16x32_bf16 v[24:27], v[156:159], v[164:167], v[24:27]
	v_mfma_f32_16x16x32_bf16 v[100:103], v[148:151], v[190:193], v[100:103]
	v_mfma_f32_16x16x32_bf16 v[36:39], v[156:159], v[190:193], v[36:39]
	v_mfma_f32_16x16x32_bf16 v[96:99], v[148:151], v[198:201], v[96:99]
	v_mfma_f32_16x16x32_bf16 v[52:55], v[156:159], v[198:201], v[52:55]
	v_mfma_f32_16x16x32_bf16 v[80:83], v[148:151], v[218:221], v[80:83]
	v_mfma_f32_16x16x32_bf16 v[64:67], v[156:159], v[218:221], v[64:67]
	s_setprio 0
	s_barrier
	s_add_i32 s14, s85, s67
	v_lshl_add_u64 v[214:215], v[214:215], 0, s[30:31]
	s_mov_b32 m0, s14
	ds_read_b128 v[160:163], v206 offset:49152
	ds_read_b128 v[164:167], v206 offset:50176
	ds_read_b128 v[186:189], v206 offset:51200
	ds_read_b128 v[190:193], v206 offset:52224
	ds_read_b128 v[194:197], v206 offset:53248
	ds_read_b128 v[198:201], v206 offset:54272
	ds_read_b128 v[210:213], v206 offset:55296
	ds_read_b128 v[218:221], v206 offset:56320
	global_load_lds_dwordx4 v[214:215], off
	s_add_i32 m0, s14, 0x2000
	s_add_u32 s12, s12, 0x40080
	v_lshl_add_u64 v[214:215], v[222:223], 0, s[30:31]
	s_addc_u32 s13, s13, 0
	s_add_i32 s14, s89, s67
	global_load_lds_dwordx4 v[214:215], off
	v_lshl_add_u64 v[214:215], s[12:13], 0, v[172:173]
	s_mov_b32 m0, s14
	s_nop 0
	global_load_lds_dwordx4 v[214:215], off
	v_lshl_add_u64 v[214:215], s[12:13], 0, v[168:169]
	s_add_i32 m0, s14, 0x2000
	s_nop 0
	global_load_lds_dwordx4 v[214:215], off
	v_lshl_add_u64 v[214:215], v[224:225], 0, s[30:31]
	s_mov_b32 m0, s77
	s_nop 0
	global_load_lds_dwordx4 v[214:215], off
	v_lshl_add_u64 v[214:215], v[226:227], 0, s[30:31]
	s_mov_b32 m0, s78
	s_nop 0
	global_load_lds_dwordx4 v[214:215], off
	s_waitcnt vmcnt(8)
	s_waitcnt lgkmcnt(0)
	s_barrier
	s_setprio 1
	s_waitcnt lgkmcnt(0)
	v_mfma_f32_16x16x32_bf16 v[76:79], v[128:131], v[160:163], v[76:79]
	v_mfma_f32_16x16x32_bf16 v[72:75], v[136:139], v[160:163], v[72:75]
	v_mfma_f32_16x16x32_bf16 v[60:63], v[128:131], v[186:189], v[60:63]
	v_mfma_f32_16x16x32_bf16 v[56:59], v[136:139], v[186:189], v[56:59]
	v_mfma_f32_16x16x32_bf16 v[44:47], v[128:131], v[194:197], v[44:47]
	v_mfma_f32_16x16x32_bf16 v[40:43], v[136:139], v[194:197], v[40:43]
	v_mfma_f32_16x16x32_bf16 v[20:23], v[128:131], v[210:213], v[20:23]
	v_mfma_f32_16x16x32_bf16 v[8:11], v[136:139], v[210:213], v[8:11]
	v_mfma_f32_16x16x32_bf16 v[76:79], v[132:135], v[164:167], v[76:79]
	v_mfma_f32_16x16x32_bf16 v[72:75], v[140:143], v[164:167], v[72:75]
	v_mfma_f32_16x16x32_bf16 v[60:63], v[132:135], v[190:193], v[60:63]
	v_mfma_f32_16x16x32_bf16 v[56:59], v[140:143], v[190:193], v[56:59]
	v_mfma_f32_16x16x32_bf16 v[44:47], v[132:135], v[198:201], v[44:47]
	v_mfma_f32_16x16x32_bf16 v[40:43], v[140:143], v[198:201], v[40:43]
	v_mfma_f32_16x16x32_bf16 v[20:23], v[132:135], v[218:221], v[20:23]
	v_mfma_f32_16x16x32_bf16 v[8:11], v[140:143], v[218:221], v[8:11]
	s_setprio 0
	s_setprio 1
	v_mfma_f32_16x16x32_bf16 v[68:71], v[144:147], v[160:163], v[68:71]
	v_mfma_f32_16x16x32_bf16 v[12:15], v[152:155], v[160:163], v[12:15]
	v_mfma_f32_16x16x32_bf16 v[48:51], v[144:147], v[186:189], v[48:51]
	v_mfma_f32_16x16x32_bf16 v[28:31], v[152:155], v[186:189], v[28:31]
	v_mfma_f32_16x16x32_bf16 v[32:35], v[144:147], v[194:197], v[32:35]
	v_mfma_f32_16x16x32_bf16 v[16:19], v[152:155], v[194:197], v[16:19]
	v_mfma_f32_16x16x32_bf16 v[4:7], v[144:147], v[210:213], v[4:7]
	v_mfma_f32_16x16x32_bf16 v[0:3], v[152:155], v[210:213], v[0:3]
	v_mfma_f32_16x16x32_bf16 v[68:71], v[148:151], v[164:167], v[68:71]
	v_mfma_f32_16x16x32_bf16 v[12:15], v[156:159], v[164:167], v[12:15]
	v_mfma_f32_16x16x32_bf16 v[48:51], v[148:151], v[190:193], v[48:51]
	v_mfma_f32_16x16x32_bf16 v[28:31], v[156:159], v[190:193], v[28:31]
	v_mfma_f32_16x16x32_bf16 v[32:35], v[148:151], v[198:201], v[32:35]
	v_mfma_f32_16x16x32_bf16 v[16:19], v[156:159], v[198:201], v[16:19]
	v_mfma_f32_16x16x32_bf16 v[4:7], v[148:151], v[218:221], v[4:7]
	v_mfma_f32_16x16x32_bf16 v[0:3], v[156:159], v[218:221], v[0:3]
	s_setprio 0
	s_barrier
	s_add_i32 s84, s84, 2
	s_add_u32 s10, s10, 0x100
	s_addc_u32 s11, s11, 0
	s_add_u32 s57, s57, 0x100
	s_addc_u32 s59, s59, 0
	s_cmp_gt_u32 s84, 13
	s_cbranch_scc0 .LBB0_381
	s_and_b64 vcc, exec, s[34:35]
	s_cbranch_vccz .LBB0_384
	s_barrier

.LBB0_540:
	s_add_u32 s15, s60, 0x100
	s_addc_u32 s54, s61, 0
	s_mov_b32 s55, -2
	s_waitcnt lgkmcnt(0)
.LBB0_541:
	ds_read_b128 v[112:115], v223
	ds_read_b128 v[124:127], v223 offset:1024
	ds_read_b128 v[136:139], v223 offset:2048
	ds_read_b128 v[140:143], v223 offset:3072
	ds_read_b128 v[144:147], v224
	ds_read_b128 v[148:151], v224 offset:1024
	ds_read_b128 v[152:155], v224 offset:2048
	ds_read_b128 v[156:159], v224 offset:3072
	s_add_u32 s60, s58, 0x100
	s_addc_u32 s61, s59, 0
	s_cmp_eq_u32 s55, 40
	s_cselect_b32 s65, s13, s61
	s_cselect_b32 s64, s12, s60
	s_cselect_b32 s63, s57, s54
	s_cselect_b32 s62, s56, s15
	v_lshl_add_u64 v[208:209], s[58:59], 0, v[192:193]
	s_add_i32 m0, s69, 0xc000
	ds_read_b128 v[160:163], v225
	ds_read_b128 v[164:167], v225 offset:1024
	ds_read_b128 v[168:171], v225 offset:2048
	ds_read_b128 v[172:175], v225 offset:3072
	ds_read_b128 v[176:179], v225 offset:4096
	ds_read_b128 v[180:183], v225 offset:5120
	ds_read_b128 v[200:203], v225 offset:6144
	ds_read_b128 v[204:207], v225 offset:7168
	global_load_lds_dwordx4 v[208:209], off
	v_lshl_add_u64 v[208:209], s[58:59], 0, v[194:195]
	s_add_i32 m0, s69, 0xe000
	s_nop 0
	global_load_lds_dwordx4 v[208:209], off
	s_cmp_lg_u32 s55, -2
	s_cbranch_scc1 .Lzacc3a
	v_mov_b32_e32 v64, 0
	v_mov_b32_e32 v65, 0
	v_mov_b32_e32 v66, 0
	v_mov_b32_e32 v67, 0
	v_mov_b32_e32 v68, 0
	v_mov_b32_e32 v69, 0
	v_mov_b32_e32 v70, 0
	v_mov_b32_e32 v71, 0
	v_mov_b32_e32 v72, 0
	v_mov_b32_e32 v73, 0
	v_mov_b32_e32 v74, 0
	v_mov_b32_e32 v75, 0
	v_mov_b32_e32 v76, 0
	v_mov_b32_e32 v77, 0
	v_mov_b32_e32 v78, 0
	v_mov_b32_e32 v79, 0
	v_mov_b32_e32 v80, 0
	v_mov_b32_e32 v81, 0
	v_mov_b32_e32 v82, 0
	v_mov_b32_e32 v83, 0
	v_mov_b32_e32 v84, 0
	v_mov_b32_e32 v85, 0
	v_mov_b32_e32 v86, 0
	v_mov_b32_e32 v87, 0
	v_mov_b32_e32 v88, 0
	v_mov_b32_e32 v89, 0
	v_mov_b32_e32 v90, 0
	v_mov_b32_e32 v91, 0
	v_mov_b32_e32 v92, 0
	v_mov_b32_e32 v93, 0
	v_mov_b32_e32 v94, 0
	v_mov_b32_e32 v95, 0
	v_mov_b32_e32 v96, 0
	v_mov_b32_e32 v97, 0
	v_mov_b32_e32 v98, 0
	v_mov_b32_e32 v99, 0
	v_mov_b32_e32 v100, 0
	v_mov_b32_e32 v101, 0
	v_mov_b32_e32 v102, 0
	v_mov_b32_e32 v103, 0
	v_mov_b32_e32 v104, 0
	v_mov_b32_e32 v105, 0
	v_mov_b32_e32 v106, 0
	v_mov_b32_e32 v107, 0
	v_mov_b32_e32 v108, 0
	v_mov_b32_e32 v109, 0
	v_mov_b32_e32 v110, 0
	v_mov_b32_e32 v111, 0
	v_mov_b32_e32 v116, 0
	v_mov_b32_e32 v117, 0
	v_mov_b32_e32 v118, 0
	v_mov_b32_e32 v119, 0
	v_mov_b32_e32 v120, 0
	v_mov_b32_e32 v121, 0
	v_mov_b32_e32 v122, 0
	v_mov_b32_e32 v123, 0
	v_mov_b32_e32 v128, 0
	v_mov_b32_e32 v129, 0
	v_mov_b32_e32 v130, 0
	v_mov_b32_e32 v131, 0
	v_mov_b32_e32 v132, 0
	v_mov_b32_e32 v133, 0
	v_mov_b32_e32 v134, 0
	v_mov_b32_e32 v135, 0
.Lzacc3a:
	s_waitcnt vmcnt(8)
	s_waitcnt lgkmcnt(0)
	s_barrier
	s_setprio 1
	s_waitcnt lgkmcnt(0)
	v_mfma_f32_16x16x32_bf16 v[132:135], v[112:115], v[160:163], v[132:135]
	v_mfma_f32_16x16x32_bf16 v[128:131], v[136:139], v[160:163], v[128:131]
	v_mfma_f32_16x16x32_bf16 v[108:111], v[112:115], v[168:171], v[108:111]
	v_mfma_f32_16x16x32_bf16 v[104:107], v[136:139], v[168:171], v[104:107]
	v_mfma_f32_16x16x32_bf16 v[92:95], v[112:115], v[176:179], v[92:95]
	v_mfma_f32_16x16x32_bf16 v[88:91], v[136:139], v[176:179], v[88:91]
	v_mfma_f32_16x16x32_bf16 v[76:79], v[112:115], v[200:203], v[76:79]
	v_mfma_f32_16x16x32_bf16 v[72:75], v[136:139], v[200:203], v[72:75]
	v_mfma_f32_16x16x32_bf16 v[132:135], v[124:127], v[164:167], v[132:135]
	v_mfma_f32_16x16x32_bf16 v[128:131], v[140:143], v[164:167], v[128:131]
	v_mfma_f32_16x16x32_bf16 v[108:111], v[124:127], v[172:175], v[108:111]
	v_mfma_f32_16x16x32_bf16 v[104:107], v[140:143], v[172:175], v[104:107]
	v_mfma_f32_16x16x32_bf16 v[92:95], v[124:127], v[180:183], v[92:95]
	v_mfma_f32_16x16x32_bf16 v[88:91], v[140:143], v[180:183], v[88:91]
	v_mfma_f32_16x16x32_bf16 v[76:79], v[124:127], v[204:207], v[76:79]
	v_mfma_f32_16x16x32_bf16 v[72:75], v[140:143], v[204:207], v[72:75]
	s_setprio 0
	s_setprio 1
	v_mfma_f32_16x16x32_bf16 v[120:123], v[144:147], v[160:163], v[120:123]
	v_mfma_f32_16x16x32_bf16 v[116:119], v[152:155], v[160:163], v[116:119]
	v_mfma_f32_16x16x32_bf16 v[100:103], v[144:147], v[168:171], v[100:103]
	v_mfma_f32_16x16x32_bf16 v[96:99], v[152:155], v[168:171], v[96:99]
	v_mfma_f32_16x16x32_bf16 v[84:87], v[144:147], v[176:179], v[84:87]
	v_mfma_f32_16x16x32_bf16 v[80:83], v[152:155], v[176:179], v[80:83]
	v_mfma_f32_16x16x32_bf16 v[68:71], v[144:147], v[200:203], v[68:71]
	v_mfma_f32_16x16x32_bf16 v[64:67], v[152:155], v[200:203], v[64:67]
	v_mfma_f32_16x16x32_bf16 v[120:123], v[148:151], v[164:167], v[120:123]
	v_mfma_f32_16x16x32_bf16 v[116:119], v[156:159], v[164:167], v[116:119]
	v_mfma_f32_16x16x32_bf16 v[100:103], v[148:151], v[172:175], v[100:103]
	v_mfma_f32_16x16x32_bf16 v[96:99], v[156:159], v[172:175], v[96:99]
	v_mfma_f32_16x16x32_bf16 v[84:87], v[148:151], v[180:183], v[84:87]
	v_mfma_f32_16x16x32_bf16 v[80:83], v[156:159], v[180:183], v[80:83]
	v_mfma_f32_16x16x32_bf16 v[68:71], v[148:151], v[204:207], v[68:71]
	v_mfma_f32_16x16x32_bf16 v[64:67], v[156:159], v[204:207], v[64:67]
	s_setprio 0
	s_barrier
	s_add_i32 s58, s78, s68
	v_lshl_add_u64 v[208:209], s[62:63], 0, v[186:187]
	s_mov_b32 m0, s58
	ds_read_b128 v[160:163], v225 offset:16384
	ds_read_b128 v[164:167], v225 offset:17408
	ds_read_b128 v[168:171], v225 offset:18432
	ds_read_b128 v[172:175], v225 offset:19456
	ds_read_b128 v[176:179], v225 offset:20480
	ds_read_b128 v[180:183], v225 offset:21504
	ds_read_b128 v[200:203], v225 offset:22528
	ds_read_b128 v[204:207], v225 offset:23552
	global_load_lds_dwordx4 v[208:209], off
	s_add_i32 m0, s58, 0x2000
	s_add_u32 s58, s62, 0xb0000
	v_lshl_add_u64 v[210:211], s[62:63], 0, v[190:191]
	s_addc_u32 s59, s63, 0
	s_add_i32 s83, s79, s68
	global_load_lds_dwordx4 v[210:211], off
	v_lshl_add_u64 v[212:213], s[58:59], 0, v[186:187]
	s_mov_b32 m0, s83
	v_lshl_add_u64 v[214:215], s[64:65], 0, v[188:189]
	global_load_lds_dwordx4 v[212:213], off
	v_lshl_add_u64 v[212:213], s[58:59], 0, v[190:191]
	s_add_i32 m0, s83, 0x2000
	s_nop 0
	global_load_lds_dwordx4 v[212:213], off
	v_lshl_add_u64 v[212:213], s[64:65], 0, v[184:185]
	s_mov_b32 m0, s69
	s_nop 0
	global_load_lds_dwordx4 v[212:213], off
	s_mov_b32 m0, s72
	s_nop 0
	global_load_lds_dwordx4 v[214:215], off
	s_cmp_lg_u32 s55, -2
	s_cbranch_scc1 .Lzacc3b
	v_mov_b32_e32 v0, 0
	v_mov_b32_e32 v1, 0
	v_mov_b32_e32 v2, 0
	v_mov_b32_e32 v3, 0
	v_mov_b32_e32 v4, 0
	v_mov_b32_e32 v5, 0
	v_mov_b32_e32 v6, 0
	v_mov_b32_e32 v7, 0
	v_mov_b32_e32 v8, 0
	v_mov_b32_e32 v9, 0
	v_mov_b32_e32 v10, 0
	v_mov_b32_e32 v11, 0
	v_mov_b32_e32 v12, 0
	v_mov_b32_e32 v13, 0
	v_mov_b32_e32 v14, 0
	v_mov_b32_e32 v15, 0
	v_mov_b32_e32 v16, 0
	v_mov_b32_e32 v17, 0
	v_mov_b32_e32 v18, 0
	v_mov_b32_e32 v19, 0
	v_mov_b32_e32 v20, 0
	v_mov_b32_e32 v21, 0
	v_mov_b32_e32 v22, 0
	v_mov_b32_e32 v23, 0
	v_mov_b32_e32 v24, 0
	v_mov_b32_e32 v25, 0
	v_mov_b32_e32 v26, 0
	v_mov_b32_e32 v27, 0
	v_mov_b32_e32 v28, 0
	v_mov_b32_e32 v29, 0
	v_mov_b32_e32 v30, 0
	v_mov_b32_e32 v31, 0
	v_mov_b32_e32 v32, 0
	v_mov_b32_e32 v33, 0
	v_mov_b32_e32 v34, 0
	v_mov_b32_e32 v35, 0
	v_mov_b32_e32 v36, 0
	v_mov_b32_e32 v37, 0
	v_mov_b32_e32 v38, 0
	v_mov_b32_e32 v39, 0
	v_mov_b32_e32 v40, 0
	v_mov_b32_e32 v41, 0
	v_mov_b32_e32 v42, 0
	v_mov_b32_e32 v43, 0
	v_mov_b32_e32 v44, 0
	v_mov_b32_e32 v45, 0
	v_mov_b32_e32 v46, 0
	v_mov_b32_e32 v47, 0
	v_mov_b32_e32 v48, 0
	v_mov_b32_e32 v49, 0
	v_mov_b32_e32 v50, 0
	v_mov_b32_e32 v51, 0
	v_mov_b32_e32 v52, 0
	v_mov_b32_e32 v53, 0
	v_mov_b32_e32 v54, 0
	v_mov_b32_e32 v55, 0
	v_mov_b32_e32 v56, 0
	v_mov_b32_e32 v57, 0
	v_mov_b32_e32 v58, 0
	v_mov_b32_e32 v59, 0
	v_mov_b32_e32 v60, 0
	v_mov_b32_e32 v61, 0
	v_mov_b32_e32 v62, 0
	v_mov_b32_e32 v63, 0
.Lzacc3b:
	s_waitcnt vmcnt(8)
	s_waitcnt lgkmcnt(0)
	s_barrier
	s_setprio 1
	s_waitcnt lgkmcnt(0)
	v_mfma_f32_16x16x32_bf16 v[60:63], v[112:115], v[160:163], v[60:63]
	v_mfma_f32_16x16x32_bf16 v[56:59], v[136:139], v[160:163], v[56:59]
	v_mfma_f32_16x16x32_bf16 v[44:47], v[112:115], v[168:171], v[44:47]
	v_mfma_f32_16x16x32_bf16 v[40:43], v[136:139], v[168:171], v[40:43]
	v_mfma_f32_16x16x32_bf16 v[28:31], v[112:115], v[176:179], v[28:31]
	v_mfma_f32_16x16x32_bf16 v[24:27], v[136:139], v[176:179], v[24:27]
	v_mfma_f32_16x16x32_bf16 v[12:15], v[112:115], v[200:203], v[12:15]
	v_mfma_f32_16x16x32_bf16 v[8:11], v[136:139], v[200:203], v[8:11]
	v_mfma_f32_16x16x32_bf16 v[60:63], v[124:127], v[164:167], v[60:63]
	v_mfma_f32_16x16x32_bf16 v[56:59], v[140:143], v[164:167], v[56:59]
	v_mfma_f32_16x16x32_bf16 v[44:47], v[124:127], v[172:175], v[44:47]
	v_mfma_f32_16x16x32_bf16 v[40:43], v[140:143], v[172:175], v[40:43]
	v_mfma_f32_16x16x32_bf16 v[28:31], v[124:127], v[180:183], v[28:31]
	v_mfma_f32_16x16x32_bf16 v[24:27], v[140:143], v[180:183], v[24:27]
	v_mfma_f32_16x16x32_bf16 v[12:15], v[124:127], v[204:207], v[12:15]
	v_mfma_f32_16x16x32_bf16 v[8:11], v[140:143], v[204:207], v[8:11]
	s_setprio 0
	s_setprio 1
	v_mfma_f32_16x16x32_bf16 v[52:55], v[144:147], v[160:163], v[52:55]
	v_mfma_f32_16x16x32_bf16 v[48:51], v[152:155], v[160:163], v[48:51]
	v_mfma_f32_16x16x32_bf16 v[36:39], v[144:147], v[168:171], v[36:39]
	v_mfma_f32_16x16x32_bf16 v[32:35], v[152:155], v[168:171], v[32:35]
	v_mfma_f32_16x16x32_bf16 v[20:23], v[144:147], v[176:179], v[20:23]
	v_mfma_f32_16x16x32_bf16 v[16:19], v[152:155], v[176:179], v[16:19]
	v_mfma_f32_16x16x32_bf16 v[4:7], v[144:147], v[200:203], v[4:7]
	v_mfma_f32_16x16x32_bf16 v[0:3], v[152:155], v[200:203], v[0:3]
	v_mfma_f32_16x16x32_bf16 v[52:55], v[148:151], v[164:167], v[52:55]
	v_mfma_f32_16x16x32_bf16 v[48:51], v[156:159], v[164:167], v[48:51]
	v_mfma_f32_16x16x32_bf16 v[36:39], v[148:151], v[172:175], v[36:39]
	v_mfma_f32_16x16x32_bf16 v[32:35], v[156:159], v[172:175], v[32:35]
	v_mfma_f32_16x16x32_bf16 v[20:23], v[148:151], v[180:183], v[20:23]
	v_mfma_f32_16x16x32_bf16 v[16:19], v[156:159], v[180:183], v[16:19]
	v_mfma_f32_16x16x32_bf16 v[4:7], v[148:151], v[204:207], v[4:7]
	v_mfma_f32_16x16x32_bf16 v[0:3], v[156:159], v[204:207], v[0:3]
	s_setprio 0
	s_barrier
	s_add_i32 s83, 0, 0x18000
	s_add_i32 s84, 0, 0x1c000
	v_add_u32_e32 v140, s83, v220
	v_add_u32_e32 v156, s84, v220
	ds_read_b128 v[112:115], v140
	ds_read_b128 v[124:127], v140 offset:1024
	ds_read_b128 v[136:139], v140 offset:2048
	ds_read_b128 v[140:143], v140 offset:3072
	ds_read_b128 v[144:147], v156
	ds_read_b128 v[148:151], v156 offset:1024
	ds_read_b128 v[152:155], v156 offset:2048
	ds_read_b128 v[156:159], v156 offset:3072
	s_add_u32 s58, s64, 0xb0000
	s_addc_u32 s59, s65, 0
	s_mov_b32 m0, s73
	v_lshl_add_u64 v[228:229], s[58:59], 0, v[184:185]
	ds_read_b128 v[160:163], v225 offset:32768
	ds_read_b128 v[164:167], v225 offset:33792
	ds_read_b128 v[168:171], v225 offset:34816
	ds_read_b128 v[172:175], v225 offset:35840
	ds_read_b128 v[176:179], v225 offset:36864
	ds_read_b128 v[180:183], v225 offset:37888
	ds_read_b128 v[200:203], v225 offset:38912
	ds_read_b128 v[204:207], v225 offset:39936
	global_load_lds_dwordx4 v[228:229], off
	v_lshl_add_u64 v[228:229], s[58:59], 0, v[188:189]
	s_mov_b32 m0, s74
	s_nop 0
	global_load_lds_dwordx4 v[228:229], off
	s_waitcnt vmcnt(8)
	s_waitcnt lgkmcnt(0)
	s_barrier
	s_setprio 1
	s_waitcnt lgkmcnt(0)
	v_mfma_f32_16x16x32_bf16 v[132:135], v[112:115], v[160:163], v[132:135]
	v_mfma_f32_16x16x32_bf16 v[128:131], v[136:139], v[160:163], v[128:131]
	v_mfma_f32_16x16x32_bf16 v[108:111], v[112:115], v[168:171], v[108:111]
	v_mfma_f32_16x16x32_bf16 v[104:107], v[136:139], v[168:171], v[104:107]
	v_mfma_f32_16x16x32_bf16 v[92:95], v[112:115], v[176:179], v[92:95]
	v_mfma_f32_16x16x32_bf16 v[88:91], v[136:139], v[176:179], v[88:91]
	v_mfma_f32_16x16x32_bf16 v[76:79], v[112:115], v[200:203], v[76:79]
	v_mfma_f32_16x16x32_bf16 v[72:75], v[136:139], v[200:203], v[72:75]
	v_mfma_f32_16x16x32_bf16 v[132:135], v[124:127], v[164:167], v[132:135]
	v_mfma_f32_16x16x32_bf16 v[128:131], v[140:143], v[164:167], v[128:131]
	v_mfma_f32_16x16x32_bf16 v[108:111], v[124:127], v[172:175], v[108:111]
	v_mfma_f32_16x16x32_bf16 v[104:107], v[140:143], v[172:175], v[104:107]
	v_mfma_f32_16x16x32_bf16 v[92:95], v[124:127], v[180:183], v[92:95]
	v_mfma_f32_16x16x32_bf16 v[88:91], v[140:143], v[180:183], v[88:91]
	v_mfma_f32_16x16x32_bf16 v[76:79], v[124:127], v[204:207], v[76:79]
	v_mfma_f32_16x16x32_bf16 v[72:75], v[140:143], v[204:207], v[72:75]
	s_setprio 0
	s_setprio 1
	v_mfma_f32_16x16x32_bf16 v[120:123], v[144:147], v[160:163], v[120:123]
	v_mfma_f32_16x16x32_bf16 v[116:119], v[152:155], v[160:163], v[116:119]
	v_mfma_f32_16x16x32_bf16 v[100:103], v[144:147], v[168:171], v[100:103]
	v_mfma_f32_16x16x32_bf16 v[96:99], v[152:155], v[168:171], v[96:99]
	v_mfma_f32_16x16x32_bf16 v[84:87], v[144:147], v[176:179], v[84:87]
	v_mfma_f32_16x16x32_bf16 v[80:83], v[152:155], v[176:179], v[80:83]
	v_mfma_f32_16x16x32_bf16 v[68:71], v[144:147], v[200:203], v[68:71]
	v_mfma_f32_16x16x32_bf16 v[64:67], v[152:155], v[200:203], v[64:67]
	v_mfma_f32_16x16x32_bf16 v[120:123], v[148:151], v[164:167], v[120:123]
	v_mfma_f32_16x16x32_bf16 v[116:119], v[156:159], v[164:167], v[116:119]
	v_mfma_f32_16x16x32_bf16 v[100:103], v[148:151], v[172:175], v[100:103]
	v_mfma_f32_16x16x32_bf16 v[96:99], v[156:159], v[172:175], v[96:99]
	v_mfma_f32_16x16x32_bf16 v[84:87], v[148:151], v[180:183], v[84:87]
	v_mfma_f32_16x16x32_bf16 v[80:83], v[156:159], v[180:183], v[80:83]
	v_mfma_f32_16x16x32_bf16 v[68:71], v[148:151], v[204:207], v[68:71]
	v_mfma_f32_16x16x32_bf16 v[64:67], v[156:159], v[204:207], v[64:67]
	s_setprio 0
	s_barrier
	s_add_i32 s58, s83, s68
	v_lshl_add_u64 v[208:209], v[208:209], 0, s[26:27]
	s_mov_b32 m0, s58
	ds_read_b128 v[160:163], v225 offset:49152
	ds_read_b128 v[164:167], v225 offset:50176
	ds_read_b128 v[168:171], v225 offset:51200
	ds_read_b128 v[172:175], v225 offset:52224
	ds_read_b128 v[176:179], v225 offset:53248
	ds_read_b128 v[180:183], v225 offset:54272
	ds_read_b128 v[200:203], v225 offset:55296
	ds_read_b128 v[204:207], v225 offset:56320
	global_load_lds_dwordx4 v[208:209], off
	s_add_i32 m0, s58, 0x2000
	s_add_u32 s58, s62, 0xb0080
	v_lshl_add_u64 v[208:209], v[210:211], 0, s[26:27]
	s_addc_u32 s59, s63, 0
	s_add_i32 s62, s84, s68
	global_load_lds_dwordx4 v[208:209], off
	v_lshl_add_u64 v[208:209], s[58:59], 0, v[186:187]
	s_mov_b32 m0, s62
	s_nop 0
	global_load_lds_dwordx4 v[208:209], off
	v_lshl_add_u64 v[208:209], s[58:59], 0, v[190:191]
	s_add_i32 m0, s62, 0x2000
	s_nop 0
	global_load_lds_dwordx4 v[208:209], off
	v_lshl_add_u64 v[208:209], v[212:213], 0, s[26:27]
	s_mov_b32 m0, s51
	s_nop 0
	global_load_lds_dwordx4 v[208:209], off
	v_lshl_add_u64 v[208:209], v[214:215], 0, s[26:27]
	s_mov_b32 m0, s76
	s_nop 0
	global_load_lds_dwordx4 v[208:209], off
	s_waitcnt vmcnt(8)
	s_waitcnt lgkmcnt(0)
	s_barrier
	s_setprio 1
	s_waitcnt lgkmcnt(0)
	v_mfma_f32_16x16x32_bf16 v[60:63], v[112:115], v[160:163], v[60:63]
	v_mfma_f32_16x16x32_bf16 v[56:59], v[136:139], v[160:163], v[56:59]
	v_mfma_f32_16x16x32_bf16 v[44:47], v[112:115], v[168:171], v[44:47]
	v_mfma_f32_16x16x32_bf16 v[40:43], v[136:139], v[168:171], v[40:43]
	v_mfma_f32_16x16x32_bf16 v[28:31], v[112:115], v[176:179], v[28:31]
	v_mfma_f32_16x16x32_bf16 v[24:27], v[136:139], v[176:179], v[24:27]
	v_mfma_f32_16x16x32_bf16 v[12:15], v[112:115], v[200:203], v[12:15]
	v_mfma_f32_16x16x32_bf16 v[8:11], v[136:139], v[200:203], v[8:11]
	v_mfma_f32_16x16x32_bf16 v[60:63], v[124:127], v[164:167], v[60:63]
	v_mfma_f32_16x16x32_bf16 v[56:59], v[140:143], v[164:167], v[56:59]
	v_mfma_f32_16x16x32_bf16 v[44:47], v[124:127], v[172:175], v[44:47]
	v_mfma_f32_16x16x32_bf16 v[40:43], v[140:143], v[172:175], v[40:43]
	v_mfma_f32_16x16x32_bf16 v[28:31], v[124:127], v[180:183], v[28:31]
	v_mfma_f32_16x16x32_bf16 v[24:27], v[140:143], v[180:183], v[24:27]
	v_mfma_f32_16x16x32_bf16 v[12:15], v[124:127], v[204:207], v[12:15]
	v_mfma_f32_16x16x32_bf16 v[8:11], v[140:143], v[204:207], v[8:11]
	s_setprio 0
	s_setprio 1
	v_mfma_f32_16x16x32_bf16 v[52:55], v[144:147], v[160:163], v[52:55]
	v_mfma_f32_16x16x32_bf16 v[48:51], v[152:155], v[160:163], v[48:51]
	v_mfma_f32_16x16x32_bf16 v[36:39], v[144:147], v[168:171], v[36:39]
	v_mfma_f32_16x16x32_bf16 v[32:35], v[152:155], v[168:171], v[32:35]
	v_mfma_f32_16x16x32_bf16 v[20:23], v[144:147], v[176:179], v[20:23]
	v_mfma_f32_16x16x32_bf16 v[16:19], v[152:155], v[176:179], v[16:19]
	v_mfma_f32_16x16x32_bf16 v[4:7], v[144:147], v[200:203], v[4:7]
	v_mfma_f32_16x16x32_bf16 v[0:3], v[152:155], v[200:203], v[0:3]
	v_mfma_f32_16x16x32_bf16 v[52:55], v[148:151], v[164:167], v[52:55]
	v_mfma_f32_16x16x32_bf16 v[48:51], v[156:159], v[164:167], v[48:51]
	v_mfma_f32_16x16x32_bf16 v[36:39], v[148:151], v[172:175], v[36:39]
	v_mfma_f32_16x16x32_bf16 v[32:35], v[156:159], v[172:175], v[32:35]
	v_mfma_f32_16x16x32_bf16 v[20:23], v[148:151], v[180:183], v[20:23]
	v_mfma_f32_16x16x32_bf16 v[16:19], v[156:159], v[180:183], v[16:19]
	v_mfma_f32_16x16x32_bf16 v[4:7], v[148:151], v[204:207], v[4:7]
	v_mfma_f32_16x16x32_bf16 v[0:3], v[156:159], v[204:207], v[0:3]
	s_setprio 0
	s_barrier
	s_add_i32 s55, s55, 2
	s_add_u32 s15, s15, 0x100
	s_addc_u32 s54, s54, 0
	s_cmp_gt_u32 s55, 41
	s_mov_b64 s[58:59], s[60:61]
	s_cbranch_scc0 .LBB0_541
	s_and_b64 vcc, exec, s[28:29]
	s_cbranch_vccz .LBB0_544
	s_barrier

.LBB0_627:
	s_ashr_i32 s27, s26, 31
	s_lshl_b64 s[28:29], s[26:27], 19
	s_add_u32 s28, s51, s28
	s_addc_u32 s29, s53, s29
	s_and_b64 s[30:31], s[6:7], exec
	s_cselect_b32 s21, s29, s35
	s_cselect_b32 s27, s28, s34
	s_ashr_i32 s25, s24, 31
	s_lshl_b64 s[30:31], s[24:25], 19
	s_add_u32 s30, s4, s30
	s_addc_u32 s31, s5, s31
	s_and_b64 s[38:39], s[6:7], exec
	s_cselect_b32 s25, s31, s37
	s_cselect_b32 s65, s30, s36
	s_add_u32 s34, s34, 0x40080
	s_addc_u32 s35, s35, 0
	s_add_u32 s66, s36, 0x100
	s_addc_u32 s67, s37, 0
	s_mov_b32 s68, -2
.LBB0_628:
	ds_read_b128 v[160:163], v154
	ds_read_b128 v[164:167], v154 offset:1024
	ds_read_b128 v[168:171], v154 offset:2048
	ds_read_b128 v[172:175], v154 offset:3072
	ds_read_b128 v[176:179], v155
	ds_read_b128 v[180:183], v155 offset:1024
	ds_read_b128 v[184:187], v155 offset:2048
	ds_read_b128 v[188:191], v155 offset:3072
	s_add_u32 s36, s34, 0xfffc0080
	s_addc_u32 s37, s35, -1
	s_cmp_eq_u32 s68, 12
	s_cselect_b32 s39, s21, s37
	s_cselect_b32 s38, s27, s36
	s_cselect_b32 s37, s25, s67
	s_cselect_b32 s36, s65, s66
	v_lshl_add_u64 v[152:153], s[34:35], 0, v[140:141]
	s_add_i32 m0, s8, 0xc000
	ds_read_b128 v[192:195], v156
	ds_read_b128 v[196:199], v156 offset:1024
	ds_read_b128 v[200:203], v156 offset:2048
	ds_read_b128 v[204:207], v156 offset:3072
	ds_read_b128 v[208:211], v156 offset:4096
	ds_read_b128 v[212:215], v156 offset:5120
	ds_read_b128 v[218:221], v156 offset:6144
	ds_read_b128 v[222:225], v156 offset:7168
	global_load_lds_dwordx4 v[152:153], off
	v_lshl_add_u64 v[152:153], s[34:35], 0, v[142:143]
	s_add_i32 m0, s8, 0xe000
	s_nop 0
	global_load_lds_dwordx4 v[152:153], off
	s_cmp_lg_u32 s68, -2
	s_cbranch_scc1 .Lzacc4a
	v_mov_b32_e32 v64, 0
	v_mov_b32_e32 v65, 0
	v_mov_b32_e32 v66, 0
	v_mov_b32_e32 v67, 0
	v_mov_b32_e32 v68, 0
	v_mov_b32_e32 v69, 0
	v_mov_b32_e32 v70, 0
	v_mov_b32_e32 v71, 0
	v_mov_b32_e32 v72, 0
	v_mov_b32_e32 v73, 0
	v_mov_b32_e32 v74, 0
	v_mov_b32_e32 v75, 0
	v_mov_b32_e32 v76, 0
	v_mov_b32_e32 v77, 0
	v_mov_b32_e32 v78, 0
	v_mov_b32_e32 v79, 0
	v_mov_b32_e32 v80, 0
	v_mov_b32_e32 v81, 0
	v_mov_b32_e32 v82, 0
	v_mov_b32_e32 v83, 0
	v_mov_b32_e32 v84, 0
	v_mov_b32_e32 v85, 0
	v_mov_b32_e32 v86, 0
	v_mov_b32_e32 v87, 0
	v_mov_b32_e32 v88, 0
	v_mov_b32_e32 v89, 0
	v_mov_b32_e32 v90, 0
	v_mov_b32_e32 v91, 0
	v_mov_b32_e32 v92, 0
	v_mov_b32_e32 v93, 0
	v_mov_b32_e32 v94, 0
	v_mov_b32_e32 v95, 0
	v_mov_b32_e32 v96, 0
	v_mov_b32_e32 v97, 0
	v_mov_b32_e32 v98, 0
	v_mov_b32_e32 v99, 0
	v_mov_b32_e32 v100, 0
	v_mov_b32_e32 v101, 0
	v_mov_b32_e32 v102, 0
	v_mov_b32_e32 v103, 0
	v_mov_b32_e32 v104, 0
	v_mov_b32_e32 v105, 0
	v_mov_b32_e32 v106, 0
	v_mov_b32_e32 v107, 0
	v_mov_b32_e32 v108, 0
	v_mov_b32_e32 v109, 0
	v_mov_b32_e32 v110, 0
	v_mov_b32_e32 v111, 0
	v_mov_b32_e32 v112, 0
	v_mov_b32_e32 v113, 0
	v_mov_b32_e32 v114, 0
	v_mov_b32_e32 v115, 0
	v_mov_b32_e32 v116, 0
	v_mov_b32_e32 v117, 0
	v_mov_b32_e32 v118, 0
	v_mov_b32_e32 v119, 0
	v_mov_b32_e32 v120, 0
	v_mov_b32_e32 v121, 0
	v_mov_b32_e32 v122, 0
	v_mov_b32_e32 v123, 0
	v_mov_b32_e32 v124, 0
	v_mov_b32_e32 v125, 0
	v_mov_b32_e32 v126, 0
	v_mov_b32_e32 v127, 0
.Lzacc4a:
	s_waitcnt vmcnt(8)
	s_waitcnt lgkmcnt(0)
	s_barrier
	s_setprio 1
	s_waitcnt lgkmcnt(0)
	v_mfma_f32_16x16x32_bf16 v[124:127], v[160:163], v[192:195], v[124:127]
	v_mfma_f32_16x16x32_bf16 v[120:123], v[168:171], v[192:195], v[120:123]
	v_mfma_f32_16x16x32_bf16 v[116:119], v[160:163], v[200:203], v[116:119]
	v_mfma_f32_16x16x32_bf16 v[108:111], v[168:171], v[200:203], v[108:111]
	v_mfma_f32_16x16x32_bf16 v[100:103], v[160:163], v[208:211], v[100:103]
	v_mfma_f32_16x16x32_bf16 v[92:95], v[168:171], v[208:211], v[92:95]
	v_mfma_f32_16x16x32_bf16 v[84:87], v[160:163], v[218:221], v[84:87]
	v_mfma_f32_16x16x32_bf16 v[76:79], v[168:171], v[218:221], v[76:79]
	v_mfma_f32_16x16x32_bf16 v[124:127], v[164:167], v[196:199], v[124:127]
	v_mfma_f32_16x16x32_bf16 v[120:123], v[172:175], v[196:199], v[120:123]
	v_mfma_f32_16x16x32_bf16 v[116:119], v[164:167], v[204:207], v[116:119]
	v_mfma_f32_16x16x32_bf16 v[108:111], v[172:175], v[204:207], v[108:111]
	v_mfma_f32_16x16x32_bf16 v[100:103], v[164:167], v[212:215], v[100:103]
	v_mfma_f32_16x16x32_bf16 v[92:95], v[172:175], v[212:215], v[92:95]
	v_mfma_f32_16x16x32_bf16 v[84:87], v[164:167], v[222:225], v[84:87]
	v_mfma_f32_16x16x32_bf16 v[76:79], v[172:175], v[222:225], v[76:79]
	s_setprio 0
	s_setprio 1
	v_mfma_f32_16x16x32_bf16 v[112:115], v[176:179], v[192:195], v[112:115]
	v_mfma_f32_16x16x32_bf16 v[104:107], v[184:187], v[192:195], v[104:107]
	v_mfma_f32_16x16x32_bf16 v[96:99], v[176:179], v[200:203], v[96:99]
	v_mfma_f32_16x16x32_bf16 v[88:91], v[184:187], v[200:203], v[88:91]
	v_mfma_f32_16x16x32_bf16 v[80:83], v[176:179], v[208:211], v[80:83]
	v_mfma_f32_16x16x32_bf16 v[72:75], v[184:187], v[208:211], v[72:75]
	v_mfma_f32_16x16x32_bf16 v[68:71], v[176:179], v[218:221], v[68:71]
	v_mfma_f32_16x16x32_bf16 v[64:67], v[184:187], v[218:221], v[64:67]
	v_mfma_f32_16x16x32_bf16 v[112:115], v[180:183], v[196:199], v[112:115]
	v_mfma_f32_16x16x32_bf16 v[104:107], v[188:191], v[196:199], v[104:107]
	v_mfma_f32_16x16x32_bf16 v[96:99], v[180:183], v[204:207], v[96:99]
	v_mfma_f32_16x16x32_bf16 v[88:91], v[188:191], v[204:207], v[88:91]
	v_mfma_f32_16x16x32_bf16 v[80:83], v[180:183], v[212:215], v[80:83]
	v_mfma_f32_16x16x32_bf16 v[72:75], v[188:191], v[212:215], v[72:75]
	v_mfma_f32_16x16x32_bf16 v[68:71], v[180:183], v[222:225], v[68:71]
	v_mfma_f32_16x16x32_bf16 v[64:67], v[188:191], v[222:225], v[64:67]
	s_setprio 0
	s_barrier
	s_add_i32 s69, s63, s54
	v_lshl_add_u64 v[152:153], s[36:37], 0, v[132:133]
	s_mov_b32 m0, s69
	ds_read_b128 v[192:195], v156 offset:16384
	ds_read_b128 v[196:199], v156 offset:17408
	ds_read_b128 v[200:203], v156 offset:18432
	ds_read_b128 v[204:207], v156 offset:19456
	ds_read_b128 v[208:211], v156 offset:20480
	ds_read_b128 v[212:215], v156 offset:21504
	ds_read_b128 v[218:221], v156 offset:22528
	ds_read_b128 v[222:225], v156 offset:23552
	global_load_lds_dwordx4 v[152:153], off
	s_add_i32 m0, s69, 0x2000
	s_add_u32 s72, s36, 0x40000
	v_lshl_add_u64 v[226:227], s[36:37], 0, v[128:129]
	s_addc_u32 s73, s37, 0
	s_add_i32 s69, s64, s54
	global_load_lds_dwordx4 v[226:227], off
	v_lshl_add_u64 v[228:229], s[72:73], 0, v[132:133]
	s_mov_b32 m0, s69
	v_lshl_add_u64 v[230:231], s[38:39], 0, v[130:131]
	global_load_lds_dwordx4 v[228:229], off
	v_lshl_add_u64 v[228:229], s[72:73], 0, v[128:129]
	s_add_i32 m0, s69, 0x2000
	s_nop 0
	global_load_lds_dwordx4 v[228:229], off
	v_lshl_add_u64 v[228:229], s[38:39], 0, v[134:135]
	s_mov_b32 m0, s8
	s_nop 0
	global_load_lds_dwordx4 v[228:229], off
	s_mov_b32 m0, s55
	s_nop 0
	global_load_lds_dwordx4 v[230:231], off
	s_cmp_lg_u32 s68, -2
	s_cbranch_scc1 .Lzacc4b
	v_mov_b32_e32 v0, 0
	v_mov_b32_e32 v1, 0
	v_mov_b32_e32 v2, 0
	v_mov_b32_e32 v3, 0
	v_mov_b32_e32 v4, 0
	v_mov_b32_e32 v5, 0
	v_mov_b32_e32 v6, 0
	v_mov_b32_e32 v7, 0
	v_mov_b32_e32 v8, 0
	v_mov_b32_e32 v9, 0
	v_mov_b32_e32 v10, 0
	v_mov_b32_e32 v11, 0
	v_mov_b32_e32 v12, 0
	v_mov_b32_e32 v13, 0
	v_mov_b32_e32 v14, 0
	v_mov_b32_e32 v15, 0
	v_mov_b32_e32 v16, 0
	v_mov_b32_e32 v17, 0
	v_mov_b32_e32 v18, 0
	v_mov_b32_e32 v19, 0
	v_mov_b32_e32 v20, 0
	v_mov_b32_e32 v21, 0
	v_mov_b32_e32 v22, 0
	v_mov_b32_e32 v23, 0
	v_mov_b32_e32 v24, 0
	v_mov_b32_e32 v25, 0
	v_mov_b32_e32 v26, 0
	v_mov_b32_e32 v27, 0
	v_mov_b32_e32 v28, 0
	v_mov_b32_e32 v29, 0
	v_mov_b32_e32 v30, 0
	v_mov_b32_e32 v31, 0
	v_mov_b32_e32 v32, 0
	v_mov_b32_e32 v33, 0
	v_mov_b32_e32 v34, 0
	v_mov_b32_e32 v35, 0
	v_mov_b32_e32 v36, 0
	v_mov_b32_e32 v37, 0
	v_mov_b32_e32 v38, 0
	v_mov_b32_e32 v39, 0
	v_mov_b32_e32 v40, 0
	v_mov_b32_e32 v41, 0
	v_mov_b32_e32 v42, 0
	v_mov_b32_e32 v43, 0
	v_mov_b32_e32 v44, 0
	v_mov_b32_e32 v45, 0
	v_mov_b32_e32 v46, 0
	v_mov_b32_e32 v47, 0
	v_mov_b32_e32 v48, 0
	v_mov_b32_e32 v49, 0
	v_mov_b32_e32 v50, 0
	v_mov_b32_e32 v51, 0
	v_mov_b32_e32 v52, 0
	v_mov_b32_e32 v53, 0
	v_mov_b32_e32 v54, 0
	v_mov_b32_e32 v55, 0
	v_mov_b32_e32 v56, 0
	v_mov_b32_e32 v57, 0
	v_mov_b32_e32 v58, 0
	v_mov_b32_e32 v59, 0
	v_mov_b32_e32 v60, 0
	v_mov_b32_e32 v61, 0
	v_mov_b32_e32 v62, 0
	v_mov_b32_e32 v63, 0
.Lzacc4b:
	s_waitcnt vmcnt(8)
	s_waitcnt lgkmcnt(0)
	s_barrier
	s_setprio 1
	s_waitcnt lgkmcnt(0)
	v_mfma_f32_16x16x32_bf16 v[60:63], v[160:163], v[192:195], v[60:63]
	v_mfma_f32_16x16x32_bf16 v[56:59], v[168:171], v[192:195], v[56:59]
	v_mfma_f32_16x16x32_bf16 v[52:55], v[160:163], v[200:203], v[52:55]
	v_mfma_f32_16x16x32_bf16 v[44:47], v[168:171], v[200:203], v[44:47]
	v_mfma_f32_16x16x32_bf16 v[36:39], v[160:163], v[208:211], v[36:39]
	v_mfma_f32_16x16x32_bf16 v[28:31], v[168:171], v[208:211], v[28:31]
	v_mfma_f32_16x16x32_bf16 v[20:23], v[160:163], v[218:221], v[20:23]
	v_mfma_f32_16x16x32_bf16 v[12:15], v[168:171], v[218:221], v[12:15]
	v_mfma_f32_16x16x32_bf16 v[60:63], v[164:167], v[196:199], v[60:63]
	v_mfma_f32_16x16x32_bf16 v[56:59], v[172:175], v[196:199], v[56:59]
	v_mfma_f32_16x16x32_bf16 v[52:55], v[164:167], v[204:207], v[52:55]
	v_mfma_f32_16x16x32_bf16 v[44:47], v[172:175], v[204:207], v[44:47]
	v_mfma_f32_16x16x32_bf16 v[36:39], v[164:167], v[212:215], v[36:39]
	v_mfma_f32_16x16x32_bf16 v[28:31], v[172:175], v[212:215], v[28:31]
	v_mfma_f32_16x16x32_bf16 v[20:23], v[164:167], v[222:225], v[20:23]
	v_mfma_f32_16x16x32_bf16 v[12:15], v[172:175], v[222:225], v[12:15]
	s_setprio 0
	s_setprio 1
	v_mfma_f32_16x16x32_bf16 v[48:51], v[176:179], v[192:195], v[48:51]
	v_mfma_f32_16x16x32_bf16 v[40:43], v[184:187], v[192:195], v[40:43]
	v_mfma_f32_16x16x32_bf16 v[32:35], v[176:179], v[200:203], v[32:35]
	v_mfma_f32_16x16x32_bf16 v[24:27], v[184:187], v[200:203], v[24:27]
	v_mfma_f32_16x16x32_bf16 v[16:19], v[176:179], v[208:211], v[16:19]
	v_mfma_f32_16x16x32_bf16 v[8:11], v[184:187], v[208:211], v[8:11]
	v_mfma_f32_16x16x32_bf16 v[4:7], v[176:179], v[218:221], v[4:7]
	v_mfma_f32_16x16x32_bf16 v[0:3], v[184:187], v[218:221], v[0:3]
	v_mfma_f32_16x16x32_bf16 v[48:51], v[180:183], v[196:199], v[48:51]
	v_mfma_f32_16x16x32_bf16 v[40:43], v[188:191], v[196:199], v[40:43]
	v_mfma_f32_16x16x32_bf16 v[32:35], v[180:183], v[204:207], v[32:35]
	v_mfma_f32_16x16x32_bf16 v[24:27], v[188:191], v[204:207], v[24:27]
	v_mfma_f32_16x16x32_bf16 v[16:19], v[180:183], v[212:215], v[16:19]
	v_mfma_f32_16x16x32_bf16 v[8:11], v[188:191], v[212:215], v[8:11]
	v_mfma_f32_16x16x32_bf16 v[4:7], v[180:183], v[222:225], v[4:7]
	v_mfma_f32_16x16x32_bf16 v[0:3], v[188:191], v[222:225], v[0:3]
	s_setprio 0
	s_barrier
	s_add_i32 s69, 0, 0x18000
	v_add_u32_e32 v136, s69, v151
	s_add_i32 s71, 0, 0x1c000
	ds_read_b128 v[160:163], v136
	ds_read_b128 v[164:167], v136 offset:1024
	ds_read_b128 v[168:171], v136 offset:2048
	ds_read_b128 v[172:175], v136 offset:3072
	v_add_u32_e32 v136, s71, v151
	ds_read_b128 v[176:179], v136
	ds_read_b128 v[180:183], v136 offset:1024
	ds_read_b128 v[184:187], v136 offset:2048
	ds_read_b128 v[188:191], v136 offset:3072
	s_add_u32 s38, s38, 0x40000
	s_addc_u32 s39, s39, 0
	s_mov_b32 m0, s56
	v_lshl_add_u64 v[232:233], s[38:39], 0, v[134:135]
	ds_read_b128 v[192:195], v156 offset:32768
	ds_read_b128 v[196:199], v156 offset:33792
	ds_read_b128 v[200:203], v156 offset:34816
	ds_read_b128 v[204:207], v156 offset:35840
	ds_read_b128 v[208:211], v156 offset:36864
	ds_read_b128 v[212:215], v156 offset:37888
	ds_read_b128 v[218:221], v156 offset:38912
	ds_read_b128 v[222:225], v156 offset:39936
	global_load_lds_dwordx4 v[232:233], off
	v_lshl_add_u64 v[232:233], s[38:39], 0, v[130:131]
	s_mov_b32 m0, s57
	s_nop 0
	global_load_lds_dwordx4 v[232:233], off
	s_waitcnt vmcnt(8)
	s_waitcnt lgkmcnt(0)
	s_barrier
	s_setprio 1
	s_waitcnt lgkmcnt(0)
	v_mfma_f32_16x16x32_bf16 v[124:127], v[160:163], v[192:195], v[124:127]
	v_mfma_f32_16x16x32_bf16 v[120:123], v[168:171], v[192:195], v[120:123]
	v_mfma_f32_16x16x32_bf16 v[116:119], v[160:163], v[200:203], v[116:119]
	v_mfma_f32_16x16x32_bf16 v[108:111], v[168:171], v[200:203], v[108:111]
	v_mfma_f32_16x16x32_bf16 v[100:103], v[160:163], v[208:211], v[100:103]
	v_mfma_f32_16x16x32_bf16 v[92:95], v[168:171], v[208:211], v[92:95]
	v_mfma_f32_16x16x32_bf16 v[84:87], v[160:163], v[218:221], v[84:87]
	v_mfma_f32_16x16x32_bf16 v[76:79], v[168:171], v[218:221], v[76:79]
	v_mfma_f32_16x16x32_bf16 v[124:127], v[164:167], v[196:199], v[124:127]
	v_mfma_f32_16x16x32_bf16 v[120:123], v[172:175], v[196:199], v[120:123]
	v_mfma_f32_16x16x32_bf16 v[116:119], v[164:167], v[204:207], v[116:119]
	v_mfma_f32_16x16x32_bf16 v[108:111], v[172:175], v[204:207], v[108:111]
	v_mfma_f32_16x16x32_bf16 v[100:103], v[164:167], v[212:215], v[100:103]
	v_mfma_f32_16x16x32_bf16 v[92:95], v[172:175], v[212:215], v[92:95]
	v_mfma_f32_16x16x32_bf16 v[84:87], v[164:167], v[222:225], v[84:87]
	v_mfma_f32_16x16x32_bf16 v[76:79], v[172:175], v[222:225], v[76:79]
	s_setprio 0
	s_setprio 1
	v_mfma_f32_16x16x32_bf16 v[112:115], v[176:179], v[192:195], v[112:115]
	v_mfma_f32_16x16x32_bf16 v[104:107], v[184:187], v[192:195], v[104:107]
	v_mfma_f32_16x16x32_bf16 v[96:99], v[176:179], v[200:203], v[96:99]
	v_mfma_f32_16x16x32_bf16 v[88:91], v[184:187], v[200:203], v[88:91]
	v_mfma_f32_16x16x32_bf16 v[80:83], v[176:179], v[208:211], v[80:83]
	v_mfma_f32_16x16x32_bf16 v[72:75], v[184:187], v[208:211], v[72:75]
	v_mfma_f32_16x16x32_bf16 v[68:71], v[176:179], v[218:221], v[68:71]
	v_mfma_f32_16x16x32_bf16 v[64:67], v[184:187], v[218:221], v[64:67]
	v_mfma_f32_16x16x32_bf16 v[112:115], v[180:183], v[196:199], v[112:115]
	v_mfma_f32_16x16x32_bf16 v[104:107], v[188:191], v[196:199], v[104:107]
	v_mfma_f32_16x16x32_bf16 v[96:99], v[180:183], v[204:207], v[96:99]
	v_mfma_f32_16x16x32_bf16 v[88:91], v[188:191], v[204:207], v[88:91]
	v_mfma_f32_16x16x32_bf16 v[80:83], v[180:183], v[212:215], v[80:83]
	v_mfma_f32_16x16x32_bf16 v[72:75], v[188:191], v[212:215], v[72:75]
	v_mfma_f32_16x16x32_bf16 v[68:71], v[180:183], v[222:225], v[68:71]
	v_mfma_f32_16x16x32_bf16 v[64:67], v[188:191], v[222:225], v[64:67]
	s_setprio 0
	s_barrier
	s_add_i32 s38, s69, s54
	v_lshl_add_u64 v[152:153], v[152:153], 0, s[14:15]
	s_mov_b32 m0, s38
	ds_read_b128 v[192:195], v156 offset:49152
	ds_read_b128 v[196:199], v156 offset:50176
	ds_read_b128 v[200:203], v156 offset:51200
	ds_read_b128 v[204:207], v156 offset:52224
	ds_read_b128 v[208:211], v156 offset:53248
	ds_read_b128 v[212:215], v156 offset:54272
	ds_read_b128 v[218:221], v156 offset:55296
	ds_read_b128 v[222:225], v156 offset:56320
	global_load_lds_dwordx4 v[152:153], off
	s_add_i32 m0, s38, 0x2000
	s_add_u32 s36, s36, 0x40080
	v_lshl_add_u64 v[152:153], v[226:227], 0, s[14:15]
	s_addc_u32 s37, s37, 0
	s_add_i32 s38, s71, s54
	global_load_lds_dwordx4 v[152:153], off
	v_lshl_add_u64 v[152:153], s[36:37], 0, v[132:133]
	s_mov_b32 m0, s38
	s_nop 0
	global_load_lds_dwordx4 v[152:153], off
	v_lshl_add_u64 v[152:153], s[36:37], 0, v[128:129]
	s_add_i32 m0, s38, 0x2000
	s_nop 0
	global_load_lds_dwordx4 v[152:153], off
	v_lshl_add_u64 v[152:153], v[228:229], 0, s[14:15]
	s_mov_b32 m0, s59
	s_nop 0
	global_load_lds_dwordx4 v[152:153], off
	v_lshl_add_u64 v[152:153], v[230:231], 0, s[14:15]
	s_mov_b32 m0, s60
	s_nop 0
	global_load_lds_dwordx4 v[152:153], off
	s_waitcnt vmcnt(8)
	s_waitcnt lgkmcnt(0)
	s_barrier
	s_setprio 1
	s_waitcnt lgkmcnt(0)
	v_mfma_f32_16x16x32_bf16 v[60:63], v[160:163], v[192:195], v[60:63]
	v_mfma_f32_16x16x32_bf16 v[56:59], v[168:171], v[192:195], v[56:59]
	v_mfma_f32_16x16x32_bf16 v[52:55], v[160:163], v[200:203], v[52:55]
	v_mfma_f32_16x16x32_bf16 v[44:47], v[168:171], v[200:203], v[44:47]
	v_mfma_f32_16x16x32_bf16 v[36:39], v[160:163], v[208:211], v[36:39]
	v_mfma_f32_16x16x32_bf16 v[28:31], v[168:171], v[208:211], v[28:31]
	v_mfma_f32_16x16x32_bf16 v[20:23], v[160:163], v[218:221], v[20:23]
	v_mfma_f32_16x16x32_bf16 v[12:15], v[168:171], v[218:221], v[12:15]
	v_mfma_f32_16x16x32_bf16 v[60:63], v[164:167], v[196:199], v[60:63]
	v_mfma_f32_16x16x32_bf16 v[56:59], v[172:175], v[196:199], v[56:59]
	v_mfma_f32_16x16x32_bf16 v[52:55], v[164:167], v[204:207], v[52:55]
	v_mfma_f32_16x16x32_bf16 v[44:47], v[172:175], v[204:207], v[44:47]
	v_mfma_f32_16x16x32_bf16 v[36:39], v[164:167], v[212:215], v[36:39]
	v_mfma_f32_16x16x32_bf16 v[28:31], v[172:175], v[212:215], v[28:31]
	v_mfma_f32_16x16x32_bf16 v[20:23], v[164:167], v[222:225], v[20:23]
	v_mfma_f32_16x16x32_bf16 v[12:15], v[172:175], v[222:225], v[12:15]
	s_setprio 0
	s_setprio 1
	v_mfma_f32_16x16x32_bf16 v[48:51], v[176:179], v[192:195], v[48:51]
	v_mfma_f32_16x16x32_bf16 v[40:43], v[184:187], v[192:195], v[40:43]
	v_mfma_f32_16x16x32_bf16 v[32:35], v[176:179], v[200:203], v[32:35]
	v_mfma_f32_16x16x32_bf16 v[24:27], v[184:187], v[200:203], v[24:27]
	v_mfma_f32_16x16x32_bf16 v[16:19], v[176:179], v[208:211], v[16:19]
	v_mfma_f32_16x16x32_bf16 v[8:11], v[184:187], v[208:211], v[8:11]
	v_mfma_f32_16x16x32_bf16 v[4:7], v[176:179], v[218:221], v[4:7]
	v_mfma_f32_16x16x32_bf16 v[0:3], v[184:187], v[218:221], v[0:3]
	v_mfma_f32_16x16x32_bf16 v[48:51], v[180:183], v[196:199], v[48:51]
	v_mfma_f32_16x16x32_bf16 v[40:43], v[188:191], v[196:199], v[40:43]
	v_mfma_f32_16x16x32_bf16 v[32:35], v[180:183], v[204:207], v[32:35]
	v_mfma_f32_16x16x32_bf16 v[24:27], v[188:191], v[204:207], v[24:27]
	v_mfma_f32_16x16x32_bf16 v[16:19], v[180:183], v[212:215], v[16:19]
	v_mfma_f32_16x16x32_bf16 v[8:11], v[188:191], v[212:215], v[8:11]
	v_mfma_f32_16x16x32_bf16 v[4:7], v[180:183], v[222:225], v[4:7]
	v_mfma_f32_16x16x32_bf16 v[0:3], v[188:191], v[222:225], v[0:3]
	s_setprio 0
	s_barrier
	s_add_i32 s68, s68, 2
	s_add_u32 s34, s34, 0x100
	s_addc_u32 s35, s35, 0
	s_add_u32 s66, s66, 0x100
	s_addc_u32 s67, s67, 0
	s_cmp_gt_u32 s68, 13
	s_cbranch_scc0 .LBB0_628
	s_and_b64 vcc, exec, s[16:17]
	s_cbranch_vccz .LBB0_631
	s_barrier

.LBB0_903:
	s_ashr_i32 s37, s36, 31
	s_lshl_b64 s[38:39], s[36:37], 19
	s_add_u32 s38, s67, s38
	s_addc_u32 s39, s68, s39
	s_and_b64 s[54:55], s[10:11], exec
	s_cselect_b32 s5, s39, s61
	s_cselect_b32 s13, s38, s60
	s_ashr_i32 s35, s34, 31
	s_lshl_b64 s[54:55], s[34:35], 19
	s_add_u32 s56, s53, s54
	s_addc_u32 s57, s66, s55
	s_and_b64 s[54:55], s[10:11], exec
	s_cselect_b32 s35, s57, s63
	s_cselect_b32 s37, s56, s62
	s_add_u32 s60, s60, 0x40080
	s_addc_u32 s61, s61, 0
	s_add_u32 s54, s62, 0x100
	s_addc_u32 s55, s63, 0
	s_mov_b32 s59, -2
	s_waitcnt lgkmcnt(0)
	s_waitcnt vmcnt(0)
.LBB0_904:
	ds_read_b128 v[112:115], v223
	ds_read_b128 v[124:127], v223 offset:1024
	ds_read_b128 v[136:139], v223 offset:2048
	ds_read_b128 v[140:143], v223 offset:3072
	ds_read_b128 v[144:147], v224
	ds_read_b128 v[148:151], v224 offset:1024
	ds_read_b128 v[152:155], v224 offset:2048
	ds_read_b128 v[156:159], v224 offset:3072
	s_add_u32 s46, s60, 0xfffc0080
	s_addc_u32 s47, s61, -1
	s_cmp_eq_u32 s59, 12
	s_cselect_b32 s65, s5, s47
	s_cselect_b32 s64, s13, s46
	s_cselect_b32 s63, s35, s55
	s_cselect_b32 s62, s37, s54
	v_lshl_add_u64 v[208:209], s[60:61], 0, v[192:193]
	s_add_i32 m0, s70, 0xc000
	ds_read_b128 v[160:163], v225
	ds_read_b128 v[164:167], v225 offset:1024
	ds_read_b128 v[168:171], v225 offset:2048
	ds_read_b128 v[172:175], v225 offset:3072
	ds_read_b128 v[176:179], v225 offset:4096
	ds_read_b128 v[180:183], v225 offset:5120
	ds_read_b128 v[200:203], v225 offset:6144
	ds_read_b128 v[204:207], v225 offset:7168
	global_load_lds_dwordx4 v[208:209], off
	v_lshl_add_u64 v[208:209], s[60:61], 0, v[194:195]
	s_add_i32 m0, s70, 0xe000
	s_nop 0
	global_load_lds_dwordx4 v[208:209], off
	s_cmp_lg_u32 s59, -2
	s_cbranch_scc1 .Lzacc5a
	v_mov_b32_e32 v64, 0
	v_mov_b32_e32 v65, 0
	v_mov_b32_e32 v66, 0
	v_mov_b32_e32 v67, 0
	v_mov_b32_e32 v68, 0
	v_mov_b32_e32 v69, 0
	v_mov_b32_e32 v70, 0
	v_mov_b32_e32 v71, 0
	v_mov_b32_e32 v72, 0
	v_mov_b32_e32 v73, 0
	v_mov_b32_e32 v74, 0
	v_mov_b32_e32 v75, 0
	v_mov_b32_e32 v76, 0
	v_mov_b32_e32 v77, 0
	v_mov_b32_e32 v78, 0
	v_mov_b32_e32 v79, 0
	v_mov_b32_e32 v80, 0
	v_mov_b32_e32 v81, 0
	v_mov_b32_e32 v82, 0
	v_mov_b32_e32 v83, 0
	v_mov_b32_e32 v84, 0
	v_mov_b32_e32 v85, 0
	v_mov_b32_e32 v86, 0
	v_mov_b32_e32 v87, 0
	v_mov_b32_e32 v88, 0
	v_mov_b32_e32 v89, 0
	v_mov_b32_e32 v90, 0
	v_mov_b32_e32 v91, 0
	v_mov_b32_e32 v92, 0
	v_mov_b32_e32 v93, 0
	v_mov_b32_e32 v94, 0
	v_mov_b32_e32 v95, 0
	v_mov_b32_e32 v96, 0
	v_mov_b32_e32 v97, 0
	v_mov_b32_e32 v98, 0
	v_mov_b32_e32 v99, 0
	v_mov_b32_e32 v100, 0
	v_mov_b32_e32 v101, 0
	v_mov_b32_e32 v102, 0
	v_mov_b32_e32 v103, 0
	v_mov_b32_e32 v104, 0
	v_mov_b32_e32 v105, 0
	v_mov_b32_e32 v106, 0
	v_mov_b32_e32 v107, 0
	v_mov_b32_e32 v108, 0
	v_mov_b32_e32 v109, 0
	v_mov_b32_e32 v110, 0
	v_mov_b32_e32 v111, 0
	v_mov_b32_e32 v116, 0
	v_mov_b32_e32 v117, 0
	v_mov_b32_e32 v118, 0
	v_mov_b32_e32 v119, 0
	v_mov_b32_e32 v120, 0
	v_mov_b32_e32 v121, 0
	v_mov_b32_e32 v122, 0
	v_mov_b32_e32 v123, 0
	v_mov_b32_e32 v128, 0
	v_mov_b32_e32 v129, 0
	v_mov_b32_e32 v130, 0
	v_mov_b32_e32 v131, 0
	v_mov_b32_e32 v132, 0
	v_mov_b32_e32 v133, 0
	v_mov_b32_e32 v134, 0
	v_mov_b32_e32 v135, 0
.Lzacc5a:
	s_waitcnt vmcnt(8)
	s_waitcnt lgkmcnt(0)
	s_barrier
	s_setprio 1
	s_waitcnt lgkmcnt(0)
	v_mfma_f32_16x16x32_bf16 v[132:135], v[112:115], v[160:163], v[132:135]
	v_mfma_f32_16x16x32_bf16 v[128:131], v[136:139], v[160:163], v[128:131]
	v_mfma_f32_16x16x32_bf16 v[108:111], v[112:115], v[168:171], v[108:111]
	v_mfma_f32_16x16x32_bf16 v[104:107], v[136:139], v[168:171], v[104:107]
	v_mfma_f32_16x16x32_bf16 v[92:95], v[112:115], v[176:179], v[92:95]
	v_mfma_f32_16x16x32_bf16 v[88:91], v[136:139], v[176:179], v[88:91]
	v_mfma_f32_16x16x32_bf16 v[76:79], v[112:115], v[200:203], v[76:79]
	v_mfma_f32_16x16x32_bf16 v[72:75], v[136:139], v[200:203], v[72:75]
	v_mfma_f32_16x16x32_bf16 v[132:135], v[124:127], v[164:167], v[132:135]
	v_mfma_f32_16x16x32_bf16 v[128:131], v[140:143], v[164:167], v[128:131]
	v_mfma_f32_16x16x32_bf16 v[108:111], v[124:127], v[172:175], v[108:111]
	v_mfma_f32_16x16x32_bf16 v[104:107], v[140:143], v[172:175], v[104:107]
	v_mfma_f32_16x16x32_bf16 v[92:95], v[124:127], v[180:183], v[92:95]
	v_mfma_f32_16x16x32_bf16 v[88:91], v[140:143], v[180:183], v[88:91]
	v_mfma_f32_16x16x32_bf16 v[76:79], v[124:127], v[204:207], v[76:79]
	v_mfma_f32_16x16x32_bf16 v[72:75], v[140:143], v[204:207], v[72:75]
	s_setprio 0
	s_setprio 1
	v_mfma_f32_16x16x32_bf16 v[120:123], v[144:147], v[160:163], v[120:123]
	v_mfma_f32_16x16x32_bf16 v[116:119], v[152:155], v[160:163], v[116:119]
	v_mfma_f32_16x16x32_bf16 v[100:103], v[144:147], v[168:171], v[100:103]
	v_mfma_f32_16x16x32_bf16 v[96:99], v[152:155], v[168:171], v[96:99]
	v_mfma_f32_16x16x32_bf16 v[84:87], v[144:147], v[176:179], v[84:87]
	v_mfma_f32_16x16x32_bf16 v[80:83], v[152:155], v[176:179], v[80:83]
	v_mfma_f32_16x16x32_bf16 v[68:71], v[144:147], v[200:203], v[68:71]
	v_mfma_f32_16x16x32_bf16 v[64:67], v[152:155], v[200:203], v[64:67]
	v_mfma_f32_16x16x32_bf16 v[120:123], v[148:151], v[164:167], v[120:123]
	v_mfma_f32_16x16x32_bf16 v[116:119], v[156:159], v[164:167], v[116:119]
	v_mfma_f32_16x16x32_bf16 v[100:103], v[148:151], v[172:175], v[100:103]
	v_mfma_f32_16x16x32_bf16 v[96:99], v[156:159], v[172:175], v[96:99]
	v_mfma_f32_16x16x32_bf16 v[84:87], v[148:151], v[180:183], v[84:87]
	v_mfma_f32_16x16x32_bf16 v[80:83], v[156:159], v[180:183], v[80:83]
	v_mfma_f32_16x16x32_bf16 v[68:71], v[148:151], v[204:207], v[68:71]
	v_mfma_f32_16x16x32_bf16 v[64:67], v[156:159], v[204:207], v[64:67]
	s_setprio 0
	s_barrier
	s_add_i32 s46, s77, s69
	v_lshl_add_u64 v[208:209], s[62:63], 0, v[186:187]
	s_mov_b32 m0, s46
	ds_read_b128 v[160:163], v225 offset:16384
	ds_read_b128 v[164:167], v225 offset:17408
	ds_read_b128 v[168:171], v225 offset:18432
	ds_read_b128 v[172:175], v225 offset:19456
	ds_read_b128 v[176:179], v225 offset:20480
	ds_read_b128 v[180:183], v225 offset:21504
	ds_read_b128 v[200:203], v225 offset:22528
	ds_read_b128 v[204:207], v225 offset:23552
	global_load_lds_dwordx4 v[208:209], off
	s_add_i32 m0, s46, 0x2000
	s_add_u32 s80, s62, 0x40000
	v_lshl_add_u64 v[210:211], s[62:63], 0, v[190:191]
	s_addc_u32 s81, s63, 0
	s_add_i32 s46, s78, s69
	global_load_lds_dwordx4 v[210:211], off
	v_lshl_add_u64 v[212:213], s[80:81], 0, v[186:187]
	s_mov_b32 m0, s46
	v_lshl_add_u64 v[214:215], s[64:65], 0, v[188:189]
	global_load_lds_dwordx4 v[212:213], off
	v_lshl_add_u64 v[212:213], s[80:81], 0, v[190:191]
	s_add_i32 m0, s46, 0x2000
	s_nop 0
	global_load_lds_dwordx4 v[212:213], off
	v_lshl_add_u64 v[212:213], s[64:65], 0, v[184:185]
	s_mov_b32 m0, s70
	s_nop 0
	global_load_lds_dwordx4 v[212:213], off
	s_mov_b32 m0, s71
	s_nop 0
	global_load_lds_dwordx4 v[214:215], off
	s_cmp_lg_u32 s59, -2
	s_cbranch_scc1 .Lzacc5b
	v_mov_b32_e32 v0, 0
	v_mov_b32_e32 v1, 0
	v_mov_b32_e32 v2, 0
	v_mov_b32_e32 v3, 0
	v_mov_b32_e32 v4, 0
	v_mov_b32_e32 v5, 0
	v_mov_b32_e32 v6, 0
	v_mov_b32_e32 v7, 0
	v_mov_b32_e32 v8, 0
	v_mov_b32_e32 v9, 0
	v_mov_b32_e32 v10, 0
	v_mov_b32_e32 v11, 0
	v_mov_b32_e32 v12, 0
	v_mov_b32_e32 v13, 0
	v_mov_b32_e32 v14, 0
	v_mov_b32_e32 v15, 0
	v_mov_b32_e32 v16, 0
	v_mov_b32_e32 v17, 0
	v_mov_b32_e32 v18, 0
	v_mov_b32_e32 v19, 0
	v_mov_b32_e32 v20, 0
	v_mov_b32_e32 v21, 0
	v_mov_b32_e32 v22, 0
	v_mov_b32_e32 v23, 0
	v_mov_b32_e32 v24, 0
	v_mov_b32_e32 v25, 0
	v_mov_b32_e32 v26, 0
	v_mov_b32_e32 v27, 0
	v_mov_b32_e32 v28, 0
	v_mov_b32_e32 v29, 0
	v_mov_b32_e32 v30, 0
	v_mov_b32_e32 v31, 0
	v_mov_b32_e32 v32, 0
	v_mov_b32_e32 v33, 0
	v_mov_b32_e32 v34, 0
	v_mov_b32_e32 v35, 0
	v_mov_b32_e32 v36, 0
	v_mov_b32_e32 v37, 0
	v_mov_b32_e32 v38, 0
	v_mov_b32_e32 v39, 0
	v_mov_b32_e32 v40, 0
	v_mov_b32_e32 v41, 0
	v_mov_b32_e32 v42, 0
	v_mov_b32_e32 v43, 0
	v_mov_b32_e32 v44, 0
	v_mov_b32_e32 v45, 0
	v_mov_b32_e32 v46, 0
	v_mov_b32_e32 v47, 0
	v_mov_b32_e32 v48, 0
	v_mov_b32_e32 v49, 0
	v_mov_b32_e32 v50, 0
	v_mov_b32_e32 v51, 0
	v_mov_b32_e32 v52, 0
	v_mov_b32_e32 v53, 0
	v_mov_b32_e32 v54, 0
	v_mov_b32_e32 v55, 0
	v_mov_b32_e32 v56, 0
	v_mov_b32_e32 v57, 0
	v_mov_b32_e32 v58, 0
	v_mov_b32_e32 v59, 0
	v_mov_b32_e32 v60, 0
	v_mov_b32_e32 v61, 0
	v_mov_b32_e32 v62, 0
	v_mov_b32_e32 v63, 0
.Lzacc5b:
	s_waitcnt vmcnt(8)
	s_waitcnt lgkmcnt(0)
	s_barrier
	s_setprio 1
	s_waitcnt lgkmcnt(0)
	v_mfma_f32_16x16x32_bf16 v[60:63], v[112:115], v[160:163], v[60:63]
	v_mfma_f32_16x16x32_bf16 v[56:59], v[136:139], v[160:163], v[56:59]
	v_mfma_f32_16x16x32_bf16 v[44:47], v[112:115], v[168:171], v[44:47]
	v_mfma_f32_16x16x32_bf16 v[40:43], v[136:139], v[168:171], v[40:43]
	v_mfma_f32_16x16x32_bf16 v[28:31], v[112:115], v[176:179], v[28:31]
	v_mfma_f32_16x16x32_bf16 v[24:27], v[136:139], v[176:179], v[24:27]
	v_mfma_f32_16x16x32_bf16 v[12:15], v[112:115], v[200:203], v[12:15]
	v_mfma_f32_16x16x32_bf16 v[8:11], v[136:139], v[200:203], v[8:11]
	v_mfma_f32_16x16x32_bf16 v[60:63], v[124:127], v[164:167], v[60:63]
	v_mfma_f32_16x16x32_bf16 v[56:59], v[140:143], v[164:167], v[56:59]
	v_mfma_f32_16x16x32_bf16 v[44:47], v[124:127], v[172:175], v[44:47]
	v_mfma_f32_16x16x32_bf16 v[40:43], v[140:143], v[172:175], v[40:43]
	v_mfma_f32_16x16x32_bf16 v[28:31], v[124:127], v[180:183], v[28:31]
	v_mfma_f32_16x16x32_bf16 v[24:27], v[140:143], v[180:183], v[24:27]
	v_mfma_f32_16x16x32_bf16 v[12:15], v[124:127], v[204:207], v[12:15]
	v_mfma_f32_16x16x32_bf16 v[8:11], v[140:143], v[204:207], v[8:11]
	s_setprio 0
	s_setprio 1
	v_mfma_f32_16x16x32_bf16 v[52:55], v[144:147], v[160:163], v[52:55]
	v_mfma_f32_16x16x32_bf16 v[48:51], v[152:155], v[160:163], v[48:51]
	v_mfma_f32_16x16x32_bf16 v[36:39], v[144:147], v[168:171], v[36:39]
	v_mfma_f32_16x16x32_bf16 v[32:35], v[152:155], v[168:171], v[32:35]
	v_mfma_f32_16x16x32_bf16 v[20:23], v[144:147], v[176:179], v[20:23]
	v_mfma_f32_16x16x32_bf16 v[16:19], v[152:155], v[176:179], v[16:19]
	v_mfma_f32_16x16x32_bf16 v[4:7], v[144:147], v[200:203], v[4:7]
	v_mfma_f32_16x16x32_bf16 v[0:3], v[152:155], v[200:203], v[0:3]
	v_mfma_f32_16x16x32_bf16 v[52:55], v[148:151], v[164:167], v[52:55]
	v_mfma_f32_16x16x32_bf16 v[48:51], v[156:159], v[164:167], v[48:51]
	v_mfma_f32_16x16x32_bf16 v[36:39], v[148:151], v[172:175], v[36:39]
	v_mfma_f32_16x16x32_bf16 v[32:35], v[156:159], v[172:175], v[32:35]
	v_mfma_f32_16x16x32_bf16 v[20:23], v[148:151], v[180:183], v[20:23]
	v_mfma_f32_16x16x32_bf16 v[16:19], v[156:159], v[180:183], v[16:19]
	v_mfma_f32_16x16x32_bf16 v[4:7], v[148:151], v[204:207], v[4:7]
	v_mfma_f32_16x16x32_bf16 v[0:3], v[156:159], v[204:207], v[0:3]
	s_setprio 0
	s_barrier
	s_add_i32 s46, 0, 0x18000
	s_add_i32 s47, 0, 0x1c000
	v_add_u32_e32 v140, s46, v220
	v_add_u32_e32 v156, s47, v220
	ds_read_b128 v[112:115], v140
	ds_read_b128 v[124:127], v140 offset:1024
	ds_read_b128 v[136:139], v140 offset:2048
	ds_read_b128 v[140:143], v140 offset:3072
	ds_read_b128 v[144:147], v156
	ds_read_b128 v[148:151], v156 offset:1024
	ds_read_b128 v[152:155], v156 offset:2048
	ds_read_b128 v[156:159], v156 offset:3072
	s_add_u32 s64, s64, 0x40000
	s_addc_u32 s65, s65, 0
	s_mov_b32 m0, s72
	v_lshl_add_u64 v[228:229], s[64:65], 0, v[184:185]
	ds_read_b128 v[160:163], v225 offset:32768
	ds_read_b128 v[164:167], v225 offset:33792
	ds_read_b128 v[168:171], v225 offset:34816
	ds_read_b128 v[172:175], v225 offset:35840
	ds_read_b128 v[176:179], v225 offset:36864
	ds_read_b128 v[180:183], v225 offset:37888
	ds_read_b128 v[200:203], v225 offset:38912
	ds_read_b128 v[204:207], v225 offset:39936
	global_load_lds_dwordx4 v[228:229], off
	v_lshl_add_u64 v[228:229], s[64:65], 0, v[188:189]
	s_mov_b32 m0, s73
	s_nop 0
	global_load_lds_dwordx4 v[228:229], off
	s_waitcnt vmcnt(8)
	s_waitcnt lgkmcnt(0)
	s_barrier
	s_setprio 1
	s_waitcnt lgkmcnt(0)
	v_mfma_f32_16x16x32_bf16 v[132:135], v[112:115], v[160:163], v[132:135]
	v_mfma_f32_16x16x32_bf16 v[128:131], v[136:139], v[160:163], v[128:131]
	v_mfma_f32_16x16x32_bf16 v[108:111], v[112:115], v[168:171], v[108:111]
	v_mfma_f32_16x16x32_bf16 v[104:107], v[136:139], v[168:171], v[104:107]
	v_mfma_f32_16x16x32_bf16 v[92:95], v[112:115], v[176:179], v[92:95]
	v_mfma_f32_16x16x32_bf16 v[88:91], v[136:139], v[176:179], v[88:91]
	v_mfma_f32_16x16x32_bf16 v[76:79], v[112:115], v[200:203], v[76:79]
	v_mfma_f32_16x16x32_bf16 v[72:75], v[136:139], v[200:203], v[72:75]
	v_mfma_f32_16x16x32_bf16 v[132:135], v[124:127], v[164:167], v[132:135]
	v_mfma_f32_16x16x32_bf16 v[128:131], v[140:143], v[164:167], v[128:131]
	v_mfma_f32_16x16x32_bf16 v[108:111], v[124:127], v[172:175], v[108:111]
	v_mfma_f32_16x16x32_bf16 v[104:107], v[140:143], v[172:175], v[104:107]
	v_mfma_f32_16x16x32_bf16 v[92:95], v[124:127], v[180:183], v[92:95]
	v_mfma_f32_16x16x32_bf16 v[88:91], v[140:143], v[180:183], v[88:91]
	v_mfma_f32_16x16x32_bf16 v[76:79], v[124:127], v[204:207], v[76:79]
	v_mfma_f32_16x16x32_bf16 v[72:75], v[140:143], v[204:207], v[72:75]
	s_setprio 0
	s_setprio 1
	v_mfma_f32_16x16x32_bf16 v[120:123], v[144:147], v[160:163], v[120:123]
	v_mfma_f32_16x16x32_bf16 v[116:119], v[152:155], v[160:163], v[116:119]
	v_mfma_f32_16x16x32_bf16 v[100:103], v[144:147], v[168:171], v[100:103]
	v_mfma_f32_16x16x32_bf16 v[96:99], v[152:155], v[168:171], v[96:99]
	v_mfma_f32_16x16x32_bf16 v[84:87], v[144:147], v[176:179], v[84:87]
	v_mfma_f32_16x16x32_bf16 v[80:83], v[152:155], v[176:179], v[80:83]
	v_mfma_f32_16x16x32_bf16 v[68:71], v[144:147], v[200:203], v[68:71]
	v_mfma_f32_16x16x32_bf16 v[64:67], v[152:155], v[200:203], v[64:67]
	v_mfma_f32_16x16x32_bf16 v[120:123], v[148:151], v[164:167], v[120:123]
	v_mfma_f32_16x16x32_bf16 v[116:119], v[156:159], v[164:167], v[116:119]
	v_mfma_f32_16x16x32_bf16 v[100:103], v[148:151], v[172:175], v[100:103]
	v_mfma_f32_16x16x32_bf16 v[96:99], v[156:159], v[172:175], v[96:99]
	v_mfma_f32_16x16x32_bf16 v[84:87], v[148:151], v[180:183], v[84:87]
	v_mfma_f32_16x16x32_bf16 v[80:83], v[156:159], v[180:183], v[80:83]
	v_mfma_f32_16x16x32_bf16 v[68:71], v[148:151], v[204:207], v[68:71]
	v_mfma_f32_16x16x32_bf16 v[64:67], v[156:159], v[204:207], v[64:67]
	s_setprio 0
	s_barrier
	s_add_i32 s46, s46, s69
	v_lshl_add_u64 v[208:209], v[208:209], 0, s[22:23]
	s_mov_b32 m0, s46
	ds_read_b128 v[160:163], v225 offset:49152
	ds_read_b128 v[164:167], v225 offset:50176
	ds_read_b128 v[168:171], v225 offset:51200
	ds_read_b128 v[172:175], v225 offset:52224
	ds_read_b128 v[176:179], v225 offset:53248
	ds_read_b128 v[180:183], v225 offset:54272
	ds_read_b128 v[200:203], v225 offset:55296
	ds_read_b128 v[204:207], v225 offset:56320
	global_load_lds_dwordx4 v[208:209], off
	s_add_i32 m0, s46, 0x2000
	s_add_u32 s62, s62, 0x40080
	v_lshl_add_u64 v[208:209], v[210:211], 0, s[22:23]
	s_addc_u32 s63, s63, 0
	s_add_i32 s46, s47, s69
	global_load_lds_dwordx4 v[208:209], off
	v_lshl_add_u64 v[208:209], s[62:63], 0, v[186:187]
	s_mov_b32 m0, s46
	s_nop 0
	global_load_lds_dwordx4 v[208:209], off
	v_lshl_add_u64 v[208:209], s[62:63], 0, v[190:191]
	s_add_i32 m0, s46, 0x2000
	s_nop 0
	global_load_lds_dwordx4 v[208:209], off
	v_lshl_add_u64 v[208:209], v[212:213], 0, s[22:23]
	s_mov_b32 m0, s51
	s_nop 0
	global_load_lds_dwordx4 v[208:209], off
	v_lshl_add_u64 v[208:209], v[214:215], 0, s[22:23]
	s_mov_b32 m0, s75
	s_nop 0
	global_load_lds_dwordx4 v[208:209], off
	s_waitcnt vmcnt(8)
	s_waitcnt lgkmcnt(0)
	s_barrier
	s_setprio 1
	s_waitcnt lgkmcnt(0)
	v_mfma_f32_16x16x32_bf16 v[60:63], v[112:115], v[160:163], v[60:63]
	v_mfma_f32_16x16x32_bf16 v[56:59], v[136:139], v[160:163], v[56:59]
	v_mfma_f32_16x16x32_bf16 v[44:47], v[112:115], v[168:171], v[44:47]
	v_mfma_f32_16x16x32_bf16 v[40:43], v[136:139], v[168:171], v[40:43]
	v_mfma_f32_16x16x32_bf16 v[28:31], v[112:115], v[176:179], v[28:31]
	v_mfma_f32_16x16x32_bf16 v[24:27], v[136:139], v[176:179], v[24:27]
	v_mfma_f32_16x16x32_bf16 v[12:15], v[112:115], v[200:203], v[12:15]
	v_mfma_f32_16x16x32_bf16 v[8:11], v[136:139], v[200:203], v[8:11]
	v_mfma_f32_16x16x32_bf16 v[60:63], v[124:127], v[164:167], v[60:63]
	v_mfma_f32_16x16x32_bf16 v[56:59], v[140:143], v[164:167], v[56:59]
	v_mfma_f32_16x16x32_bf16 v[44:47], v[124:127], v[172:175], v[44:47]
	v_mfma_f32_16x16x32_bf16 v[40:43], v[140:143], v[172:175], v[40:43]
	v_mfma_f32_16x16x32_bf16 v[28:31], v[124:127], v[180:183], v[28:31]
	v_mfma_f32_16x16x32_bf16 v[24:27], v[140:143], v[180:183], v[24:27]
	v_mfma_f32_16x16x32_bf16 v[12:15], v[124:127], v[204:207], v[12:15]
	v_mfma_f32_16x16x32_bf16 v[8:11], v[140:143], v[204:207], v[8:11]
	s_setprio 0
	s_setprio 1
	v_mfma_f32_16x16x32_bf16 v[52:55], v[144:147], v[160:163], v[52:55]
	v_mfma_f32_16x16x32_bf16 v[48:51], v[152:155], v[160:163], v[48:51]
	v_mfma_f32_16x16x32_bf16 v[36:39], v[144:147], v[168:171], v[36:39]
	v_mfma_f32_16x16x32_bf16 v[32:35], v[152:155], v[168:171], v[32:35]
	v_mfma_f32_16x16x32_bf16 v[20:23], v[144:147], v[176:179], v[20:23]
	v_mfma_f32_16x16x32_bf16 v[16:19], v[152:155], v[176:179], v[16:19]
	v_mfma_f32_16x16x32_bf16 v[4:7], v[144:147], v[200:203], v[4:7]
	v_mfma_f32_16x16x32_bf16 v[0:3], v[152:155], v[200:203], v[0:3]
	v_mfma_f32_16x16x32_bf16 v[52:55], v[148:151], v[164:167], v[52:55]
	v_mfma_f32_16x16x32_bf16 v[48:51], v[156:159], v[164:167], v[48:51]
	v_mfma_f32_16x16x32_bf16 v[36:39], v[148:151], v[172:175], v[36:39]
	v_mfma_f32_16x16x32_bf16 v[32:35], v[156:159], v[172:175], v[32:35]
	v_mfma_f32_16x16x32_bf16 v[20:23], v[148:151], v[180:183], v[20:23]
	v_mfma_f32_16x16x32_bf16 v[16:19], v[156:159], v[180:183], v[16:19]
	v_mfma_f32_16x16x32_bf16 v[4:7], v[148:151], v[204:207], v[4:7]
	v_mfma_f32_16x16x32_bf16 v[0:3], v[156:159], v[204:207], v[0:3]
	s_setprio 0
	s_barrier
	s_add_i32 s59, s59, 2
	s_add_u32 s60, s60, 0x100
	s_addc_u32 s61, s61, 0
	s_add_u32 s54, s54, 0x100
	s_addc_u32 s55, s55, 0
	s_cmp_gt_u32 s59, 13
	s_cbranch_scc0 .LBB0_904
	s_and_b64 vcc, exec, s[24:25]
	s_cbranch_vccz .LBB0_907
	s_barrier

.LBB0_990:
	s_ashr_i32 s55, s54, 31
	s_lshl_b64 s[4:5], s[54:55], 19
	s_add_u32 s56, s64, s4
	s_addc_u32 s57, s65, s5
	s_and_b64 s[4:5], s[6:7], exec
	s_cselect_b32 s4, s57, s61
	s_cselect_b32 s5, s56, s60
	s_ashr_i32 s39, s38, 31
	s_lshl_b64 s[8:9], s[38:39], 19
	s_add_u32 s58, s62, s8
	s_addc_u32 s59, s63, s9
	s_and_b64 s[8:9], s[6:7], exec
	s_cselect_b32 s12, s59, s15
	s_cselect_b32 s39, s58, s14
	s_add_u32 s8, s60, 0x40080
	s_addc_u32 s9, s61, 0
	s_add_u32 s51, s14, 0x100
	s_addc_u32 s55, s15, 0
	s_mov_b32 s60, -2
	s_waitcnt vmcnt(0)
.LBB0_991:
	ds_read_b128 v[128:131], v204
	ds_read_b128 v[132:135], v204 offset:1024
	ds_read_b128 v[136:139], v204 offset:2048
	ds_read_b128 v[140:143], v204 offset:3072
	ds_read_b128 v[144:147], v205
	ds_read_b128 v[148:151], v205 offset:1024
	ds_read_b128 v[152:155], v205 offset:2048
	ds_read_b128 v[156:159], v205 offset:3072
	s_add_u32 s10, s8, 0xfffc0080
	s_addc_u32 s11, s9, -1
	s_cmp_eq_u32 s60, 12
	s_cselect_b32 s15, s4, s11
	s_cselect_b32 s14, s5, s10
	s_cselect_b32 s11, s12, s55
	s_cselect_b32 s10, s39, s51
	v_lshl_add_u64 v[214:215], s[8:9], 0, v[178:179]
	s_add_i32 m0, s53, 0xc000
	ds_read_b128 v[160:163], v206
	ds_read_b128 v[164:167], v206 offset:1024
	ds_read_b128 v[186:189], v206 offset:2048
	ds_read_b128 v[190:193], v206 offset:3072
	ds_read_b128 v[194:197], v206 offset:4096
	ds_read_b128 v[198:201], v206 offset:5120
	ds_read_b128 v[210:213], v206 offset:6144
	ds_read_b128 v[218:221], v206 offset:7168
	global_load_lds_dwordx4 v[214:215], off
	v_lshl_add_u64 v[214:215], s[8:9], 0, v[180:181]
	s_add_i32 m0, s53, 0xe000
	s_nop 0
	global_load_lds_dwordx4 v[214:215], off
	s_cmp_lg_u32 s60, -2
	s_cbranch_scc1 .Lzacc6a
	v_mov_b32_e32 v24, 0
	v_mov_b32_e32 v25, 0
	v_mov_b32_e32 v26, 0
	v_mov_b32_e32 v27, 0
	v_mov_b32_e32 v36, 0
	v_mov_b32_e32 v37, 0
	v_mov_b32_e32 v38, 0
	v_mov_b32_e32 v39, 0
	v_mov_b32_e32 v52, 0
	v_mov_b32_e32 v53, 0
	v_mov_b32_e32 v54, 0
	v_mov_b32_e32 v55, 0
	v_mov_b32_e32 v64, 0
	v_mov_b32_e32 v65, 0
	v_mov_b32_e32 v66, 0
	v_mov_b32_e32 v67, 0
	v_mov_b32_e32 v80, 0
	v_mov_b32_e32 v81, 0
	v_mov_b32_e32 v82, 0
	v_mov_b32_e32 v83, 0
	v_mov_b32_e32 v84, 0
	v_mov_b32_e32 v85, 0
	v_mov_b32_e32 v86, 0
	v_mov_b32_e32 v87, 0
	v_mov_b32_e32 v88, 0
	v_mov_b32_e32 v89, 0
	v_mov_b32_e32 v90, 0
	v_mov_b32_e32 v91, 0
	v_mov_b32_e32 v92, 0
	v_mov_b32_e32 v93, 0
	v_mov_b32_e32 v94, 0
	v_mov_b32_e32 v95, 0
	v_mov_b32_e32 v96, 0
	v_mov_b32_e32 v97, 0
	v_mov_b32_e32 v98, 0
	v_mov_b32_e32 v99, 0
	v_mov_b32_e32 v100, 0
	v_mov_b32_e32 v101, 0
	v_mov_b32_e32 v102, 0
	v_mov_b32_e32 v103, 0
	v_mov_b32_e32 v104, 0
	v_mov_b32_e32 v105, 0
	v_mov_b32_e32 v106, 0
	v_mov_b32_e32 v107, 0
	v_mov_b32_e32 v108, 0
	v_mov_b32_e32 v109, 0
	v_mov_b32_e32 v110, 0
	v_mov_b32_e32 v111, 0
	v_mov_b32_e32 v112, 0
	v_mov_b32_e32 v113, 0
	v_mov_b32_e32 v114, 0
	v_mov_b32_e32 v115, 0
	v_mov_b32_e32 v116, 0
	v_mov_b32_e32 v117, 0
	v_mov_b32_e32 v118, 0
	v_mov_b32_e32 v119, 0
	v_mov_b32_e32 v120, 0
	v_mov_b32_e32 v121, 0
	v_mov_b32_e32 v122, 0
	v_mov_b32_e32 v123, 0
	v_mov_b32_e32 v124, 0
	v_mov_b32_e32 v125, 0
	v_mov_b32_e32 v126, 0
	v_mov_b32_e32 v127, 0
.Lzacc6a:
	s_waitcnt vmcnt(8)
	s_waitcnt lgkmcnt(0)
	s_barrier
	s_setprio 1
	s_waitcnt lgkmcnt(0)
	v_mfma_f32_16x16x32_bf16 v[124:127], v[128:131], v[160:163], v[124:127]
	v_mfma_f32_16x16x32_bf16 v[120:123], v[136:139], v[160:163], v[120:123]
	v_mfma_f32_16x16x32_bf16 v[116:119], v[128:131], v[186:189], v[116:119]
	v_mfma_f32_16x16x32_bf16 v[112:115], v[136:139], v[186:189], v[112:115]
	v_mfma_f32_16x16x32_bf16 v[108:111], v[128:131], v[194:197], v[108:111]
	v_mfma_f32_16x16x32_bf16 v[104:107], v[136:139], v[194:197], v[104:107]
	v_mfma_f32_16x16x32_bf16 v[92:95], v[128:131], v[210:213], v[92:95]
	v_mfma_f32_16x16x32_bf16 v[84:87], v[136:139], v[210:213], v[84:87]
	v_mfma_f32_16x16x32_bf16 v[124:127], v[132:135], v[164:167], v[124:127]
	v_mfma_f32_16x16x32_bf16 v[120:123], v[140:143], v[164:167], v[120:123]
	v_mfma_f32_16x16x32_bf16 v[116:119], v[132:135], v[190:193], v[116:119]
	v_mfma_f32_16x16x32_bf16 v[112:115], v[140:143], v[190:193], v[112:115]
	v_mfma_f32_16x16x32_bf16 v[108:111], v[132:135], v[198:201], v[108:111]
	v_mfma_f32_16x16x32_bf16 v[104:107], v[140:143], v[198:201], v[104:107]
	v_mfma_f32_16x16x32_bf16 v[92:95], v[132:135], v[218:221], v[92:95]
	v_mfma_f32_16x16x32_bf16 v[84:87], v[140:143], v[218:221], v[84:87]
	s_setprio 0
	s_setprio 1
	v_mfma_f32_16x16x32_bf16 v[88:91], v[144:147], v[160:163], v[88:91]
	v_mfma_f32_16x16x32_bf16 v[24:27], v[152:155], v[160:163], v[24:27]
	v_mfma_f32_16x16x32_bf16 v[100:103], v[144:147], v[186:189], v[100:103]
	v_mfma_f32_16x16x32_bf16 v[36:39], v[152:155], v[186:189], v[36:39]
	v_mfma_f32_16x16x32_bf16 v[96:99], v[144:147], v[194:197], v[96:99]
	v_mfma_f32_16x16x32_bf16 v[52:55], v[152:155], v[194:197], v[52:55]
	v_mfma_f32_16x16x32_bf16 v[80:83], v[144:147], v[210:213], v[80:83]
	v_mfma_f32_16x16x32_bf16 v[64:67], v[152:155], v[210:213], v[64:67]
	v_mfma_f32_16x16x32_bf16 v[88:91], v[148:151], v[164:167], v[88:91]
	v_mfma_f32_16x16x32_bf16 v[24:27], v[156:159], v[164:167], v[24:27]
	v_mfma_f32_16x16x32_bf16 v[100:103], v[148:151], v[190:193], v[100:103]
	v_mfma_f32_16x16x32_bf16 v[36:39], v[156:159], v[190:193], v[36:39]
	v_mfma_f32_16x16x32_bf16 v[96:99], v[148:151], v[198:201], v[96:99]
	v_mfma_f32_16x16x32_bf16 v[52:55], v[156:159], v[198:201], v[52:55]
	v_mfma_f32_16x16x32_bf16 v[80:83], v[148:151], v[218:221], v[80:83]
	v_mfma_f32_16x16x32_bf16 v[64:67], v[156:159], v[218:221], v[64:67]
	s_setprio 0
	s_barrier
	s_add_i32 s46, s82, s66
	v_lshl_add_u64 v[214:215], s[10:11], 0, v[172:173]
	s_mov_b32 m0, s46
	ds_read_b128 v[160:163], v206 offset:16384
	ds_read_b128 v[164:167], v206 offset:17408
	ds_read_b128 v[186:189], v206 offset:18432
	ds_read_b128 v[190:193], v206 offset:19456
	ds_read_b128 v[194:197], v206 offset:20480
	ds_read_b128 v[198:201], v206 offset:21504
	ds_read_b128 v[210:213], v206 offset:22528
	ds_read_b128 v[218:221], v206 offset:23552
	global_load_lds_dwordx4 v[214:215], off
	s_add_i32 m0, s46, 0x2000
	s_add_u32 s92, s10, 0x40000
	v_lshl_add_u64 v[222:223], s[10:11], 0, v[168:169]
	s_addc_u32 s93, s11, 0
	s_add_i32 s46, s83, s66
	global_load_lds_dwordx4 v[222:223], off
	v_lshl_add_u64 v[224:225], s[92:93], 0, v[172:173]
	s_mov_b32 m0, s46
	v_lshl_add_u64 v[226:227], s[14:15], 0, v[170:171]
	global_load_lds_dwordx4 v[224:225], off
	v_lshl_add_u64 v[224:225], s[92:93], 0, v[168:169]
	s_add_i32 m0, s46, 0x2000
	s_nop 0
	global_load_lds_dwordx4 v[224:225], off
	v_lshl_add_u64 v[224:225], s[14:15], 0, v[174:175]
	s_mov_b32 m0, s53
	s_nop 0
	global_load_lds_dwordx4 v[224:225], off
	s_mov_b32 m0, s67
	s_nop 0
	global_load_lds_dwordx4 v[226:227], off
	s_cmp_lg_u32 s60, -2
	s_cbranch_scc1 .Lzacc6b
	v_mov_b32_e32 v0, 0
	v_mov_b32_e32 v1, 0
	v_mov_b32_e32 v2, 0
	v_mov_b32_e32 v3, 0
	v_mov_b32_e32 v4, 0
	v_mov_b32_e32 v5, 0
	v_mov_b32_e32 v6, 0
	v_mov_b32_e32 v7, 0
	v_mov_b32_e32 v8, 0
	v_mov_b32_e32 v9, 0
	v_mov_b32_e32 v10, 0
	v_mov_b32_e32 v11, 0
	v_mov_b32_e32 v12, 0
	v_mov_b32_e32 v13, 0
	v_mov_b32_e32 v14, 0
	v_mov_b32_e32 v15, 0
	v_mov_b32_e32 v16, 0
	v_mov_b32_e32 v17, 0
	v_mov_b32_e32 v18, 0
	v_mov_b32_e32 v19, 0
	v_mov_b32_e32 v20, 0
	v_mov_b32_e32 v21, 0
	v_mov_b32_e32 v22, 0
	v_mov_b32_e32 v23, 0
	v_mov_b32_e32 v28, 0
	v_mov_b32_e32 v29, 0
	v_mov_b32_e32 v30, 0
	v_mov_b32_e32 v31, 0
	v_mov_b32_e32 v32, 0
	v_mov_b32_e32 v33, 0
	v_mov_b32_e32 v34, 0
	v_mov_b32_e32 v35, 0
	v_mov_b32_e32 v40, 0
	v_mov_b32_e32 v41, 0
	v_mov_b32_e32 v42, 0
	v_mov_b32_e32 v43, 0
	v_mov_b32_e32 v44, 0
	v_mov_b32_e32 v45, 0
	v_mov_b32_e32 v46, 0
	v_mov_b32_e32 v47, 0
	v_mov_b32_e32 v48, 0
	v_mov_b32_e32 v49, 0
	v_mov_b32_e32 v50, 0
	v_mov_b32_e32 v51, 0
	v_mov_b32_e32 v56, 0
	v_mov_b32_e32 v57, 0
	v_mov_b32_e32 v58, 0
	v_mov_b32_e32 v59, 0
	v_mov_b32_e32 v60, 0
	v_mov_b32_e32 v61, 0
	v_mov_b32_e32 v62, 0
	v_mov_b32_e32 v63, 0
	v_mov_b32_e32 v68, 0
	v_mov_b32_e32 v69, 0
	v_mov_b32_e32 v70, 0
	v_mov_b32_e32 v71, 0
	v_mov_b32_e32 v72, 0
	v_mov_b32_e32 v73, 0
	v_mov_b32_e32 v74, 0
	v_mov_b32_e32 v75, 0
	v_mov_b32_e32 v76, 0
	v_mov_b32_e32 v77, 0
	v_mov_b32_e32 v78, 0
	v_mov_b32_e32 v79, 0
.Lzacc6b:
	s_waitcnt vmcnt(8)
	s_waitcnt lgkmcnt(0)
	s_barrier
	s_setprio 1
	s_waitcnt lgkmcnt(0)
	v_mfma_f32_16x16x32_bf16 v[76:79], v[128:131], v[160:163], v[76:79]
	v_mfma_f32_16x16x32_bf16 v[72:75], v[136:139], v[160:163], v[72:75]
	v_mfma_f32_16x16x32_bf16 v[60:63], v[128:131], v[186:189], v[60:63]
	v_mfma_f32_16x16x32_bf16 v[56:59], v[136:139], v[186:189], v[56:59]
	v_mfma_f32_16x16x32_bf16 v[44:47], v[128:131], v[194:197], v[44:47]
	v_mfma_f32_16x16x32_bf16 v[40:43], v[136:139], v[194:197], v[40:43]
	v_mfma_f32_16x16x32_bf16 v[20:23], v[128:131], v[210:213], v[20:23]
	v_mfma_f32_16x16x32_bf16 v[8:11], v[136:139], v[210:213], v[8:11]
	v_mfma_f32_16x16x32_bf16 v[76:79], v[132:135], v[164:167], v[76:79]
	v_mfma_f32_16x16x32_bf16 v[72:75], v[140:143], v[164:167], v[72:75]
	v_mfma_f32_16x16x32_bf16 v[60:63], v[132:135], v[190:193], v[60:63]
	v_mfma_f32_16x16x32_bf16 v[56:59], v[140:143], v[190:193], v[56:59]
	v_mfma_f32_16x16x32_bf16 v[44:47], v[132:135], v[198:201], v[44:47]
	v_mfma_f32_16x16x32_bf16 v[40:43], v[140:143], v[198:201], v[40:43]
	v_mfma_f32_16x16x32_bf16 v[20:23], v[132:135], v[218:221], v[20:23]
	v_mfma_f32_16x16x32_bf16 v[8:11], v[140:143], v[218:221], v[8:11]
	s_setprio 0
	s_setprio 1
	v_mfma_f32_16x16x32_bf16 v[68:71], v[144:147], v[160:163], v[68:71]
	v_mfma_f32_16x16x32_bf16 v[12:15], v[152:155], v[160:163], v[12:15]
	v_mfma_f32_16x16x32_bf16 v[48:51], v[144:147], v[186:189], v[48:51]
	v_mfma_f32_16x16x32_bf16 v[28:31], v[152:155], v[186:189], v[28:31]
	v_mfma_f32_16x16x32_bf16 v[32:35], v[144:147], v[194:197], v[32:35]
	v_mfma_f32_16x16x32_bf16 v[16:19], v[152:155], v[194:197], v[16:19]
	v_mfma_f32_16x16x32_bf16 v[4:7], v[144:147], v[210:213], v[4:7]
	v_mfma_f32_16x16x32_bf16 v[0:3], v[152:155], v[210:213], v[0:3]
	v_mfma_f32_16x16x32_bf16 v[68:71], v[148:151], v[164:167], v[68:71]
	v_mfma_f32_16x16x32_bf16 v[12:15], v[156:159], v[164:167], v[12:15]
	v_mfma_f32_16x16x32_bf16 v[48:51], v[148:151], v[190:193], v[48:51]
	v_mfma_f32_16x16x32_bf16 v[28:31], v[156:159], v[190:193], v[28:31]
	v_mfma_f32_16x16x32_bf16 v[32:35], v[148:151], v[198:201], v[32:35]
	v_mfma_f32_16x16x32_bf16 v[16:19], v[156:159], v[198:201], v[16:19]
	v_mfma_f32_16x16x32_bf16 v[4:7], v[148:151], v[218:221], v[4:7]
	v_mfma_f32_16x16x32_bf16 v[0:3], v[156:159], v[218:221], v[0:3]
	s_setprio 0
	s_barrier
	s_add_i32 s46, 0, 0x18000
	s_add_i32 s47, 0, 0x1c000
	v_add_u32_e32 v140, s46, v203
	v_add_u32_e32 v156, s47, v203
	ds_read_b128 v[128:131], v140
	ds_read_b128 v[132:135], v140 offset:1024
	ds_read_b128 v[136:139], v140 offset:2048
	ds_read_b128 v[140:143], v140 offset:3072
	ds_read_b128 v[144:147], v156
	ds_read_b128 v[148:151], v156 offset:1024
	ds_read_b128 v[152:155], v156 offset:2048
	ds_read_b128 v[156:159], v156 offset:3072
	s_add_u32 s14, s14, 0x40000
	s_addc_u32 s15, s15, 0
	s_mov_b32 m0, s68
	v_lshl_add_u64 v[228:229], s[14:15], 0, v[174:175]
	ds_read_b128 v[160:163], v206 offset:32768
	ds_read_b128 v[164:167], v206 offset:33792
	ds_read_b128 v[186:189], v206 offset:34816
	ds_read_b128 v[190:193], v206 offset:35840
	ds_read_b128 v[194:197], v206 offset:36864
	ds_read_b128 v[198:201], v206 offset:37888
	ds_read_b128 v[210:213], v206 offset:38912
	ds_read_b128 v[218:221], v206 offset:39936
	global_load_lds_dwordx4 v[228:229], off
	v_lshl_add_u64 v[228:229], s[14:15], 0, v[170:171]
	s_mov_b32 m0, s69
	s_nop 0
	global_load_lds_dwordx4 v[228:229], off
	s_waitcnt vmcnt(8)
	s_waitcnt lgkmcnt(0)
	s_barrier
	s_setprio 1
	s_waitcnt lgkmcnt(0)
	v_mfma_f32_16x16x32_bf16 v[124:127], v[128:131], v[160:163], v[124:127]
	v_mfma_f32_16x16x32_bf16 v[120:123], v[136:139], v[160:163], v[120:123]
	v_mfma_f32_16x16x32_bf16 v[116:119], v[128:131], v[186:189], v[116:119]
	v_mfma_f32_16x16x32_bf16 v[112:115], v[136:139], v[186:189], v[112:115]
	v_mfma_f32_16x16x32_bf16 v[108:111], v[128:131], v[194:197], v[108:111]
	v_mfma_f32_16x16x32_bf16 v[104:107], v[136:139], v[194:197], v[104:107]
	v_mfma_f32_16x16x32_bf16 v[92:95], v[128:131], v[210:213], v[92:95]
	v_mfma_f32_16x16x32_bf16 v[84:87], v[136:139], v[210:213], v[84:87]
	v_mfma_f32_16x16x32_bf16 v[124:127], v[132:135], v[164:167], v[124:127]
	v_mfma_f32_16x16x32_bf16 v[120:123], v[140:143], v[164:167], v[120:123]
	v_mfma_f32_16x16x32_bf16 v[116:119], v[132:135], v[190:193], v[116:119]
	v_mfma_f32_16x16x32_bf16 v[112:115], v[140:143], v[190:193], v[112:115]
	v_mfma_f32_16x16x32_bf16 v[108:111], v[132:135], v[198:201], v[108:111]
	v_mfma_f32_16x16x32_bf16 v[104:107], v[140:143], v[198:201], v[104:107]
	v_mfma_f32_16x16x32_bf16 v[92:95], v[132:135], v[218:221], v[92:95]
	v_mfma_f32_16x16x32_bf16 v[84:87], v[140:143], v[218:221], v[84:87]
	s_setprio 0
	s_setprio 1
	v_mfma_f32_16x16x32_bf16 v[88:91], v[144:147], v[160:163], v[88:91]
	v_mfma_f32_16x16x32_bf16 v[24:27], v[152:155], v[160:163], v[24:27]
	v_mfma_f32_16x16x32_bf16 v[100:103], v[144:147], v[186:189], v[100:103]
	v_mfma_f32_16x16x32_bf16 v[36:39], v[152:155], v[186:189], v[36:39]
	v_mfma_f32_16x16x32_bf16 v[96:99], v[144:147], v[194:197], v[96:99]
	v_mfma_f32_16x16x32_bf16 v[52:55], v[152:155], v[194:197], v[52:55]
	v_mfma_f32_16x16x32_bf16 v[80:83], v[144:147], v[210:213], v[80:83]
	v_mfma_f32_16x16x32_bf16 v[64:67], v[152:155], v[210:213], v[64:67]
	v_mfma_f32_16x16x32_bf16 v[88:91], v[148:151], v[164:167], v[88:91]
	v_mfma_f32_16x16x32_bf16 v[24:27], v[156:159], v[164:167], v[24:27]
	v_mfma_f32_16x16x32_bf16 v[100:103], v[148:151], v[190:193], v[100:103]
	v_mfma_f32_16x16x32_bf16 v[36:39], v[156:159], v[190:193], v[36:39]
	v_mfma_f32_16x16x32_bf16 v[96:99], v[148:151], v[198:201], v[96:99]
	v_mfma_f32_16x16x32_bf16 v[52:55], v[156:159], v[198:201], v[52:55]
	v_mfma_f32_16x16x32_bf16 v[80:83], v[148:151], v[218:221], v[80:83]
	v_mfma_f32_16x16x32_bf16 v[64:67], v[156:159], v[218:221], v[64:67]
	s_setprio 0
	s_barrier
	s_add_i32 s14, s46, s66
	v_lshl_add_u64 v[214:215], v[214:215], 0, s[26:27]
	s_mov_b32 m0, s14
	ds_read_b128 v[160:163], v206 offset:49152
	ds_read_b128 v[164:167], v206 offset:50176
	ds_read_b128 v[186:189], v206 offset:51200
	ds_read_b128 v[190:193], v206 offset:52224
	ds_read_b128 v[194:197], v206 offset:53248
	ds_read_b128 v[198:201], v206 offset:54272
	ds_read_b128 v[210:213], v206 offset:55296
	ds_read_b128 v[218:221], v206 offset:56320
	global_load_lds_dwordx4 v[214:215], off
	s_add_i32 m0, s14, 0x2000
	s_add_u32 s10, s10, 0x40080
	v_lshl_add_u64 v[214:215], v[222:223], 0, s[26:27]
	s_addc_u32 s11, s11, 0
	s_add_i32 s14, s47, s66
	global_load_lds_dwordx4 v[214:215], off
	v_lshl_add_u64 v[214:215], s[10:11], 0, v[172:173]
	s_mov_b32 m0, s14
	s_nop 0
	global_load_lds_dwordx4 v[214:215], off
	v_lshl_add_u64 v[214:215], s[10:11], 0, v[168:169]
	s_add_i32 m0, s14, 0x2000
	s_nop 0
	global_load_lds_dwordx4 v[214:215], off
	v_lshl_add_u64 v[214:215], v[224:225], 0, s[26:27]
	s_mov_b32 m0, s75
	s_nop 0
	global_load_lds_dwordx4 v[214:215], off
	v_lshl_add_u64 v[214:215], v[226:227], 0, s[26:27]
	s_mov_b32 m0, s76
	s_nop 0
	global_load_lds_dwordx4 v[214:215], off
	s_waitcnt vmcnt(8)
	s_waitcnt lgkmcnt(0)
	s_barrier
	s_setprio 1
	s_waitcnt lgkmcnt(0)
	v_mfma_f32_16x16x32_bf16 v[76:79], v[128:131], v[160:163], v[76:79]
	v_mfma_f32_16x16x32_bf16 v[72:75], v[136:139], v[160:163], v[72:75]
	v_mfma_f32_16x16x32_bf16 v[60:63], v[128:131], v[186:189], v[60:63]
	v_mfma_f32_16x16x32_bf16 v[56:59], v[136:139], v[186:189], v[56:59]
	v_mfma_f32_16x16x32_bf16 v[44:47], v[128:131], v[194:197], v[44:47]
	v_mfma_f32_16x16x32_bf16 v[40:43], v[136:139], v[194:197], v[40:43]
	v_mfma_f32_16x16x32_bf16 v[20:23], v[128:131], v[210:213], v[20:23]
	v_mfma_f32_16x16x32_bf16 v[8:11], v[136:139], v[210:213], v[8:11]
	v_mfma_f32_16x16x32_bf16 v[76:79], v[132:135], v[164:167], v[76:79]
	v_mfma_f32_16x16x32_bf16 v[72:75], v[140:143], v[164:167], v[72:75]
	v_mfma_f32_16x16x32_bf16 v[60:63], v[132:135], v[190:193], v[60:63]
	v_mfma_f32_16x16x32_bf16 v[56:59], v[140:143], v[190:193], v[56:59]
	v_mfma_f32_16x16x32_bf16 v[44:47], v[132:135], v[198:201], v[44:47]
	v_mfma_f32_16x16x32_bf16 v[40:43], v[140:143], v[198:201], v[40:43]
	v_mfma_f32_16x16x32_bf16 v[20:23], v[132:135], v[218:221], v[20:23]
	v_mfma_f32_16x16x32_bf16 v[8:11], v[140:143], v[218:221], v[8:11]
	s_setprio 0
	s_setprio 1
	v_mfma_f32_16x16x32_bf16 v[68:71], v[144:147], v[160:163], v[68:71]
	v_mfma_f32_16x16x32_bf16 v[12:15], v[152:155], v[160:163], v[12:15]
	v_mfma_f32_16x16x32_bf16 v[48:51], v[144:147], v[186:189], v[48:51]
	v_mfma_f32_16x16x32_bf16 v[28:31], v[152:155], v[186:189], v[28:31]
	v_mfma_f32_16x16x32_bf16 v[32:35], v[144:147], v[194:197], v[32:35]
	v_mfma_f32_16x16x32_bf16 v[16:19], v[152:155], v[194:197], v[16:19]
	v_mfma_f32_16x16x32_bf16 v[4:7], v[144:147], v[210:213], v[4:7]
	v_mfma_f32_16x16x32_bf16 v[0:3], v[152:155], v[210:213], v[0:3]
	v_mfma_f32_16x16x32_bf16 v[68:71], v[148:151], v[164:167], v[68:71]
	v_mfma_f32_16x16x32_bf16 v[12:15], v[156:159], v[164:167], v[12:15]
	v_mfma_f32_16x16x32_bf16 v[48:51], v[148:151], v[190:193], v[48:51]
	v_mfma_f32_16x16x32_bf16 v[28:31], v[156:159], v[190:193], v[28:31]
	v_mfma_f32_16x16x32_bf16 v[32:35], v[148:151], v[198:201], v[32:35]
	v_mfma_f32_16x16x32_bf16 v[16:19], v[156:159], v[198:201], v[16:19]
	v_mfma_f32_16x16x32_bf16 v[4:7], v[148:151], v[218:221], v[4:7]
	v_mfma_f32_16x16x32_bf16 v[0:3], v[156:159], v[218:221], v[0:3]
	s_setprio 0
	s_barrier
	s_add_i32 s60, s60, 2
	s_add_u32 s8, s8, 0x100
	s_addc_u32 s9, s9, 0
	s_add_u32 s51, s51, 0x100
	s_addc_u32 s55, s55, 0
	s_cmp_gt_u32 s60, 13
	s_cbranch_scc0 .LBB0_991
	s_and_b64 vcc, exec, s[30:31]
	s_cbranch_vccz .LBB0_994
	s_barrier

.LBB0_1150:
	s_add_u32 s69, s38, 0x100
	s_addc_u32 s70, s39, 0
	s_mov_b32 s71, -2
	s_waitcnt lgkmcnt(0)
	s_waitcnt vmcnt(0)
.LBB0_1151:
	ds_read_b128 v[112:115], v223
	ds_read_b128 v[124:127], v223 offset:1024
	ds_read_b128 v[136:139], v223 offset:2048
	ds_read_b128 v[140:143], v223 offset:3072
	ds_read_b128 v[144:147], v224
	ds_read_b128 v[148:151], v224 offset:1024
	ds_read_b128 v[152:155], v224 offset:2048
	ds_read_b128 v[156:159], v224 offset:3072
	s_add_u32 s38, s36, 0x100
	s_addc_u32 s39, s37, 0
	s_cmp_eq_u32 s71, 40
	s_cselect_b32 s49, s11, s39
	s_cselect_b32 s48, s10, s38
	s_cselect_b32 s47, s35, s70
	s_cselect_b32 s46, s34, s69
	v_lshl_add_u64 v[208:209], s[36:37], 0, v[192:193]
	s_add_i32 m0, s55, 0xc000
	ds_read_b128 v[160:163], v225
	ds_read_b128 v[164:167], v225 offset:1024
	ds_read_b128 v[168:171], v225 offset:2048
	ds_read_b128 v[172:175], v225 offset:3072
	ds_read_b128 v[176:179], v225 offset:4096
	ds_read_b128 v[180:183], v225 offset:5120
	ds_read_b128 v[200:203], v225 offset:6144
	ds_read_b128 v[204:207], v225 offset:7168
	global_load_lds_dwordx4 v[208:209], off
	v_lshl_add_u64 v[208:209], s[36:37], 0, v[194:195]
	s_add_i32 m0, s55, 0xe000
	s_nop 0
	global_load_lds_dwordx4 v[208:209], off
	s_cmp_lg_u32 s71, -2
	s_cbranch_scc1 .Lzacc7a
	v_mov_b32_e32 v64, 0
	v_mov_b32_e32 v65, 0
	v_mov_b32_e32 v66, 0
	v_mov_b32_e32 v67, 0
	v_mov_b32_e32 v68, 0
	v_mov_b32_e32 v69, 0
	v_mov_b32_e32 v70, 0
	v_mov_b32_e32 v71, 0
	v_mov_b32_e32 v72, 0
	v_mov_b32_e32 v73, 0
	v_mov_b32_e32 v74, 0
	v_mov_b32_e32 v75, 0
	v_mov_b32_e32 v76, 0
	v_mov_b32_e32 v77, 0
	v_mov_b32_e32 v78, 0
	v_mov_b32_e32 v79, 0
	v_mov_b32_e32 v80, 0
	v_mov_b32_e32 v81, 0
	v_mov_b32_e32 v82, 0
	v_mov_b32_e32 v83, 0
	v_mov_b32_e32 v84, 0
	v_mov_b32_e32 v85, 0
	v_mov_b32_e32 v86, 0
	v_mov_b32_e32 v87, 0
	v_mov_b32_e32 v88, 0
	v_mov_b32_e32 v89, 0
	v_mov_b32_e32 v90, 0
	v_mov_b32_e32 v91, 0
	v_mov_b32_e32 v92, 0
	v_mov_b32_e32 v93, 0
	v_mov_b32_e32 v94, 0
	v_mov_b32_e32 v95, 0
	v_mov_b32_e32 v96, 0
	v_mov_b32_e32 v97, 0
	v_mov_b32_e32 v98, 0
	v_mov_b32_e32 v99, 0
	v_mov_b32_e32 v100, 0
	v_mov_b32_e32 v101, 0
	v_mov_b32_e32 v102, 0
	v_mov_b32_e32 v103, 0
	v_mov_b32_e32 v104, 0
	v_mov_b32_e32 v105, 0
	v_mov_b32_e32 v106, 0
	v_mov_b32_e32 v107, 0
	v_mov_b32_e32 v108, 0
	v_mov_b32_e32 v109, 0
	v_mov_b32_e32 v110, 0
	v_mov_b32_e32 v111, 0
	v_mov_b32_e32 v116, 0
	v_mov_b32_e32 v117, 0
	v_mov_b32_e32 v118, 0
	v_mov_b32_e32 v119, 0
	v_mov_b32_e32 v120, 0
	v_mov_b32_e32 v121, 0
	v_mov_b32_e32 v122, 0
	v_mov_b32_e32 v123, 0
	v_mov_b32_e32 v128, 0
	v_mov_b32_e32 v129, 0
	v_mov_b32_e32 v130, 0
	v_mov_b32_e32 v131, 0
	v_mov_b32_e32 v132, 0
	v_mov_b32_e32 v133, 0
	v_mov_b32_e32 v134, 0
	v_mov_b32_e32 v135, 0
.Lzacc7a:
	s_waitcnt vmcnt(8)
	s_waitcnt lgkmcnt(0)
	s_barrier
	s_setprio 1
	s_waitcnt lgkmcnt(0)
	v_mfma_f32_16x16x32_bf16 v[132:135], v[112:115], v[160:163], v[132:135]
	v_mfma_f32_16x16x32_bf16 v[128:131], v[136:139], v[160:163], v[128:131]
	v_mfma_f32_16x16x32_bf16 v[108:111], v[112:115], v[168:171], v[108:111]
	v_mfma_f32_16x16x32_bf16 v[104:107], v[136:139], v[168:171], v[104:107]
	v_mfma_f32_16x16x32_bf16 v[92:95], v[112:115], v[176:179], v[92:95]
	v_mfma_f32_16x16x32_bf16 v[88:91], v[136:139], v[176:179], v[88:91]
	v_mfma_f32_16x16x32_bf16 v[76:79], v[112:115], v[200:203], v[76:79]
	v_mfma_f32_16x16x32_bf16 v[72:75], v[136:139], v[200:203], v[72:75]
	v_mfma_f32_16x16x32_bf16 v[132:135], v[124:127], v[164:167], v[132:135]
	v_mfma_f32_16x16x32_bf16 v[128:131], v[140:143], v[164:167], v[128:131]
	v_mfma_f32_16x16x32_bf16 v[108:111], v[124:127], v[172:175], v[108:111]
	v_mfma_f32_16x16x32_bf16 v[104:107], v[140:143], v[172:175], v[104:107]
	v_mfma_f32_16x16x32_bf16 v[92:95], v[124:127], v[180:183], v[92:95]
	v_mfma_f32_16x16x32_bf16 v[88:91], v[140:143], v[180:183], v[88:91]
	v_mfma_f32_16x16x32_bf16 v[76:79], v[124:127], v[204:207], v[76:79]
	v_mfma_f32_16x16x32_bf16 v[72:75], v[140:143], v[204:207], v[72:75]
	s_setprio 0
	s_setprio 1
	v_mfma_f32_16x16x32_bf16 v[120:123], v[144:147], v[160:163], v[120:123]
	v_mfma_f32_16x16x32_bf16 v[116:119], v[152:155], v[160:163], v[116:119]
	v_mfma_f32_16x16x32_bf16 v[100:103], v[144:147], v[168:171], v[100:103]
	v_mfma_f32_16x16x32_bf16 v[96:99], v[152:155], v[168:171], v[96:99]
	v_mfma_f32_16x16x32_bf16 v[84:87], v[144:147], v[176:179], v[84:87]
	v_mfma_f32_16x16x32_bf16 v[80:83], v[152:155], v[176:179], v[80:83]
	v_mfma_f32_16x16x32_bf16 v[68:71], v[144:147], v[200:203], v[68:71]
	v_mfma_f32_16x16x32_bf16 v[64:67], v[152:155], v[200:203], v[64:67]
	v_mfma_f32_16x16x32_bf16 v[120:123], v[148:151], v[164:167], v[120:123]
	v_mfma_f32_16x16x32_bf16 v[116:119], v[156:159], v[164:167], v[116:119]
	v_mfma_f32_16x16x32_bf16 v[100:103], v[148:151], v[172:175], v[100:103]
	v_mfma_f32_16x16x32_bf16 v[96:99], v[156:159], v[172:175], v[96:99]
	v_mfma_f32_16x16x32_bf16 v[84:87], v[148:151], v[180:183], v[84:87]
	v_mfma_f32_16x16x32_bf16 v[80:83], v[156:159], v[180:183], v[80:83]
	v_mfma_f32_16x16x32_bf16 v[68:71], v[148:151], v[204:207], v[68:71]
	v_mfma_f32_16x16x32_bf16 v[64:67], v[156:159], v[204:207], v[64:67]
	s_setprio 0
	s_barrier
	s_add_i32 s36, s63, s54
	v_lshl_add_u64 v[208:209], s[46:47], 0, v[186:187]
	s_mov_b32 m0, s36
	ds_read_b128 v[160:163], v225 offset:16384
	ds_read_b128 v[164:167], v225 offset:17408
	ds_read_b128 v[168:171], v225 offset:18432
	ds_read_b128 v[172:175], v225 offset:19456
	ds_read_b128 v[176:179], v225 offset:20480
	ds_read_b128 v[180:183], v225 offset:21504
	ds_read_b128 v[200:203], v225 offset:22528
	ds_read_b128 v[204:207], v225 offset:23552
	global_load_lds_dwordx4 v[208:209], off
	s_add_i32 m0, s36, 0x2000
	s_add_u32 s36, s46, 0xb0000
	v_lshl_add_u64 v[210:211], s[46:47], 0, v[190:191]
	s_addc_u32 s37, s47, 0
	s_add_i32 s72, s64, s54
	global_load_lds_dwordx4 v[210:211], off
	v_lshl_add_u64 v[212:213], s[36:37], 0, v[186:187]
	s_mov_b32 m0, s72
	v_lshl_add_u64 v[214:215], s[48:49], 0, v[188:189]
	global_load_lds_dwordx4 v[212:213], off
	v_lshl_add_u64 v[212:213], s[36:37], 0, v[190:191]
	s_add_i32 m0, s72, 0x2000
	s_nop 0
	global_load_lds_dwordx4 v[212:213], off
	v_lshl_add_u64 v[212:213], s[48:49], 0, v[184:185]
	s_mov_b32 m0, s55
	s_nop 0
	global_load_lds_dwordx4 v[212:213], off
	s_mov_b32 m0, s56
	s_nop 0
	global_load_lds_dwordx4 v[214:215], off
	s_cmp_lg_u32 s71, -2
	s_cbranch_scc1 .Lzacc7b
	v_mov_b32_e32 v0, 0
	v_mov_b32_e32 v1, 0
	v_mov_b32_e32 v2, 0
	v_mov_b32_e32 v3, 0
	v_mov_b32_e32 v4, 0
	v_mov_b32_e32 v5, 0
	v_mov_b32_e32 v6, 0
	v_mov_b32_e32 v7, 0
	v_mov_b32_e32 v8, 0
	v_mov_b32_e32 v9, 0
	v_mov_b32_e32 v10, 0
	v_mov_b32_e32 v11, 0
	v_mov_b32_e32 v12, 0
	v_mov_b32_e32 v13, 0
	v_mov_b32_e32 v14, 0
	v_mov_b32_e32 v15, 0
	v_mov_b32_e32 v16, 0
	v_mov_b32_e32 v17, 0
	v_mov_b32_e32 v18, 0
	v_mov_b32_e32 v19, 0
	v_mov_b32_e32 v20, 0
	v_mov_b32_e32 v21, 0
	v_mov_b32_e32 v22, 0
	v_mov_b32_e32 v23, 0
	v_mov_b32_e32 v24, 0
	v_mov_b32_e32 v25, 0
	v_mov_b32_e32 v26, 0
	v_mov_b32_e32 v27, 0
	v_mov_b32_e32 v28, 0
	v_mov_b32_e32 v29, 0
	v_mov_b32_e32 v30, 0
	v_mov_b32_e32 v31, 0
	v_mov_b32_e32 v32, 0
	v_mov_b32_e32 v33, 0
	v_mov_b32_e32 v34, 0
	v_mov_b32_e32 v35, 0
	v_mov_b32_e32 v36, 0
	v_mov_b32_e32 v37, 0
	v_mov_b32_e32 v38, 0
	v_mov_b32_e32 v39, 0
	v_mov_b32_e32 v40, 0
	v_mov_b32_e32 v41, 0
	v_mov_b32_e32 v42, 0
	v_mov_b32_e32 v43, 0
	v_mov_b32_e32 v44, 0
	v_mov_b32_e32 v45, 0
	v_mov_b32_e32 v46, 0
	v_mov_b32_e32 v47, 0
	v_mov_b32_e32 v48, 0
	v_mov_b32_e32 v49, 0
	v_mov_b32_e32 v50, 0
	v_mov_b32_e32 v51, 0
	v_mov_b32_e32 v52, 0
	v_mov_b32_e32 v53, 0
	v_mov_b32_e32 v54, 0
	v_mov_b32_e32 v55, 0
	v_mov_b32_e32 v56, 0
	v_mov_b32_e32 v57, 0
	v_mov_b32_e32 v58, 0
	v_mov_b32_e32 v59, 0
	v_mov_b32_e32 v60, 0
	v_mov_b32_e32 v61, 0
	v_mov_b32_e32 v62, 0
	v_mov_b32_e32 v63, 0
.Lzacc7b:
	s_waitcnt vmcnt(8)
	s_waitcnt lgkmcnt(0)
	s_barrier
	s_setprio 1
	s_waitcnt lgkmcnt(0)
	v_mfma_f32_16x16x32_bf16 v[60:63], v[112:115], v[160:163], v[60:63]
	v_mfma_f32_16x16x32_bf16 v[56:59], v[136:139], v[160:163], v[56:59]
	v_mfma_f32_16x16x32_bf16 v[44:47], v[112:115], v[168:171], v[44:47]
	v_mfma_f32_16x16x32_bf16 v[40:43], v[136:139], v[168:171], v[40:43]
	v_mfma_f32_16x16x32_bf16 v[28:31], v[112:115], v[176:179], v[28:31]
	v_mfma_f32_16x16x32_bf16 v[24:27], v[136:139], v[176:179], v[24:27]
	v_mfma_f32_16x16x32_bf16 v[12:15], v[112:115], v[200:203], v[12:15]
	v_mfma_f32_16x16x32_bf16 v[8:11], v[136:139], v[200:203], v[8:11]
	v_mfma_f32_16x16x32_bf16 v[60:63], v[124:127], v[164:167], v[60:63]
	v_mfma_f32_16x16x32_bf16 v[56:59], v[140:143], v[164:167], v[56:59]
	v_mfma_f32_16x16x32_bf16 v[44:47], v[124:127], v[172:175], v[44:47]
	v_mfma_f32_16x16x32_bf16 v[40:43], v[140:143], v[172:175], v[40:43]
	v_mfma_f32_16x16x32_bf16 v[28:31], v[124:127], v[180:183], v[28:31]
	v_mfma_f32_16x16x32_bf16 v[24:27], v[140:143], v[180:183], v[24:27]
	v_mfma_f32_16x16x32_bf16 v[12:15], v[124:127], v[204:207], v[12:15]
	v_mfma_f32_16x16x32_bf16 v[8:11], v[140:143], v[204:207], v[8:11]
	s_setprio 0
	s_setprio 1
	v_mfma_f32_16x16x32_bf16 v[52:55], v[144:147], v[160:163], v[52:55]
	v_mfma_f32_16x16x32_bf16 v[48:51], v[152:155], v[160:163], v[48:51]
	v_mfma_f32_16x16x32_bf16 v[36:39], v[144:147], v[168:171], v[36:39]
	v_mfma_f32_16x16x32_bf16 v[32:35], v[152:155], v[168:171], v[32:35]
	v_mfma_f32_16x16x32_bf16 v[20:23], v[144:147], v[176:179], v[20:23]
	v_mfma_f32_16x16x32_bf16 v[16:19], v[152:155], v[176:179], v[16:19]
	v_mfma_f32_16x16x32_bf16 v[4:7], v[144:147], v[200:203], v[4:7]
	v_mfma_f32_16x16x32_bf16 v[0:3], v[152:155], v[200:203], v[0:3]
	v_mfma_f32_16x16x32_bf16 v[52:55], v[148:151], v[164:167], v[52:55]
	v_mfma_f32_16x16x32_bf16 v[48:51], v[156:159], v[164:167], v[48:51]
	v_mfma_f32_16x16x32_bf16 v[36:39], v[148:151], v[172:175], v[36:39]
	v_mfma_f32_16x16x32_bf16 v[32:35], v[156:159], v[172:175], v[32:35]
	v_mfma_f32_16x16x32_bf16 v[20:23], v[148:151], v[180:183], v[20:23]
	v_mfma_f32_16x16x32_bf16 v[16:19], v[156:159], v[180:183], v[16:19]
	v_mfma_f32_16x16x32_bf16 v[4:7], v[148:151], v[204:207], v[4:7]
	v_mfma_f32_16x16x32_bf16 v[0:3], v[156:159], v[204:207], v[0:3]
	s_setprio 0
	s_barrier
	s_add_i32 s72, 0, 0x18000
	s_add_i32 s73, 0, 0x1c000
	v_add_u32_e32 v140, s72, v220
	v_add_u32_e32 v156, s73, v220
	ds_read_b128 v[112:115], v140
	ds_read_b128 v[124:127], v140 offset:1024
	ds_read_b128 v[136:139], v140 offset:2048
	ds_read_b128 v[140:143], v140 offset:3072
	ds_read_b128 v[144:147], v156
	ds_read_b128 v[148:151], v156 offset:1024
	ds_read_b128 v[152:155], v156 offset:2048
	ds_read_b128 v[156:159], v156 offset:3072
	s_add_u32 s36, s48, 0xb0000
	s_addc_u32 s37, s49, 0
	s_mov_b32 m0, s57
	v_lshl_add_u64 v[226:227], s[36:37], 0, v[184:185]
	ds_read_b128 v[160:163], v225 offset:32768
	ds_read_b128 v[164:167], v225 offset:33792
	ds_read_b128 v[168:171], v225 offset:34816
	ds_read_b128 v[172:175], v225 offset:35840
	ds_read_b128 v[176:179], v225 offset:36864
	ds_read_b128 v[180:183], v225 offset:37888
	ds_read_b128 v[200:203], v225 offset:38912
	ds_read_b128 v[204:207], v225 offset:39936
	global_load_lds_dwordx4 v[226:227], off
	v_lshl_add_u64 v[226:227], s[36:37], 0, v[188:189]
	s_mov_b32 m0, s58
	s_nop 0
	global_load_lds_dwordx4 v[226:227], off
	s_waitcnt vmcnt(8)
	s_waitcnt lgkmcnt(0)
	s_barrier
	s_setprio 1
	s_waitcnt lgkmcnt(0)
	v_mfma_f32_16x16x32_bf16 v[132:135], v[112:115], v[160:163], v[132:135]
	v_mfma_f32_16x16x32_bf16 v[128:131], v[136:139], v[160:163], v[128:131]
	v_mfma_f32_16x16x32_bf16 v[108:111], v[112:115], v[168:171], v[108:111]
	v_mfma_f32_16x16x32_bf16 v[104:107], v[136:139], v[168:171], v[104:107]
	v_mfma_f32_16x16x32_bf16 v[92:95], v[112:115], v[176:179], v[92:95]
	v_mfma_f32_16x16x32_bf16 v[88:91], v[136:139], v[176:179], v[88:91]
	v_mfma_f32_16x16x32_bf16 v[76:79], v[112:115], v[200:203], v[76:79]
	v_mfma_f32_16x16x32_bf16 v[72:75], v[136:139], v[200:203], v[72:75]
	v_mfma_f32_16x16x32_bf16 v[132:135], v[124:127], v[164:167], v[132:135]
	v_mfma_f32_16x16x32_bf16 v[128:131], v[140:143], v[164:167], v[128:131]
	v_mfma_f32_16x16x32_bf16 v[108:111], v[124:127], v[172:175], v[108:111]
	v_mfma_f32_16x16x32_bf16 v[104:107], v[140:143], v[172:175], v[104:107]
	v_mfma_f32_16x16x32_bf16 v[92:95], v[124:127], v[180:183], v[92:95]
	v_mfma_f32_16x16x32_bf16 v[88:91], v[140:143], v[180:183], v[88:91]
	v_mfma_f32_16x16x32_bf16 v[76:79], v[124:127], v[204:207], v[76:79]
	v_mfma_f32_16x16x32_bf16 v[72:75], v[140:143], v[204:207], v[72:75]
	s_setprio 0
	s_setprio 1
	v_mfma_f32_16x16x32_bf16 v[120:123], v[144:147], v[160:163], v[120:123]
	v_mfma_f32_16x16x32_bf16 v[116:119], v[152:155], v[160:163], v[116:119]
	v_mfma_f32_16x16x32_bf16 v[100:103], v[144:147], v[168:171], v[100:103]
	v_mfma_f32_16x16x32_bf16 v[96:99], v[152:155], v[168:171], v[96:99]
	v_mfma_f32_16x16x32_bf16 v[84:87], v[144:147], v[176:179], v[84:87]
	v_mfma_f32_16x16x32_bf16 v[80:83], v[152:155], v[176:179], v[80:83]
	v_mfma_f32_16x16x32_bf16 v[68:71], v[144:147], v[200:203], v[68:71]
	v_mfma_f32_16x16x32_bf16 v[64:67], v[152:155], v[200:203], v[64:67]
	v_mfma_f32_16x16x32_bf16 v[120:123], v[148:151], v[164:167], v[120:123]
	v_mfma_f32_16x16x32_bf16 v[116:119], v[156:159], v[164:167], v[116:119]
	v_mfma_f32_16x16x32_bf16 v[100:103], v[148:151], v[172:175], v[100:103]
	v_mfma_f32_16x16x32_bf16 v[96:99], v[156:159], v[172:175], v[96:99]
	v_mfma_f32_16x16x32_bf16 v[84:87], v[148:151], v[180:183], v[84:87]
	v_mfma_f32_16x16x32_bf16 v[80:83], v[156:159], v[180:183], v[80:83]
	v_mfma_f32_16x16x32_bf16 v[68:71], v[148:151], v[204:207], v[68:71]
	v_mfma_f32_16x16x32_bf16 v[64:67], v[156:159], v[204:207], v[64:67]
	s_setprio 0
	s_barrier
	s_add_i32 s36, s72, s54
	v_lshl_add_u64 v[208:209], v[208:209], 0, s[20:21]
	s_mov_b32 m0, s36
	ds_read_b128 v[160:163], v225 offset:49152
	ds_read_b128 v[164:167], v225 offset:50176
	ds_read_b128 v[168:171], v225 offset:51200
	ds_read_b128 v[172:175], v225 offset:52224
	ds_read_b128 v[176:179], v225 offset:53248
	ds_read_b128 v[180:183], v225 offset:54272
	ds_read_b128 v[200:203], v225 offset:55296
	ds_read_b128 v[204:207], v225 offset:56320
	global_load_lds_dwordx4 v[208:209], off
	s_add_i32 m0, s36, 0x2000
	s_add_u32 s36, s46, 0xb0080
	v_lshl_add_u64 v[208:209], v[210:211], 0, s[20:21]
	s_addc_u32 s37, s47, 0
	s_add_i32 s46, s73, s54
	global_load_lds_dwordx4 v[208:209], off
	v_lshl_add_u64 v[208:209], s[36:37], 0, v[186:187]
	s_mov_b32 m0, s46
	s_nop 0
	global_load_lds_dwordx4 v[208:209], off
	v_lshl_add_u64 v[208:209], s[36:37], 0, v[190:191]
	s_add_i32 m0, s46, 0x2000
	s_nop 0
	global_load_lds_dwordx4 v[208:209], off
	v_lshl_add_u64 v[208:209], v[212:213], 0, s[20:21]
	s_mov_b32 m0, s60
	s_nop 0
	global_load_lds_dwordx4 v[208:209], off
	v_lshl_add_u64 v[208:209], v[214:215], 0, s[20:21]
	s_mov_b32 m0, s61
	s_nop 0
	global_load_lds_dwordx4 v[208:209], off
	s_waitcnt vmcnt(8)
	s_waitcnt lgkmcnt(0)
	s_barrier
	s_setprio 1
	s_waitcnt lgkmcnt(0)
	v_mfma_f32_16x16x32_bf16 v[60:63], v[112:115], v[160:163], v[60:63]
	v_mfma_f32_16x16x32_bf16 v[56:59], v[136:139], v[160:163], v[56:59]
	v_mfma_f32_16x16x32_bf16 v[44:47], v[112:115], v[168:171], v[44:47]
	v_mfma_f32_16x16x32_bf16 v[40:43], v[136:139], v[168:171], v[40:43]
	v_mfma_f32_16x16x32_bf16 v[28:31], v[112:115], v[176:179], v[28:31]
	v_mfma_f32_16x16x32_bf16 v[24:27], v[136:139], v[176:179], v[24:27]
	v_mfma_f32_16x16x32_bf16 v[12:15], v[112:115], v[200:203], v[12:15]
	v_mfma_f32_16x16x32_bf16 v[8:11], v[136:139], v[200:203], v[8:11]
	v_mfma_f32_16x16x32_bf16 v[60:63], v[124:127], v[164:167], v[60:63]
	v_mfma_f32_16x16x32_bf16 v[56:59], v[140:143], v[164:167], v[56:59]
	v_mfma_f32_16x16x32_bf16 v[44:47], v[124:127], v[172:175], v[44:47]
	v_mfma_f32_16x16x32_bf16 v[40:43], v[140:143], v[172:175], v[40:43]
	v_mfma_f32_16x16x32_bf16 v[28:31], v[124:127], v[180:183], v[28:31]
	v_mfma_f32_16x16x32_bf16 v[24:27], v[140:143], v[180:183], v[24:27]
	v_mfma_f32_16x16x32_bf16 v[12:15], v[124:127], v[204:207], v[12:15]
	v_mfma_f32_16x16x32_bf16 v[8:11], v[140:143], v[204:207], v[8:11]
	s_setprio 0
	s_setprio 1
	v_mfma_f32_16x16x32_bf16 v[52:55], v[144:147], v[160:163], v[52:55]
	v_mfma_f32_16x16x32_bf16 v[48:51], v[152:155], v[160:163], v[48:51]
	v_mfma_f32_16x16x32_bf16 v[36:39], v[144:147], v[168:171], v[36:39]
	v_mfma_f32_16x16x32_bf16 v[32:35], v[152:155], v[168:171], v[32:35]
	v_mfma_f32_16x16x32_bf16 v[20:23], v[144:147], v[176:179], v[20:23]
	v_mfma_f32_16x16x32_bf16 v[16:19], v[152:155], v[176:179], v[16:19]
	v_mfma_f32_16x16x32_bf16 v[4:7], v[144:147], v[200:203], v[4:7]
	v_mfma_f32_16x16x32_bf16 v[0:3], v[152:155], v[200:203], v[0:3]
	v_mfma_f32_16x16x32_bf16 v[52:55], v[148:151], v[164:167], v[52:55]
	v_mfma_f32_16x16x32_bf16 v[48:51], v[156:159], v[164:167], v[48:51]
	v_mfma_f32_16x16x32_bf16 v[36:39], v[148:151], v[172:175], v[36:39]
	v_mfma_f32_16x16x32_bf16 v[32:35], v[156:159], v[172:175], v[32:35]
	v_mfma_f32_16x16x32_bf16 v[20:23], v[148:151], v[180:183], v[20:23]
	v_mfma_f32_16x16x32_bf16 v[16:19], v[156:159], v[180:183], v[16:19]
	v_mfma_f32_16x16x32_bf16 v[4:7], v[148:151], v[204:207], v[4:7]
	v_mfma_f32_16x16x32_bf16 v[0:3], v[156:159], v[204:207], v[0:3]
	s_setprio 0
	s_barrier
	s_add_i32 s71, s71, 2
	s_add_u32 s69, s69, 0x100
	s_addc_u32 s70, s70, 0
	s_cmp_gt_u32 s71, 41
	s_mov_b64 s[36:37], s[38:39]
	s_cbranch_scc0 .LBB0_1151
	s_and_b64 vcc, exec, s[22:23]
	s_cbranch_vccz .LBB0_1154
	s_barrier
